# 4-phase GEMM loops, ph1 and ph5 stagings moved inside MFMA segments (after M1, M5) with fresh temps and literal LDS bases; phases 2,4 have no pre-barrier lgkmcnt wait
# baseline (speedup 1.0000x reference)
; #define PG8_STAGE(bufoff, gbase, voff) do { _Pragma("unroll") for (int _i = 0; _i < 2; ++_i) \
;         __builtin_amdgcn_global_load_lds((const unsigned*)((const char*)(gbase) + (voff)[_i]), (LAS unsigned*)(lds + (bufoff) + ldsw + _i * 8192), 16, 0, 0); } while (0)
; #define PG8_LDA(dst, b, h) do { _Pragma("unroll") for (int m = 0; m < 4; ++m) _Pragma("unroll") for (int k = 0; k < 2; ++k) dst[m][k] = *(const LAS bf16x8*)(lds + PG8_SA(b, h) + aoff + m * 2048 + k * 1024); } while (0)
; #define PG8_LDB(dst, b, h) do { _Pragma("unroll") for (int n = 0; n < 2; ++n) _Pragma("unroll") for (int k = 0; k < 2; ++k) dst[n][k] = *(const LAS bf16x8*)(lds + PG8_SB(b, h) + boff + n * 2048 + k * 1024); } while (0)
; #define PG8_MMA(ai, bj, At, Bt) do { __builtin_amdgcn_s_setprio(1); _Pragma("unroll") for (int m = 0; m < 4; ++m) _Pragma("unroll") for (int n = 0; n < 2; ++n) _Pragma("unroll") for (int k = 0; k < 2; ++k) \
;         acc[ai][bj][m][n] = __builtin_amdgcn_mfma_f32_16x16x32_bf16(Bt[n][k], At[m][k], acc[ai][bj][m][n], 0, 0, 0); __builtin_amdgcn_s_setprio(0); } while (0)
; #define PG8_WAIT_L(n) asm volatile("s_waitcnt lgkmcnt(" #n ")" ::: "memory")
; #define PG8_BAR __builtin_amdgcn_s_barrier()
; #define PG8_SCHED __builtin_amdgcn_sched_barrier(0)
; template <class Epi, class Sched>
; __device__ __forceinline__ void gemm_phase(LAS unsigned char* lds, const Gemm g, const Sched& S, const Epi& E) {
;     ...
;         for (int t = 0; t < nt; t += 2) {
;             const bool last = (t == nt - 2);
;             const char* a1 = cA + (size_t)(t + 1) * kstep;
;             const char* a2 = last ? nA : cA + (size_t)(t + 2) * kstep; const char* b2 = last ? nB : cB + (size_t)(t + 2) * kstep;
;             const char* a3 = a2 + kstep; const char* b3 = b2 + kstep;
;             PG8_LDB(B0, 0, 0); PG8_SCHED; PG8_LDA(At, 0, 0); PG8_STAGE(PG8_SA(1, 1), a1 + hstep, voffA);
;             PG8_WAIT_L(8); PG8_BAR; PG8_WAIT_L(0); PG8_MMA(0, 0, At, B0); PG8_BAR; PG8_SCHED;
;             PG8_LDB(B1, 0, 1); PG8_STAGE(PG8_SB(0, 0), b2, voffB);
;             PG8_BAR; PG8_WAIT_L(0); PG8_MMA(0, 1, At, B1); PG8_BAR;
;             PG8_LDA(At, 0, 1); PG8_STAGE(PG8_SA(0, 0), a2, voffA);
;             PG8_BAR; PG8_WAIT_L(0); PG8_MMA(1, 0, At, B0); PG8_BAR; PG8_SCHED;
.LBB0_44:
	v_add_u32_e32 v78, 0x10000, v163
	ds_read_b128 v[66:69], v78
	ds_read_b128 v[70:73], v78 offset:1024
	ds_read_b128 v[74:77], v78 offset:2048
	ds_read_b128 v[78:81], v78 offset:3072
	ds_read_b128 v[152:155], v165
	ds_read_b128 v[166:169], v165 offset:1024
	ds_read_b128 v[170:173], v165 offset:2048
	ds_read_b128 v[174:177], v165 offset:3072
	ds_read_b128 v[178:181], v165 offset:4096
	ds_read_b128 v[182:185], v165 offset:5120
	ds_read_b128 v[186:189], v165 offset:6144
	ds_read_b128 v[190:193], v165 offset:7168
	v_add_u32_e32 v156, 0x14000, v163
	ds_read_b128 v[194:197], v156
	ds_read_b128 v[198:201], v156 offset:1024
	ds_read_b128 v[202:205], v156 offset:2048
	ds_read_b128 v[210:213], v156 offset:3072
	s_waitcnt lgkmcnt(4)
	s_barrier
	s_waitcnt lgkmcnt(0)
	s_setprio 1
	v_mfma_f32_16x16x32_bf16 v[142:145], v[66:69], v[152:155], v[142:145]
	v_mfma_f32_16x16x32_bf16 v[138:141], v[74:77], v[152:155], v[138:141]
	v_mfma_f32_16x16x32_bf16 v[126:129], v[66:69], v[170:173], v[126:129]
	v_mfma_f32_16x16x32_bf16 v[122:125], v[74:77], v[170:173], v[122:125]
	v_mfma_f32_16x16x32_bf16 v[110:113], v[66:69], v[178:181], v[110:113]
	v_mfma_f32_16x16x32_bf16 v[106:109], v[74:77], v[178:181], v[106:109]
	v_mfma_f32_16x16x32_bf16 v[102:105], v[66:69], v[186:189], v[102:105]
	v_mfma_f32_16x16x32_bf16 v[98:101], v[74:77], v[186:189], v[98:101]
	v_mfma_f32_16x16x32_bf16 v[142:145], v[70:73], v[166:169], v[142:145]
	v_mfma_f32_16x16x32_bf16 v[138:141], v[78:81], v[166:169], v[138:141]
	v_mfma_f32_16x16x32_bf16 v[126:129], v[70:73], v[174:177], v[126:129]
	v_mfma_f32_16x16x32_bf16 v[122:125], v[78:81], v[174:177], v[122:125]
	v_mfma_f32_16x16x32_bf16 v[110:113], v[70:73], v[182:185], v[110:113]
	v_mfma_f32_16x16x32_bf16 v[106:109], v[78:81], v[182:185], v[106:109]
	v_mfma_f32_16x16x32_bf16 v[102:105], v[70:73], v[190:193], v[102:105]
	v_mfma_f32_16x16x32_bf16 v[98:101], v[78:81], v[190:193], v[98:101]
	s_add_u32 s50, s28, 0x100
	s_addc_u32 s51, s29, 0
	s_cmpk_eq_i32 s75, 0x7c
	s_cselect_b32 s55, s27, s51
	s_cselect_b32 s54, s71, s50
	s_cselect_b32 s53, s25, s74
	s_cselect_b32 s52, s72, s73
	v_lshl_add_u64 v[228:229], s[28:29], 0, v[150:151]
	s_add_i32 m0, s9, 0xc000
	s_nop 0
	global_load_lds_dwordx4 v[228:229], off
	v_lshl_add_u64 v[228:229], s[28:29], 0, v[148:149]
	s_add_i32 m0, s9, 0xe000
	s_nop 0
	global_load_lds_dwordx4 v[228:229], off
	v_mfma_f32_16x16x32_bf16 v[134:137], v[194:197], v[152:155], v[134:137]
	v_mfma_f32_16x16x32_bf16 v[130:133], v[202:205], v[152:155], v[130:133]
	v_mfma_f32_16x16x32_bf16 v[118:121], v[194:197], v[170:173], v[118:121]
	v_mfma_f32_16x16x32_bf16 v[114:117], v[202:205], v[170:173], v[114:117]
	v_mfma_f32_16x16x32_bf16 v[94:97], v[194:197], v[178:181], v[94:97]
	v_mfma_f32_16x16x32_bf16 v[90:93], v[202:205], v[178:181], v[90:93]
	v_mfma_f32_16x16x32_bf16 v[86:89], v[194:197], v[186:189], v[86:89]
	v_mfma_f32_16x16x32_bf16 v[82:85], v[202:205], v[186:189], v[82:85]
	v_mfma_f32_16x16x32_bf16 v[134:137], v[198:201], v[166:169], v[134:137]
	v_mfma_f32_16x16x32_bf16 v[130:133], v[210:213], v[166:169], v[130:133]
	v_mfma_f32_16x16x32_bf16 v[118:121], v[198:201], v[174:177], v[118:121]
	v_mfma_f32_16x16x32_bf16 v[114:117], v[210:213], v[174:177], v[114:117]
	v_mfma_f32_16x16x32_bf16 v[94:97], v[198:201], v[182:185], v[94:97]
	v_mfma_f32_16x16x32_bf16 v[90:93], v[210:213], v[182:185], v[90:93]
	v_mfma_f32_16x16x32_bf16 v[86:89], v[198:201], v[190:193], v[86:89]
	v_mfma_f32_16x16x32_bf16 v[82:85], v[210:213], v[190:193], v[82:85]
	s_setprio 0
	s_barrier
	s_add_i32 s28, s60, 0x10000
	v_lshl_add_u64 v[156:157], s[52:53], 0, v[0:1]
	s_mov_b32 m0, s28
	v_lshl_add_u64 v[160:161], s[52:53], 0, v[146:147]
	global_load_lds_dwordx4 v[156:157], off
	s_add_i32 m0, s28, 0x2000
	s_nop 0
	global_load_lds_dwordx4 v[160:161], off
	s_mov_b32 m0, s9
	v_lshl_add_u64 v[206:207], s[54:55], 0, v[0:1]
	global_load_lds_dwordx4 v[206:207], off
	v_lshl_add_u64 v[214:215], s[54:55], 0, v[146:147]
	s_mov_b32 m0, s61
	s_nop 0
	global_load_lds_dwordx4 v[214:215], off
	ds_read_b128 v[152:155], v165 offset:16384
	ds_read_b128 v[166:169], v165 offset:17408
	ds_read_b128 v[170:173], v165 offset:18432
	ds_read_b128 v[174:177], v165 offset:19456
	ds_read_b128 v[178:181], v165 offset:20480
	ds_read_b128 v[182:185], v165 offset:21504
	ds_read_b128 v[186:189], v165 offset:22528
	ds_read_b128 v[190:193], v165 offset:23552
	s_waitcnt vmcnt(4)
	s_barrier
	s_waitcnt lgkmcnt(0)
	s_setprio 1
	v_mfma_f32_16x16x32_bf16 v[62:65], v[66:69], v[152:155], v[62:65]
	v_mfma_f32_16x16x32_bf16 v[58:61], v[74:77], v[152:155], v[58:61]
	v_mfma_f32_16x16x32_bf16 v[46:49], v[66:69], v[170:173], v[46:49]
	v_mfma_f32_16x16x32_bf16 v[42:45], v[74:77], v[170:173], v[42:45]
	v_mfma_f32_16x16x32_bf16 v[30:33], v[66:69], v[178:181], v[30:33]
	v_mfma_f32_16x16x32_bf16 v[26:29], v[74:77], v[178:181], v[26:29]
	v_mfma_f32_16x16x32_bf16 v[22:25], v[66:69], v[186:189], v[22:25]
	v_mfma_f32_16x16x32_bf16 v[14:17], v[74:77], v[186:189], v[14:17]
	v_mfma_f32_16x16x32_bf16 v[62:65], v[70:73], v[166:169], v[62:65]
	v_mfma_f32_16x16x32_bf16 v[58:61], v[78:81], v[166:169], v[58:61]
	v_mfma_f32_16x16x32_bf16 v[46:49], v[70:73], v[174:177], v[46:49]
	v_mfma_f32_16x16x32_bf16 v[42:45], v[78:81], v[174:177], v[42:45]
	v_mfma_f32_16x16x32_bf16 v[30:33], v[70:73], v[182:185], v[30:33]
	v_mfma_f32_16x16x32_bf16 v[26:29], v[78:81], v[182:185], v[26:29]
	v_mfma_f32_16x16x32_bf16 v[22:25], v[70:73], v[190:193], v[22:25]
	v_mfma_f32_16x16x32_bf16 v[14:17], v[78:81], v[190:193], v[14:17]
	v_mfma_f32_16x16x32_bf16 v[54:57], v[194:197], v[152:155], v[54:57]
	v_mfma_f32_16x16x32_bf16 v[50:53], v[202:205], v[152:155], v[50:53]
	v_mfma_f32_16x16x32_bf16 v[38:41], v[194:197], v[170:173], v[38:41]
	v_mfma_f32_16x16x32_bf16 v[34:37], v[202:205], v[170:173], v[34:37]
	v_mfma_f32_16x16x32_bf16 v[18:21], v[194:197], v[178:181], v[18:21]
	v_mfma_f32_16x16x32_bf16 v[10:13], v[202:205], v[178:181], v[10:13]
	v_mfma_f32_16x16x32_bf16 v[6:9], v[194:197], v[186:189], v[6:9]
	v_mfma_f32_16x16x32_bf16 v[2:5], v[202:205], v[186:189], v[2:5]
	v_mfma_f32_16x16x32_bf16 v[54:57], v[198:201], v[166:169], v[54:57]
	v_mfma_f32_16x16x32_bf16 v[50:53], v[210:213], v[166:169], v[50:53]
	v_mfma_f32_16x16x32_bf16 v[38:41], v[198:201], v[174:177], v[38:41]
	v_mfma_f32_16x16x32_bf16 v[34:37], v[210:213], v[174:177], v[34:37]
	v_mfma_f32_16x16x32_bf16 v[18:21], v[198:201], v[182:185], v[18:21]
	v_mfma_f32_16x16x32_bf16 v[10:13], v[210:213], v[182:185], v[10:13]
	v_mfma_f32_16x16x32_bf16 v[6:9], v[198:201], v[190:193], v[6:9]
	v_mfma_f32_16x16x32_bf16 v[2:5], v[210:213], v[190:193], v[2:5]
	s_setprio 0
	s_barrier
; #define PG8_STAGE(bufoff, gbase, voff) do { _Pragma("unroll") for (int _i = 0; _i < 2; ++_i) \
;         __builtin_amdgcn_global_load_lds((const unsigned*)((const char*)(gbase) + (voff)[_i]), (LAS unsigned*)(lds + (bufoff) + ldsw + _i * 8192), 16, 0, 0); } while (0)
; #define PG8_MMA(ai, bj, At, Bt) do { __builtin_amdgcn_s_setprio(1); _Pragma("unroll") for (int m = 0; m < 4; ++m) _Pragma("unroll") for (int n = 0; n < 2; ++n) _Pragma("unroll") for (int k = 0; k < 2; ++k) \
;         acc[ai][bj][m][n] = __builtin_amdgcn_mfma_f32_16x16x32_bf16(Bt[n][k], At[m][k], acc[ai][bj][m][n], 0, 0, 0); __builtin_amdgcn_s_setprio(0); } while (0)
; #define PG8_WAIT_V(n) asm volatile("s_waitcnt vmcnt(" #n ")" ::: "memory")
; #define PG8_WAIT_L(n) asm volatile("s_waitcnt lgkmcnt(" #n ")" ::: "memory")
; #define PG8_BAR __builtin_amdgcn_s_barrier()
; #define PG8_SCHED __builtin_amdgcn_sched_barrier(0)
; template <class Epi, class Sched>
; __device__ __forceinline__ void gemm_phase(LAS unsigned char* lds, const Gemm g, const Sched& S, const Epi& E) {
;     ...
;             PG8_BAR; PG8_WAIT_L(0); PG8_MMA(1, 0, At, B0); PG8_BAR; PG8_SCHED;
;             PG8_STAGE(PG8_SB(0, 1), b2 + hstep, voffB);
;             PG8_WAIT_V(6); PG8_BAR; PG8_MMA(1, 1, At, B1); PG8_BAR;
	s_add_u32 s28, s52, 0x200000
	s_addc_u32 s29, s53, 0
	s_add_i32 s38, s60, 0x14000
	v_lshl_add_u64 v[66:67], s[28:29], 0, v[0:1]
	s_mov_b32 m0, s38
	s_nop 0
	global_load_lds_dwordx4 v[66:67], off
	v_lshl_add_u64 v[66:67], s[28:29], 0, v[146:147]
	s_add_i32 m0, s38, 0x2000
	s_nop 0
	global_load_lds_dwordx4 v[66:67], off
	v_add_u32_e32 v78, 0x18000, v163
	ds_read_b128 v[66:69], v78
	ds_read_b128 v[70:73], v78 offset:1024
	ds_read_b128 v[74:77], v78 offset:2048
	ds_read_b128 v[78:81], v78 offset:3072
	ds_read_b128 v[152:155], v165 offset:32768
	ds_read_b128 v[166:169], v165 offset:33792
	ds_read_b128 v[170:173], v165 offset:34816
	ds_read_b128 v[174:177], v165 offset:35840
	ds_read_b128 v[178:181], v165 offset:36864
	ds_read_b128 v[182:185], v165 offset:37888
	ds_read_b128 v[186:189], v165 offset:38912
	ds_read_b128 v[190:193], v165 offset:39936
	v_add_u32_e32 v210, 0x1c000, v163
	ds_read_b128 v[194:197], v210
	ds_read_b128 v[198:201], v210 offset:1024
	ds_read_b128 v[202:205], v210 offset:2048
	ds_read_b128 v[210:213], v210 offset:3072
	s_waitcnt lgkmcnt(4)
	s_barrier
	s_waitcnt lgkmcnt(0)
	s_setprio 1
	v_mfma_f32_16x16x32_bf16 v[142:145], v[66:69], v[152:155], v[142:145]
	v_mfma_f32_16x16x32_bf16 v[138:141], v[74:77], v[152:155], v[138:141]
	v_mfma_f32_16x16x32_bf16 v[126:129], v[66:69], v[170:173], v[126:129]
	v_mfma_f32_16x16x32_bf16 v[122:125], v[74:77], v[170:173], v[122:125]
	v_mfma_f32_16x16x32_bf16 v[110:113], v[66:69], v[178:181], v[110:113]
	v_mfma_f32_16x16x32_bf16 v[106:109], v[74:77], v[178:181], v[106:109]
	v_mfma_f32_16x16x32_bf16 v[102:105], v[66:69], v[186:189], v[102:105]
	v_mfma_f32_16x16x32_bf16 v[98:101], v[74:77], v[186:189], v[98:101]
	v_mfma_f32_16x16x32_bf16 v[142:145], v[70:73], v[166:169], v[142:145]
	v_mfma_f32_16x16x32_bf16 v[138:141], v[78:81], v[166:169], v[138:141]
	v_mfma_f32_16x16x32_bf16 v[126:129], v[70:73], v[174:177], v[126:129]
	v_mfma_f32_16x16x32_bf16 v[122:125], v[78:81], v[174:177], v[122:125]
	v_mfma_f32_16x16x32_bf16 v[110:113], v[70:73], v[182:185], v[110:113]
	v_mfma_f32_16x16x32_bf16 v[106:109], v[78:81], v[182:185], v[106:109]
	v_mfma_f32_16x16x32_bf16 v[102:105], v[70:73], v[190:193], v[102:105]
	v_mfma_f32_16x16x32_bf16 v[98:101], v[78:81], v[190:193], v[98:101]
	s_add_u32 s28, s54, 0x200000
	s_addc_u32 s29, s55, 0
	s_mov_b32 m0, s62
	v_lshl_add_u64 v[226:227], s[28:29], 0, v[0:1]
	global_load_lds_dwordx4 v[226:227], off
	v_lshl_add_u64 v[226:227], s[28:29], 0, v[146:147]
	s_mov_b32 m0, s63
	s_nop 0
	global_load_lds_dwordx4 v[226:227], off
	v_mfma_f32_16x16x32_bf16 v[134:137], v[194:197], v[152:155], v[134:137]
	v_mfma_f32_16x16x32_bf16 v[130:133], v[202:205], v[152:155], v[130:133]
	v_mfma_f32_16x16x32_bf16 v[118:121], v[194:197], v[170:173], v[118:121]
	v_mfma_f32_16x16x32_bf16 v[114:117], v[202:205], v[170:173], v[114:117]
	v_mfma_f32_16x16x32_bf16 v[94:97], v[194:197], v[178:181], v[94:97]
	v_mfma_f32_16x16x32_bf16 v[90:93], v[202:205], v[178:181], v[90:93]
	v_mfma_f32_16x16x32_bf16 v[86:89], v[194:197], v[186:189], v[86:89]
	v_mfma_f32_16x16x32_bf16 v[82:85], v[202:205], v[186:189], v[82:85]
	v_mfma_f32_16x16x32_bf16 v[134:137], v[198:201], v[166:169], v[134:137]
	v_mfma_f32_16x16x32_bf16 v[130:133], v[210:213], v[166:169], v[130:133]
	v_mfma_f32_16x16x32_bf16 v[118:121], v[198:201], v[174:177], v[118:121]
	v_mfma_f32_16x16x32_bf16 v[114:117], v[210:213], v[174:177], v[114:117]
	v_mfma_f32_16x16x32_bf16 v[94:97], v[198:201], v[182:185], v[94:97]
	v_mfma_f32_16x16x32_bf16 v[90:93], v[210:213], v[182:185], v[90:93]
	v_mfma_f32_16x16x32_bf16 v[86:89], v[198:201], v[190:193], v[86:89]
	v_mfma_f32_16x16x32_bf16 v[82:85], v[210:213], v[190:193], v[82:85]
	s_setprio 0
	s_barrier
; #define PG8_STAGE(bufoff, gbase, voff) do { _Pragma("unroll") for (int _i = 0; _i < 2; ++_i) \
;         __builtin_amdgcn_global_load_lds((const unsigned*)((const char*)(gbase) + (voff)[_i]), (LAS unsigned*)(lds + (bufoff) + ldsw + _i * 8192), 16, 0, 0); } while (0)
; #define PG8_LDA(dst, b, h) do { _Pragma("unroll") for (int m = 0; m < 4; ++m) _Pragma("unroll") for (int k = 0; k < 2; ++k) dst[m][k] = *(const LAS bf16x8*)(lds + PG8_SA(b, h) + aoff + m * 2048 + k * 1024); } while (0)
; #define PG8_LDB(dst, b, h) do { _Pragma("unroll") for (int n = 0; n < 2; ++n) _Pragma("unroll") for (int k = 0; k < 2; ++k) dst[n][k] = *(const LAS bf16x8*)(lds + PG8_SB(b, h) + boff + n * 2048 + k * 1024); } while (0)
; #define PG8_MMA(ai, bj, At, Bt) do { __builtin_amdgcn_s_setprio(1); _Pragma("unroll") for (int m = 0; m < 4; ++m) _Pragma("unroll") for (int n = 0; n < 2; ++n) _Pragma("unroll") for (int k = 0; k < 2; ++k) \
;         acc[ai][bj][m][n] = __builtin_amdgcn_mfma_f32_16x16x32_bf16(Bt[n][k], At[m][k], acc[ai][bj][m][n], 0, 0, 0); __builtin_amdgcn_s_setprio(0); } while (0)
; #define PG8_WAIT_V(n) asm volatile("s_waitcnt vmcnt(" #n ")" ::: "memory")
; #define PG8_WAIT_L(n) asm volatile("s_waitcnt lgkmcnt(" #n ")" ::: "memory")
; #define PG8_BAR __builtin_amdgcn_s_barrier()
; #define PG8_SCHED __builtin_amdgcn_sched_barrier(0)
; template <class Epi, class Sched>
; __device__ __forceinline__ void gemm_phase(LAS unsigned char* lds, const Gemm g, const Sched& S, const Epi& E) {
;     ...
;             PG8_WAIT_V(6); PG8_BAR; PG8_MMA(1, 1, At, B1); PG8_BAR;
;             PG8_LDB(B0, 1, 0); PG8_SCHED; PG8_LDA(At, 1, 0); PG8_STAGE(PG8_SA(0, 1), a2 + hstep, voffA);
;             PG8_WAIT_L(8); PG8_BAR; PG8_WAIT_L(0); PG8_MMA(0, 0, At, B0); PG8_BAR; PG8_SCHED;
;             PG8_LDB(B1, 1, 1); PG8_STAGE(PG8_SB(1, 0), b3, voffB);
;             PG8_BAR; PG8_WAIT_L(0); PG8_MMA(0, 1, At, B1); PG8_BAR;
;             PG8_LDA(At, 1, 1); PG8_STAGE(PG8_SA(1, 0), a3, voffA);
;             PG8_BAR; PG8_WAIT_L(0); PG8_MMA(1, 0, At, B0); PG8_BAR; PG8_SCHED;
;             PG8_STAGE(PG8_SB(1, 1), b3 + hstep, voffB);
;             PG8_WAIT_V(6); PG8_BAR; PG8_MMA(1, 1, At, B1); PG8_BAR;
;         }
;         E(acc, cur, wr, wc, fr, fq);
	s_add_i32 s28, s60, 0x18000
	v_lshl_add_u64 v[156:157], v[156:157], 0, s[36:37]
	s_mov_b32 m0, s28
	s_nop 0
	global_load_lds_dwordx4 v[156:157], off
	v_lshl_add_u64 v[156:157], v[160:161], 0, s[36:37]
	s_add_i32 m0, s28, 0x2000
	s_nop 0
	global_load_lds_dwordx4 v[156:157], off
	s_mov_b32 m0, s66
	v_lshl_add_u64 v[156:157], v[206:207], 0, s[36:37]
	global_load_lds_dwordx4 v[156:157], off
	v_lshl_add_u64 v[156:157], v[214:215], 0, s[36:37]
	s_mov_b32 m0, s67
	s_nop 0
	global_load_lds_dwordx4 v[156:157], off
	ds_read_b128 v[152:155], v165 offset:49152
	ds_read_b128 v[166:169], v165 offset:50176
	ds_read_b128 v[170:173], v165 offset:51200
	ds_read_b128 v[174:177], v165 offset:52224
	ds_read_b128 v[178:181], v165 offset:53248
	ds_read_b128 v[182:185], v165 offset:54272
	ds_read_b128 v[186:189], v165 offset:55296
	ds_read_b128 v[190:193], v165 offset:56320
	s_waitcnt vmcnt(4)
	s_barrier
	s_waitcnt lgkmcnt(0)
	s_setprio 1
	v_mfma_f32_16x16x32_bf16 v[62:65], v[66:69], v[152:155], v[62:65]
	v_mfma_f32_16x16x32_bf16 v[58:61], v[74:77], v[152:155], v[58:61]
	v_mfma_f32_16x16x32_bf16 v[46:49], v[66:69], v[170:173], v[46:49]
	v_mfma_f32_16x16x32_bf16 v[42:45], v[74:77], v[170:173], v[42:45]
	v_mfma_f32_16x16x32_bf16 v[30:33], v[66:69], v[178:181], v[30:33]
	v_mfma_f32_16x16x32_bf16 v[26:29], v[74:77], v[178:181], v[26:29]
	v_mfma_f32_16x16x32_bf16 v[22:25], v[66:69], v[186:189], v[22:25]
	v_mfma_f32_16x16x32_bf16 v[14:17], v[74:77], v[186:189], v[14:17]
	v_mfma_f32_16x16x32_bf16 v[62:65], v[70:73], v[166:169], v[62:65]
	v_mfma_f32_16x16x32_bf16 v[58:61], v[78:81], v[166:169], v[58:61]
	v_mfma_f32_16x16x32_bf16 v[46:49], v[70:73], v[174:177], v[46:49]
	v_mfma_f32_16x16x32_bf16 v[42:45], v[78:81], v[174:177], v[42:45]
	v_mfma_f32_16x16x32_bf16 v[30:33], v[70:73], v[182:185], v[30:33]
	v_mfma_f32_16x16x32_bf16 v[26:29], v[78:81], v[182:185], v[26:29]
	v_mfma_f32_16x16x32_bf16 v[22:25], v[70:73], v[190:193], v[22:25]
	v_mfma_f32_16x16x32_bf16 v[14:17], v[78:81], v[190:193], v[14:17]
	s_add_u32 s28, s52, 0x200080
	s_addc_u32 s29, s53, 0
	s_add_i32 s38, s60, 0x1c000
	v_lshl_add_u64 v[66:67], s[28:29], 0, v[0:1]
	s_mov_b32 m0, s38
	s_nop 0
	global_load_lds_dwordx4 v[66:67], off
	v_lshl_add_u64 v[66:67], s[28:29], 0, v[146:147]
	s_add_i32 m0, s38, 0x2000
	s_nop 0
	global_load_lds_dwordx4 v[66:67], off
	v_mfma_f32_16x16x32_bf16 v[54:57], v[194:197], v[152:155], v[54:57]
	v_mfma_f32_16x16x32_bf16 v[50:53], v[202:205], v[152:155], v[50:53]
	v_mfma_f32_16x16x32_bf16 v[38:41], v[194:197], v[170:173], v[38:41]
	v_mfma_f32_16x16x32_bf16 v[34:37], v[202:205], v[170:173], v[34:37]
	v_mfma_f32_16x16x32_bf16 v[18:21], v[194:197], v[178:181], v[18:21]
	v_mfma_f32_16x16x32_bf16 v[10:13], v[202:205], v[178:181], v[10:13]
	v_mfma_f32_16x16x32_bf16 v[6:9], v[194:197], v[186:189], v[6:9]
	v_mfma_f32_16x16x32_bf16 v[2:5], v[202:205], v[186:189], v[2:5]
	v_mfma_f32_16x16x32_bf16 v[54:57], v[198:201], v[166:169], v[54:57]
	v_mfma_f32_16x16x32_bf16 v[50:53], v[210:213], v[166:169], v[50:53]
	v_mfma_f32_16x16x32_bf16 v[38:41], v[198:201], v[174:177], v[38:41]
	v_mfma_f32_16x16x32_bf16 v[34:37], v[210:213], v[174:177], v[34:37]
	v_mfma_f32_16x16x32_bf16 v[18:21], v[198:201], v[182:185], v[18:21]
	v_mfma_f32_16x16x32_bf16 v[10:13], v[210:213], v[182:185], v[10:13]
	v_mfma_f32_16x16x32_bf16 v[6:9], v[198:201], v[190:193], v[6:9]
	v_mfma_f32_16x16x32_bf16 v[2:5], v[210:213], v[190:193], v[2:5]
	s_setprio 0
	s_add_i32 s75, s75, 2
	s_add_u32 s73, s73, 0x100
	s_addc_u32 s74, s74, 0
	s_cmpk_gt_u32 s75, 0x7d
	s_mov_b64 s[28:29], s[50:51]
	s_barrier
	s_cbranch_scc0 .LBB0_44
	s_cmp_lt_i32 s8, 64
	s_cselect_b64 s[50:51], -1, 0
	s_cmp_gt_i32 s8, 63
	s_cbranch_scc0 .LBB0_35
	s_mov_b64 s[52:53], 0x18000
	s_mov_b64 s[28:29], s[46:47]
	s_branch .LBB0_36

; #define PG8_STAGE(bufoff, gbase, voff) do { _Pragma("unroll") for (int _i = 0; _i < 2; ++_i) \
;         __builtin_amdgcn_global_load_lds((const unsigned*)((const char*)(gbase) + (voff)[_i]), (LAS unsigned*)(lds + (bufoff) + ldsw + _i * 8192), 16, 0, 0); } while (0)
; #define PG8_LDA(dst, b, h) do { _Pragma("unroll") for (int m = 0; m < 4; ++m) _Pragma("unroll") for (int k = 0; k < 2; ++k) dst[m][k] = *(const LAS bf16x8*)(lds + PG8_SA(b, h) + aoff + m * 2048 + k * 1024); } while (0)
; #define PG8_LDB(dst, b, h) do { _Pragma("unroll") for (int n = 0; n < 2; ++n) _Pragma("unroll") for (int k = 0; k < 2; ++k) dst[n][k] = *(const LAS bf16x8*)(lds + PG8_SB(b, h) + boff + n * 2048 + k * 1024); } while (0)
; #define PG8_MMA(ai, bj, At, Bt) do { __builtin_amdgcn_s_setprio(1); _Pragma("unroll") for (int m = 0; m < 4; ++m) _Pragma("unroll") for (int n = 0; n < 2; ++n) _Pragma("unroll") for (int k = 0; k < 2; ++k) \
;         acc[ai][bj][m][n] = __builtin_amdgcn_mfma_f32_16x16x32_bf16(Bt[n][k], At[m][k], acc[ai][bj][m][n], 0, 0, 0); __builtin_amdgcn_s_setprio(0); } while (0)
; #define PG8_WAIT_L(n) asm volatile("s_waitcnt lgkmcnt(" #n ")" ::: "memory")
; #define PG8_BAR __builtin_amdgcn_s_barrier()
; #define PG8_SCHED __builtin_amdgcn_sched_barrier(0)
; template <class Epi, class Sched>
; __device__ __forceinline__ void gemm_phase(LAS unsigned char* lds, const Gemm g, const Sched& S, const Epi& E) {
;     ...
;         for (int t = 0; t < nt; t += 2) {
;             const bool last = (t == nt - 2);
;             const char* a1 = cA + (size_t)(t + 1) * kstep;
;             const char* a2 = last ? nA : cA + (size_t)(t + 2) * kstep; const char* b2 = last ? nB : cB + (size_t)(t + 2) * kstep;
;             const char* a3 = a2 + kstep; const char* b3 = b2 + kstep;
;             PG8_LDB(B0, 0, 0); PG8_SCHED; PG8_LDA(At, 0, 0); PG8_STAGE(PG8_SA(1, 1), a1 + hstep, voffA);
;             PG8_WAIT_L(8); PG8_BAR; PG8_WAIT_L(0); PG8_MMA(0, 0, At, B0); PG8_BAR; PG8_SCHED;
;             PG8_LDB(B1, 0, 1); PG8_STAGE(PG8_SB(0, 0), b2, voffB);
;             PG8_BAR; PG8_WAIT_L(0); PG8_MMA(0, 1, At, B1); PG8_BAR;
;             PG8_LDA(At, 0, 1); PG8_STAGE(PG8_SA(0, 0), a2, voffA);
;             PG8_BAR; PG8_WAIT_L(0); PG8_MMA(1, 0, At, B0); PG8_BAR; PG8_SCHED;
.LBB0_58:
	v_add_u32_e32 v152, 0x10000, v137
	ds_read_b128 v[140:143], v152
	ds_read_b128 v[144:147], v152 offset:1024
	ds_read_b128 v[148:151], v152 offset:2048
	ds_read_b128 v[152:155], v152 offset:3072
	ds_read_b128 v[160:163], v139
	ds_read_b128 v[164:167], v139 offset:1024
	ds_read_b128 v[168:171], v139 offset:2048
	ds_read_b128 v[172:175], v139 offset:3072
	ds_read_b128 v[176:179], v139 offset:4096
	ds_read_b128 v[180:183], v139 offset:5120
	ds_read_b128 v[184:187], v139 offset:6144
	ds_read_b128 v[188:191], v139 offset:7168
	v_add_u32_e32 v156, 0x14000, v137
	ds_read_b128 v[192:195], v156
	ds_read_b128 v[196:199], v156 offset:1024
	ds_read_b128 v[200:203], v156 offset:2048
	ds_read_b128 v[204:207], v156 offset:3072
	s_waitcnt lgkmcnt(4)
	s_barrier
	s_waitcnt lgkmcnt(0)
	s_setprio 1
	v_mfma_f32_16x16x32_bf16 v[126:129], v[140:143], v[160:163], v[126:129]
	v_mfma_f32_16x16x32_bf16 v[122:125], v[148:151], v[160:163], v[122:125]
	v_mfma_f32_16x16x32_bf16 v[118:121], v[140:143], v[168:171], v[118:121]
	v_mfma_f32_16x16x32_bf16 v[114:117], v[148:151], v[168:171], v[114:117]
	v_mfma_f32_16x16x32_bf16 v[106:109], v[140:143], v[176:179], v[106:109]
	v_mfma_f32_16x16x32_bf16 v[98:101], v[148:151], v[176:179], v[98:101]
	v_mfma_f32_16x16x32_bf16 v[90:93], v[140:143], v[184:187], v[90:93]
	v_mfma_f32_16x16x32_bf16 v[82:85], v[148:151], v[184:187], v[82:85]
	v_mfma_f32_16x16x32_bf16 v[126:129], v[144:147], v[164:167], v[126:129]
	v_mfma_f32_16x16x32_bf16 v[122:125], v[152:155], v[164:167], v[122:125]
	v_mfma_f32_16x16x32_bf16 v[118:121], v[144:147], v[172:175], v[118:121]
	v_mfma_f32_16x16x32_bf16 v[114:117], v[152:155], v[172:175], v[114:117]
	v_mfma_f32_16x16x32_bf16 v[106:109], v[144:147], v[180:183], v[106:109]
	v_mfma_f32_16x16x32_bf16 v[98:101], v[152:155], v[180:183], v[98:101]
	v_mfma_f32_16x16x32_bf16 v[90:93], v[144:147], v[188:191], v[90:93]
	v_mfma_f32_16x16x32_bf16 v[82:85], v[152:155], v[188:191], v[82:85]
	s_add_u32 s52, s50, 0x100
	s_addc_u32 s53, s51, 0
	s_cmp_eq_u32 s71, 28
	s_cselect_b32 s57, s11, s53
	s_cselect_b32 s56, s29, s52
	s_cselect_b32 s55, s41, s70
	s_cselect_b32 s54, s43, s69
	v_lshl_add_u64 v[228:229], s[50:51], 0, v[134:135]
	s_add_i32 m0, s25, 0xc000
	s_nop 0
	global_load_lds_dwordx4 v[228:229], off
	v_lshl_add_u64 v[228:229], s[50:51], 0, v[132:133]
	s_add_i32 m0, s25, 0xe000
	s_nop 0
	global_load_lds_dwordx4 v[228:229], off
	v_mfma_f32_16x16x32_bf16 v[110:113], v[192:195], v[160:163], v[110:113]
	v_mfma_f32_16x16x32_bf16 v[102:105], v[200:203], v[160:163], v[102:105]
	v_mfma_f32_16x16x32_bf16 v[94:97], v[192:195], v[168:171], v[94:97]
	v_mfma_f32_16x16x32_bf16 v[86:89], v[200:203], v[168:171], v[86:89]
	v_mfma_f32_16x16x32_bf16 v[78:81], v[192:195], v[176:179], v[78:81]
	v_mfma_f32_16x16x32_bf16 v[74:77], v[200:203], v[176:179], v[74:77]
	v_mfma_f32_16x16x32_bf16 v[70:73], v[192:195], v[184:187], v[70:73]
	v_mfma_f32_16x16x32_bf16 v[66:69], v[200:203], v[184:187], v[66:69]
	v_mfma_f32_16x16x32_bf16 v[110:113], v[196:199], v[164:167], v[110:113]
	v_mfma_f32_16x16x32_bf16 v[102:105], v[204:207], v[164:167], v[102:105]
	v_mfma_f32_16x16x32_bf16 v[94:97], v[196:199], v[172:175], v[94:97]
	v_mfma_f32_16x16x32_bf16 v[86:89], v[204:207], v[172:175], v[86:89]
	v_mfma_f32_16x16x32_bf16 v[78:81], v[196:199], v[180:183], v[78:81]
	v_mfma_f32_16x16x32_bf16 v[74:77], v[204:207], v[180:183], v[74:77]
	v_mfma_f32_16x16x32_bf16 v[70:73], v[196:199], v[188:191], v[70:73]
	v_mfma_f32_16x16x32_bf16 v[66:69], v[204:207], v[188:191], v[66:69]
	s_setprio 0
	s_barrier
	s_add_i32 s38, s63, 0x10000
	v_lshl_add_u64 v[156:157], s[54:55], 0, v[0:1]
	s_mov_b32 m0, s38
	v_lshl_add_u64 v[210:211], s[54:55], 0, v[130:131]
	global_load_lds_dwordx4 v[156:157], off
	s_add_i32 m0, s38, 0x2000
	s_nop 0
	global_load_lds_dwordx4 v[210:211], off
	s_mov_b32 m0, s25
	v_lshl_add_u64 v[212:213], s[56:57], 0, v[0:1]
	global_load_lds_dwordx4 v[212:213], off
	v_lshl_add_u64 v[214:215], s[56:57], 0, v[130:131]
	s_mov_b32 m0, s27
	s_nop 0
	global_load_lds_dwordx4 v[214:215], off
	ds_read_b128 v[160:163], v139 offset:16384
	ds_read_b128 v[164:167], v139 offset:17408
	ds_read_b128 v[168:171], v139 offset:18432
	ds_read_b128 v[172:175], v139 offset:19456
	ds_read_b128 v[176:179], v139 offset:20480
	ds_read_b128 v[180:183], v139 offset:21504
	ds_read_b128 v[184:187], v139 offset:22528
	ds_read_b128 v[188:191], v139 offset:23552
	s_waitcnt vmcnt(4)
	s_barrier
	s_waitcnt lgkmcnt(0)
	s_setprio 1
	v_mfma_f32_16x16x32_bf16 v[62:65], v[140:143], v[160:163], v[62:65]
	v_mfma_f32_16x16x32_bf16 v[58:61], v[148:151], v[160:163], v[58:61]
	v_mfma_f32_16x16x32_bf16 v[54:57], v[140:143], v[168:171], v[54:57]
	v_mfma_f32_16x16x32_bf16 v[50:53], v[148:151], v[168:171], v[50:53]
	v_mfma_f32_16x16x32_bf16 v[38:41], v[140:143], v[176:179], v[38:41]
	v_mfma_f32_16x16x32_bf16 v[34:37], v[148:151], v[176:179], v[34:37]
	v_mfma_f32_16x16x32_bf16 v[22:25], v[140:143], v[184:187], v[22:25]
	v_mfma_f32_16x16x32_bf16 v[18:21], v[148:151], v[184:187], v[18:21]
	v_mfma_f32_16x16x32_bf16 v[62:65], v[144:147], v[164:167], v[62:65]
	v_mfma_f32_16x16x32_bf16 v[58:61], v[152:155], v[164:167], v[58:61]
	v_mfma_f32_16x16x32_bf16 v[54:57], v[144:147], v[172:175], v[54:57]
	v_mfma_f32_16x16x32_bf16 v[50:53], v[152:155], v[172:175], v[50:53]
	v_mfma_f32_16x16x32_bf16 v[38:41], v[144:147], v[180:183], v[38:41]
	v_mfma_f32_16x16x32_bf16 v[34:37], v[152:155], v[180:183], v[34:37]
	v_mfma_f32_16x16x32_bf16 v[22:25], v[144:147], v[188:191], v[22:25]
	v_mfma_f32_16x16x32_bf16 v[18:21], v[152:155], v[188:191], v[18:21]
	v_mfma_f32_16x16x32_bf16 v[46:49], v[192:195], v[160:163], v[46:49]
	v_mfma_f32_16x16x32_bf16 v[42:45], v[200:203], v[160:163], v[42:45]
	v_mfma_f32_16x16x32_bf16 v[30:33], v[192:195], v[168:171], v[30:33]
	v_mfma_f32_16x16x32_bf16 v[26:29], v[200:203], v[168:171], v[26:29]
	v_mfma_f32_16x16x32_bf16 v[14:17], v[192:195], v[176:179], v[14:17]
	v_mfma_f32_16x16x32_bf16 v[10:13], v[200:203], v[176:179], v[10:13]
	v_mfma_f32_16x16x32_bf16 v[6:9], v[192:195], v[184:187], v[6:9]
	v_mfma_f32_16x16x32_bf16 v[2:5], v[200:203], v[184:187], v[2:5]
	v_mfma_f32_16x16x32_bf16 v[46:49], v[196:199], v[164:167], v[46:49]
	v_mfma_f32_16x16x32_bf16 v[42:45], v[204:207], v[164:167], v[42:45]
	v_mfma_f32_16x16x32_bf16 v[30:33], v[196:199], v[172:175], v[30:33]
	v_mfma_f32_16x16x32_bf16 v[26:29], v[204:207], v[172:175], v[26:29]
	v_mfma_f32_16x16x32_bf16 v[14:17], v[196:199], v[180:183], v[14:17]
	v_mfma_f32_16x16x32_bf16 v[10:13], v[204:207], v[180:183], v[10:13]
	v_mfma_f32_16x16x32_bf16 v[6:9], v[196:199], v[188:191], v[6:9]
	v_mfma_f32_16x16x32_bf16 v[2:5], v[204:207], v[188:191], v[2:5]
	s_setprio 0
	s_barrier
; #define PG8_STAGE(bufoff, gbase, voff) do { _Pragma("unroll") for (int _i = 0; _i < 2; ++_i) \
;         __builtin_amdgcn_global_load_lds((const unsigned*)((const char*)(gbase) + (voff)[_i]), (LAS unsigned*)(lds + (bufoff) + ldsw + _i * 8192), 16, 0, 0); } while (0)
; #define PG8_LDA(dst, b, h) do { _Pragma("unroll") for (int m = 0; m < 4; ++m) _Pragma("unroll") for (int k = 0; k < 2; ++k) dst[m][k] = *(const LAS bf16x8*)(lds + PG8_SA(b, h) + aoff + m * 2048 + k * 1024); } while (0)
; #define PG8_LDB(dst, b, h) do { _Pragma("unroll") for (int n = 0; n < 2; ++n) _Pragma("unroll") for (int k = 0; k < 2; ++k) dst[n][k] = *(const LAS bf16x8*)(lds + PG8_SB(b, h) + boff + n * 2048 + k * 1024); } while (0)
; #define PG8_WAIT_V(n) asm volatile("s_waitcnt vmcnt(" #n ")" ::: "memory")
; #define PG8_WAIT_L(n) asm volatile("s_waitcnt lgkmcnt(" #n ")" ::: "memory")
; #define PG8_BAR __builtin_amdgcn_s_barrier()
; #define PG8_SCHED __builtin_amdgcn_sched_barrier(0)
; template <class Epi, class Sched>
; __device__ __forceinline__ void gemm_phase(LAS unsigned char* lds, const Gemm g, const Sched& S, const Epi& E) {
;     ...
;             PG8_LDB(B0, 0, 0); PG8_SCHED; PG8_LDA(At, 0, 0); PG8_STAGE(PG8_SA(1, 1), a1 + hstep, voffA);
;             PG8_WAIT_L(8); PG8_BAR; PG8_WAIT_L(0); PG8_MMA(0, 0, At, B0); PG8_BAR; PG8_SCHED;
;             PG8_LDB(B1, 0, 1); PG8_STAGE(PG8_SB(0, 0), b2, voffB);
;             PG8_BAR; PG8_WAIT_L(0); PG8_MMA(0, 1, At, B1); PG8_BAR;
;             PG8_LDA(At, 0, 1); PG8_STAGE(PG8_SA(0, 0), a2, voffA);
;             PG8_BAR; PG8_WAIT_L(0); PG8_MMA(1, 0, At, B0); PG8_BAR; PG8_SCHED;
;             PG8_STAGE(PG8_SB(0, 1), b2 + hstep, voffB);
;             PG8_WAIT_V(6); PG8_BAR; PG8_MMA(1, 1, At, B1); PG8_BAR;
;             PG8_LDB(B0, 1, 0); PG8_SCHED; PG8_LDA(At, 1, 0); PG8_STAGE(PG8_SA(0, 1), a2 + hstep, voffA);
;             PG8_WAIT_L(8); PG8_BAR; PG8_WAIT_L(0); PG8_MMA(0, 0, At, B0); PG8_BAR; PG8_SCHED;
;             PG8_LDB(B1, 1, 1); PG8_STAGE(PG8_SB(1, 0), b3, voffB);
;             PG8_BAR; PG8_WAIT_L(0); PG8_MMA(0, 1, At, B1); PG8_BAR;
;             PG8_LDA(At, 1, 1); PG8_STAGE(PG8_SA(1, 0), a3, voffA);
;             PG8_BAR; PG8_WAIT_L(0); PG8_MMA(1, 0, At, B0); PG8_BAR; PG8_SCHED;
;             PG8_STAGE(PG8_SB(1, 1), b3 + hstep, voffB);
;             PG8_WAIT_V(6); PG8_BAR; PG8_MMA(1, 1, At, B1); PG8_BAR;
	s_add_u32 s38, s54, 0x200000
	s_addc_u32 s39, s55, 0
	s_add_i32 s50, s63, 0x14000
	v_lshl_add_u64 v[140:141], s[38:39], 0, v[0:1]
	s_mov_b32 m0, s50
	s_nop 0
	global_load_lds_dwordx4 v[140:141], off
	v_lshl_add_u64 v[140:141], s[38:39], 0, v[130:131]
	s_add_i32 m0, s50, 0x2000
	s_nop 0
	global_load_lds_dwordx4 v[140:141], off
	v_add_u32_e32 v152, 0x18000, v137
	ds_read_b128 v[140:143], v152
	ds_read_b128 v[144:147], v152 offset:1024
	ds_read_b128 v[148:151], v152 offset:2048
	ds_read_b128 v[152:155], v152 offset:3072
	ds_read_b128 v[160:163], v139 offset:32768
	ds_read_b128 v[164:167], v139 offset:33792
	ds_read_b128 v[168:171], v139 offset:34816
	ds_read_b128 v[172:175], v139 offset:35840
	ds_read_b128 v[176:179], v139 offset:36864
	ds_read_b128 v[180:183], v139 offset:37888
	ds_read_b128 v[184:187], v139 offset:38912
	ds_read_b128 v[188:191], v139 offset:39936
	v_add_u32_e32 v204, 0x1c000, v137
	ds_read_b128 v[192:195], v204
	ds_read_b128 v[196:199], v204 offset:1024
	ds_read_b128 v[200:203], v204 offset:2048
	ds_read_b128 v[204:207], v204 offset:3072
	s_waitcnt lgkmcnt(4)
	s_barrier
	s_waitcnt lgkmcnt(0)
	s_setprio 1
	v_mfma_f32_16x16x32_bf16 v[126:129], v[140:143], v[160:163], v[126:129]
	v_mfma_f32_16x16x32_bf16 v[122:125], v[148:151], v[160:163], v[122:125]
	v_mfma_f32_16x16x32_bf16 v[118:121], v[140:143], v[168:171], v[118:121]
	v_mfma_f32_16x16x32_bf16 v[114:117], v[148:151], v[168:171], v[114:117]
	v_mfma_f32_16x16x32_bf16 v[106:109], v[140:143], v[176:179], v[106:109]
	v_mfma_f32_16x16x32_bf16 v[98:101], v[148:151], v[176:179], v[98:101]
	v_mfma_f32_16x16x32_bf16 v[90:93], v[140:143], v[184:187], v[90:93]
	v_mfma_f32_16x16x32_bf16 v[82:85], v[148:151], v[184:187], v[82:85]
	v_mfma_f32_16x16x32_bf16 v[126:129], v[144:147], v[164:167], v[126:129]
	v_mfma_f32_16x16x32_bf16 v[122:125], v[152:155], v[164:167], v[122:125]
	v_mfma_f32_16x16x32_bf16 v[118:121], v[144:147], v[172:175], v[118:121]
	v_mfma_f32_16x16x32_bf16 v[114:117], v[152:155], v[172:175], v[114:117]
	v_mfma_f32_16x16x32_bf16 v[106:109], v[144:147], v[180:183], v[106:109]
	v_mfma_f32_16x16x32_bf16 v[98:101], v[152:155], v[180:183], v[98:101]
	v_mfma_f32_16x16x32_bf16 v[90:93], v[144:147], v[188:191], v[90:93]
	v_mfma_f32_16x16x32_bf16 v[82:85], v[152:155], v[188:191], v[82:85]
	s_add_u32 s38, s56, 0x200000
	s_addc_u32 s39, s57, 0
	s_mov_b32 m0, s64
	v_lshl_add_u64 v[226:227], s[38:39], 0, v[0:1]
	global_load_lds_dwordx4 v[226:227], off
	v_lshl_add_u64 v[226:227], s[38:39], 0, v[130:131]
	s_mov_b32 m0, s65
	s_nop 0
	global_load_lds_dwordx4 v[226:227], off
	v_mfma_f32_16x16x32_bf16 v[110:113], v[192:195], v[160:163], v[110:113]
	v_mfma_f32_16x16x32_bf16 v[102:105], v[200:203], v[160:163], v[102:105]
	v_mfma_f32_16x16x32_bf16 v[94:97], v[192:195], v[168:171], v[94:97]
	v_mfma_f32_16x16x32_bf16 v[86:89], v[200:203], v[168:171], v[86:89]
	v_mfma_f32_16x16x32_bf16 v[78:81], v[192:195], v[176:179], v[78:81]
	v_mfma_f32_16x16x32_bf16 v[74:77], v[200:203], v[176:179], v[74:77]
	v_mfma_f32_16x16x32_bf16 v[70:73], v[192:195], v[184:187], v[70:73]
	v_mfma_f32_16x16x32_bf16 v[66:69], v[200:203], v[184:187], v[66:69]
	v_mfma_f32_16x16x32_bf16 v[110:113], v[196:199], v[164:167], v[110:113]
	v_mfma_f32_16x16x32_bf16 v[102:105], v[204:207], v[164:167], v[102:105]
	v_mfma_f32_16x16x32_bf16 v[94:97], v[196:199], v[172:175], v[94:97]
	v_mfma_f32_16x16x32_bf16 v[86:89], v[204:207], v[172:175], v[86:89]
	v_mfma_f32_16x16x32_bf16 v[78:81], v[196:199], v[180:183], v[78:81]
	v_mfma_f32_16x16x32_bf16 v[74:77], v[204:207], v[180:183], v[74:77]
	v_mfma_f32_16x16x32_bf16 v[70:73], v[196:199], v[188:191], v[70:73]
	v_mfma_f32_16x16x32_bf16 v[66:69], v[204:207], v[188:191], v[66:69]
	s_setprio 0
	s_barrier
	s_add_i32 s38, s63, 0x18000
	v_lshl_add_u64 v[156:157], v[156:157], 0, s[36:37]
	s_mov_b32 m0, s38
	s_nop 0
	global_load_lds_dwordx4 v[156:157], off
	v_lshl_add_u64 v[156:157], v[210:211], 0, s[36:37]
	s_add_i32 m0, s38, 0x2000
	s_nop 0
	global_load_lds_dwordx4 v[156:157], off
	s_mov_b32 m0, s66
	v_lshl_add_u64 v[156:157], v[212:213], 0, s[36:37]
	global_load_lds_dwordx4 v[156:157], off
	v_lshl_add_u64 v[156:157], v[214:215], 0, s[36:37]
	s_mov_b32 m0, s67
	s_nop 0
	global_load_lds_dwordx4 v[156:157], off
	ds_read_b128 v[160:163], v139 offset:49152
	ds_read_b128 v[164:167], v139 offset:50176
	ds_read_b128 v[168:171], v139 offset:51200
	ds_read_b128 v[172:175], v139 offset:52224
	ds_read_b128 v[176:179], v139 offset:53248
	ds_read_b128 v[180:183], v139 offset:54272
	ds_read_b128 v[184:187], v139 offset:55296
	ds_read_b128 v[188:191], v139 offset:56320
	s_waitcnt vmcnt(4)
	s_barrier
; #define PG8_STAGE(bufoff, gbase, voff) do { _Pragma("unroll") for (int _i = 0; _i < 2; ++_i) \
;         __builtin_amdgcn_global_load_lds((const unsigned*)((const char*)(gbase) + (voff)[_i]), (LAS unsigned*)(lds + (bufoff) + ldsw + _i * 8192), 16, 0, 0); } while (0)
; #define PG8_LDA(dst, b, h) do { _Pragma("unroll") for (int m = 0; m < 4; ++m) _Pragma("unroll") for (int k = 0; k < 2; ++k) dst[m][k] = *(const LAS bf16x8*)(lds + PG8_SA(b, h) + aoff + m * 2048 + k * 1024); } while (0)
; #define PG8_MMA(ai, bj, At, Bt) do { __builtin_amdgcn_s_setprio(1); _Pragma("unroll") for (int m = 0; m < 4; ++m) _Pragma("unroll") for (int n = 0; n < 2; ++n) _Pragma("unroll") for (int k = 0; k < 2; ++k) \
;         acc[ai][bj][m][n] = __builtin_amdgcn_mfma_f32_16x16x32_bf16(Bt[n][k], At[m][k], acc[ai][bj][m][n], 0, 0, 0); __builtin_amdgcn_s_setprio(0); } while (0)
; #define PG8_WAIT_V(n) asm volatile("s_waitcnt vmcnt(" #n ")" ::: "memory")
; #define PG8_WAIT_L(n) asm volatile("s_waitcnt lgkmcnt(" #n ")" ::: "memory")
; #define PG8_BAR __builtin_amdgcn_s_barrier()
; #define PG8_SCHED __builtin_amdgcn_sched_barrier(0)
;     __device__ __forceinline__ void operator()(const f32x4 (&acc)[2][2][4][2], const Unit& u, int wr, int wc, int fr, int fq) const {
;         const int row0 = u.pm * BM + wr * 64 + fr, col0 = u.pn * BM + wc * 32 + 4 * fq;
;         float* base = part + (size_t)u.ks * Mp * ldc;
; #pragma unroll
;         for (int ai = 0; ai < 2; ++ai)
; #pragma unroll
;             for (int m = 0; m < 4; ++m) { float* rowp = base + (size_t)(row0 + ai * HALF + m * 16) * ldc + col0;
; #pragma unroll
;                 for (int bj = 0; bj < 2; ++bj)
; #pragma unroll
;                     for (int n = 0; n < 2; ++n) *(f32x4*)(rowp + bj * HALF + n * 16) = acc[ai][bj][m][n]; }
;     }
; template <class Epi, class Sched>
; __device__ __forceinline__ void gemm_phase(LAS unsigned char* lds, const Gemm g, const Sched& S, const Epi& E) {
;     ...
;             PG8_BAR; PG8_WAIT_L(0); PG8_MMA(0, 1, At, B1); PG8_BAR;
;             PG8_LDA(At, 1, 1); PG8_STAGE(PG8_SA(1, 0), a3, voffA);
;             PG8_BAR; PG8_WAIT_L(0); PG8_MMA(1, 0, At, B0); PG8_BAR; PG8_SCHED;
;             PG8_STAGE(PG8_SB(1, 1), b3 + hstep, voffB);
;             PG8_WAIT_V(6); PG8_BAR; PG8_MMA(1, 1, At, B1); PG8_BAR;
;         }
;         E(acc, cur, wr, wc, fr, fq);
;         if (!has_next) break;
	s_waitcnt lgkmcnt(0)
	s_setprio 1
	v_mfma_f32_16x16x32_bf16 v[62:65], v[140:143], v[160:163], v[62:65]
	v_mfma_f32_16x16x32_bf16 v[58:61], v[148:151], v[160:163], v[58:61]
	v_mfma_f32_16x16x32_bf16 v[54:57], v[140:143], v[168:171], v[54:57]
	v_mfma_f32_16x16x32_bf16 v[50:53], v[148:151], v[168:171], v[50:53]
	v_mfma_f32_16x16x32_bf16 v[38:41], v[140:143], v[176:179], v[38:41]
	v_mfma_f32_16x16x32_bf16 v[34:37], v[148:151], v[176:179], v[34:37]
	v_mfma_f32_16x16x32_bf16 v[22:25], v[140:143], v[184:187], v[22:25]
	v_mfma_f32_16x16x32_bf16 v[18:21], v[148:151], v[184:187], v[18:21]
	v_mfma_f32_16x16x32_bf16 v[62:65], v[144:147], v[164:167], v[62:65]
	v_mfma_f32_16x16x32_bf16 v[58:61], v[152:155], v[164:167], v[58:61]
	v_mfma_f32_16x16x32_bf16 v[54:57], v[144:147], v[172:175], v[54:57]
	v_mfma_f32_16x16x32_bf16 v[50:53], v[152:155], v[172:175], v[50:53]
	v_mfma_f32_16x16x32_bf16 v[38:41], v[144:147], v[180:183], v[38:41]
	v_mfma_f32_16x16x32_bf16 v[34:37], v[152:155], v[180:183], v[34:37]
	v_mfma_f32_16x16x32_bf16 v[22:25], v[144:147], v[188:191], v[22:25]
	v_mfma_f32_16x16x32_bf16 v[18:21], v[152:155], v[188:191], v[18:21]
	s_add_u32 s38, s54, 0x200080
	s_addc_u32 s39, s55, 0
	s_add_i32 s50, s63, 0x1c000
	v_lshl_add_u64 v[140:141], s[38:39], 0, v[0:1]
	s_mov_b32 m0, s50
	s_nop 0
	global_load_lds_dwordx4 v[140:141], off
	v_lshl_add_u64 v[140:141], s[38:39], 0, v[130:131]
	s_add_i32 m0, s50, 0x2000
	s_nop 0
	global_load_lds_dwordx4 v[140:141], off
	v_mfma_f32_16x16x32_bf16 v[46:49], v[192:195], v[160:163], v[46:49]
	v_mfma_f32_16x16x32_bf16 v[42:45], v[200:203], v[160:163], v[42:45]
	v_mfma_f32_16x16x32_bf16 v[30:33], v[192:195], v[168:171], v[30:33]
	v_mfma_f32_16x16x32_bf16 v[26:29], v[200:203], v[168:171], v[26:29]
	v_mfma_f32_16x16x32_bf16 v[14:17], v[192:195], v[176:179], v[14:17]
	v_mfma_f32_16x16x32_bf16 v[10:13], v[200:203], v[176:179], v[10:13]
	v_mfma_f32_16x16x32_bf16 v[6:9], v[192:195], v[184:187], v[6:9]
	v_mfma_f32_16x16x32_bf16 v[2:5], v[200:203], v[184:187], v[2:5]
	v_mfma_f32_16x16x32_bf16 v[46:49], v[196:199], v[164:167], v[46:49]
	v_mfma_f32_16x16x32_bf16 v[42:45], v[204:207], v[164:167], v[42:45]
	v_mfma_f32_16x16x32_bf16 v[30:33], v[196:199], v[172:175], v[30:33]
	v_mfma_f32_16x16x32_bf16 v[26:29], v[204:207], v[172:175], v[26:29]
	v_mfma_f32_16x16x32_bf16 v[14:17], v[196:199], v[180:183], v[14:17]
	v_mfma_f32_16x16x32_bf16 v[10:13], v[204:207], v[180:183], v[10:13]
	v_mfma_f32_16x16x32_bf16 v[6:9], v[196:199], v[188:191], v[6:9]
	v_mfma_f32_16x16x32_bf16 v[2:5], v[204:207], v[188:191], v[2:5]
	s_setprio 0
	s_add_i32 s71, s71, 2
	s_add_u32 s69, s69, 0x100
	s_addc_u32 s70, s70, 0
	s_cmp_gt_u32 s71, 29
	s_mov_b64 s[50:51], s[52:53]
	s_barrier
	s_cbranch_scc0 .LBB0_58
	s_ashr_i32 s11, s10, 31
	s_lshl_b64 s[10:11], s[10:11], 24
	v_lshl_or_b32 v140, s26, 8, v138
	s_add_u32 s10, s8, s10
	v_lshl_add_u32 v142, s24, 8, v136
	s_addc_u32 s11, s9, s11
	v_ashrrev_i32_e32 v141, 31, v140
	v_ashrrev_i32_e32 v143, 31, v142
	v_lshl_add_u64 v[140:141], v[140:141], 2, s[10:11]
	v_lshlrev_b64 v[144:145], 13, v[142:143]
	v_lshl_add_u64 v[144:145], v[140:141], 0, v[144:145]
	global_store_dwordx4 v[144:145], v[126:129], off
	global_store_dwordx4 v[144:145], v[122:125], off offset:64
	global_store_dwordx4 v[144:145], v[110:113], off offset:512
	global_store_dwordx4 v[144:145], v[102:105], off offset:576
	s_mov_b64 s[10:11], 0x100000
	s_mov_b32 s26, s40
	v_or_b32_e32 v102, 16, v142
	v_ashrrev_i32_e32 v103, 31, v102
	v_lshlrev_b64 v[102:103], 13, v[102:103]
	v_lshl_add_u64 v[102:103], v[140:141], 0, v[102:103]
	global_store_dwordx4 v[102:103], v[118:121], off
	global_store_dwordx4 v[102:103], v[114:117], off offset:64
	global_store_dwordx4 v[102:103], v[94:97], off offset:512
	global_store_dwordx4 v[102:103], v[86:89], off offset:576
	s_mov_b32 s24, s42
	s_mov_b64 s[52:53], s[48:49]
	v_or_b32_e32 v86, 32, v142
	v_ashrrev_i32_e32 v87, 31, v86
	v_lshlrev_b64 v[86:87], 13, v[86:87]
	v_lshl_add_u64 v[86:87], v[140:141], 0, v[86:87]
	global_store_dwordx4 v[86:87], v[106:109], off
	global_store_dwordx4 v[86:87], v[98:101], off offset:64
	global_store_dwordx4 v[86:87], v[78:81], off offset:512
	global_store_dwordx4 v[86:87], v[74:77], off offset:576
	s_mov_b64 s[50:51], s[46:47]
	s_nop 0
	v_or_b32_e32 v74, 48, v142
	v_ashrrev_i32_e32 v75, 31, v74
	v_lshlrev_b64 v[74:75], 13, v[74:75]
	v_lshl_add_u64 v[74:75], v[140:141], 0, v[74:75]
	global_store_dwordx4 v[74:75], v[90:93], off
	global_store_dwordx4 v[74:75], v[82:85], off offset:64
	global_store_dwordx4 v[74:75], v[70:73], off offset:512
	global_store_dwordx4 v[74:75], v[66:69], off offset:576
	s_nop 1
	v_add_co_u32_e32 v68, vcc, s93, v144
	v_lshl_add_u64 v[66:67], v[144:145], 0, s[10:11]
	s_nop 0
	v_addc_co_u32_e32 v69, vcc, 0, v145, vcc
	s_mov_b64 s[10:11], 0x120000
	global_store_dwordx4 v[68:69], v[62:65], off
	global_store_dwordx4 v[66:67], v[58:61], off offset:64
	global_store_dwordx4 v[66:67], v[46:49], off offset:512
	global_store_dwordx4 v[66:67], v[42:45], off offset:576
	s_nop 1
	v_lshl_add_u64 v[42:43], v[144:145], 0, s[10:11]
	s_mov_b32 s10, 0x120000
	v_add_co_u32_e32 v44, vcc, s10, v144
	s_mov_b64 s[10:11], 0x140000
	s_nop 0
	v_addc_co_u32_e32 v45, vcc, 0, v145, vcc
	global_store_dwordx4 v[44:45], v[54:57], off
	global_store_dwordx4 v[42:43], v[50:53], off offset:64
	global_store_dwordx4 v[42:43], v[30:33], off offset:512
	global_store_dwordx4 v[42:43], v[26:29], off offset:576
	s_nop 1
	v_lshl_add_u64 v[26:27], v[144:145], 0, s[10:11]
	s_mov_b32 s10, 0x140000
	v_add_co_u32_e32 v28, vcc, s10, v144
	s_mov_b64 s[10:11], 0x160000
	s_nop 0
	v_addc_co_u32_e32 v29, vcc, 0, v145, vcc
	global_store_dwordx4 v[28:29], v[38:41], off
	global_store_dwordx4 v[26:27], v[34:37], off offset:64
	global_store_dwordx4 v[26:27], v[14:17], off offset:512
	global_store_dwordx4 v[26:27], v[10:13], off offset:576
	s_nop 1
	v_add_co_u32_e32 v12, vcc, 0x160000, v144
	v_lshl_add_u64 v[10:11], v[144:145], 0, s[10:11]
	s_nop 0
	v_addc_co_u32_e32 v13, vcc, 0, v145, vcc
	s_and_b64 vcc, exec, s[44:45]
	s_mov_b32 s10, s28
	global_store_dwordx4 v[12:13], v[22:25], off
	global_store_dwordx4 v[10:11], v[18:21], off offset:64
	global_store_dwordx4 v[10:11], v[6:9], off offset:512
	global_store_dwordx4 v[10:11], v[2:5], off offset:576
	s_cbranch_vccz .LBB0_55
	s_waitcnt vmcnt(0)
	s_cmpk_gt_u32 s60, 0xff
	s_cbranch_scc1 .LBB0_62
	s_barrier

; #define PG8_STAGE(bufoff, gbase, voff) do { _Pragma("unroll") for (int _i = 0; _i < 2; ++_i) \
;         __builtin_amdgcn_global_load_lds((const unsigned*)((const char*)(gbase) + (voff)[_i]), (LAS unsigned*)(lds + (bufoff) + ldsw + _i * 8192), 16, 0, 0); } while (0)
; #define PG8_LDA(dst, b, h) do { _Pragma("unroll") for (int m = 0; m < 4; ++m) _Pragma("unroll") for (int k = 0; k < 2; ++k) dst[m][k] = *(const LAS bf16x8*)(lds + PG8_SA(b, h) + aoff + m * 2048 + k * 1024); } while (0)
; #define PG8_LDB(dst, b, h) do { _Pragma("unroll") for (int n = 0; n < 2; ++n) _Pragma("unroll") for (int k = 0; k < 2; ++k) dst[n][k] = *(const LAS bf16x8*)(lds + PG8_SB(b, h) + boff + n * 2048 + k * 1024); } while (0)
; #define PG8_MMA(ai, bj, At, Bt) do { __builtin_amdgcn_s_setprio(1); _Pragma("unroll") for (int m = 0; m < 4; ++m) _Pragma("unroll") for (int n = 0; n < 2; ++n) _Pragma("unroll") for (int k = 0; k < 2; ++k) \
;         acc[ai][bj][m][n] = __builtin_amdgcn_mfma_f32_16x16x32_bf16(Bt[n][k], At[m][k], acc[ai][bj][m][n], 0, 0, 0); __builtin_amdgcn_s_setprio(0); } while (0)
; #define PG8_WAIT_V(n) asm volatile("s_waitcnt vmcnt(" #n ")" ::: "memory")
; #define PG8_WAIT_L(n) asm volatile("s_waitcnt lgkmcnt(" #n ")" ::: "memory")
; #define PG8_BAR __builtin_amdgcn_s_barrier()
; #define PG8_SCHED __builtin_amdgcn_sched_barrier(0)
; template <class Epi, class Sched>
; __device__ __forceinline__ void gemm_phase(LAS unsigned char* lds, const Gemm g, const Sched& S, const Epi& E) {
;     ...
;             PG8_LDB(B0, 0, 0); PG8_SCHED; PG8_LDA(At, 0, 0); PG8_STAGE(PG8_SA(1, 1), a1 + hstep, voffA);
;             PG8_WAIT_L(8); PG8_BAR; PG8_WAIT_L(0); PG8_MMA(0, 0, At, B0); PG8_BAR; PG8_SCHED;
;             PG8_LDB(B1, 0, 1); PG8_STAGE(PG8_SB(0, 0), b2, voffB);
;             PG8_BAR; PG8_WAIT_L(0); PG8_MMA(0, 1, At, B1); PG8_BAR;
;             PG8_LDA(At, 0, 1); PG8_STAGE(PG8_SA(0, 0), a2, voffA);
;             PG8_BAR; PG8_WAIT_L(0); PG8_MMA(1, 0, At, B0); PG8_BAR; PG8_SCHED;
;             PG8_STAGE(PG8_SB(0, 1), b2 + hstep, voffB);
;             PG8_WAIT_V(6); PG8_BAR; PG8_MMA(1, 1, At, B1); PG8_BAR;
.LBB0_73:
	v_add_u32_e32 v140, 0x10000, v143
	ds_read_b128 v[146:149], v140
	ds_read_b128 v[150:153], v140 offset:1024
	ds_read_b128 v[154:157], v140 offset:2048
	ds_read_b128 v[160:163], v140 offset:3072
	ds_read_b128 v[164:167], v145
	ds_read_b128 v[168:171], v145 offset:1024
	ds_read_b128 v[172:175], v145 offset:2048
	ds_read_b128 v[176:179], v145 offset:3072
	ds_read_b128 v[180:183], v145 offset:4096
	ds_read_b128 v[184:187], v145 offset:5120
	ds_read_b128 v[188:191], v145 offset:6144
	ds_read_b128 v[192:195], v145 offset:7168
	v_add_u32_e32 v140, 0x14000, v143
	ds_read_b128 v[196:199], v140
	ds_read_b128 v[200:203], v140 offset:1024
	ds_read_b128 v[204:207], v140 offset:2048
	ds_read_b128 v[210:213], v140 offset:3072
	s_waitcnt lgkmcnt(4)
	s_barrier
	s_waitcnt lgkmcnt(0)
	s_setprio 1
	v_mfma_f32_16x16x32_bf16 v[126:129], v[146:149], v[164:167], v[126:129]
	v_mfma_f32_16x16x32_bf16 v[122:125], v[154:157], v[164:167], v[122:125]
	v_mfma_f32_16x16x32_bf16 v[110:113], v[146:149], v[172:175], v[110:113]
	v_mfma_f32_16x16x32_bf16 v[106:109], v[154:157], v[172:175], v[106:109]
	v_mfma_f32_16x16x32_bf16 v[94:97], v[146:149], v[180:183], v[94:97]
	v_mfma_f32_16x16x32_bf16 v[90:93], v[154:157], v[180:183], v[90:93]
	v_mfma_f32_16x16x32_bf16 v[78:81], v[146:149], v[188:191], v[78:81]
	v_mfma_f32_16x16x32_bf16 v[74:77], v[154:157], v[188:191], v[74:77]
	v_mfma_f32_16x16x32_bf16 v[126:129], v[150:153], v[168:171], v[126:129]
	v_mfma_f32_16x16x32_bf16 v[122:125], v[160:163], v[168:171], v[122:125]
	v_mfma_f32_16x16x32_bf16 v[110:113], v[150:153], v[176:179], v[110:113]
	v_mfma_f32_16x16x32_bf16 v[106:109], v[160:163], v[176:179], v[106:109]
	v_mfma_f32_16x16x32_bf16 v[94:97], v[150:153], v[184:187], v[94:97]
	v_mfma_f32_16x16x32_bf16 v[90:93], v[160:163], v[184:187], v[90:93]
	v_mfma_f32_16x16x32_bf16 v[78:81], v[150:153], v[192:195], v[78:81]
	v_mfma_f32_16x16x32_bf16 v[74:77], v[160:163], v[192:195], v[74:77]
	s_add_u32 s38, s46, 0xfff80080
	s_addc_u32 s39, s47, -1
	s_cmp_eq_u32 s73, 28
	s_cselect_b32 s51, s29, s39
	s_cselect_b32 s50, s69, s38
	s_cselect_b32 s49, s27, s72
	s_cselect_b32 s48, s70, s71
	v_lshl_add_u64 v[228:229], s[46:47], 0, v[138:139]
	s_add_i32 m0, s9, 0xc000
	s_nop 0
	global_load_lds_dwordx4 v[228:229], off
	v_lshl_add_u64 v[228:229], s[46:47], 0, v[136:137]
	s_add_i32 m0, s9, 0xe000
	s_nop 0
	global_load_lds_dwordx4 v[228:229], off
	v_mfma_f32_16x16x32_bf16 v[118:121], v[196:199], v[164:167], v[118:121]
	v_mfma_f32_16x16x32_bf16 v[114:117], v[204:207], v[164:167], v[114:117]
	v_mfma_f32_16x16x32_bf16 v[102:105], v[196:199], v[172:175], v[102:105]
	v_mfma_f32_16x16x32_bf16 v[98:101], v[204:207], v[172:175], v[98:101]
	v_mfma_f32_16x16x32_bf16 v[86:89], v[196:199], v[180:183], v[86:89]
	v_mfma_f32_16x16x32_bf16 v[82:85], v[204:207], v[180:183], v[82:85]
	v_mfma_f32_16x16x32_bf16 v[70:73], v[196:199], v[188:191], v[70:73]
	v_mfma_f32_16x16x32_bf16 v[66:69], v[204:207], v[188:191], v[66:69]
	v_mfma_f32_16x16x32_bf16 v[118:121], v[200:203], v[168:171], v[118:121]
	v_mfma_f32_16x16x32_bf16 v[114:117], v[210:213], v[168:171], v[114:117]
	v_mfma_f32_16x16x32_bf16 v[102:105], v[200:203], v[176:179], v[102:105]
	v_mfma_f32_16x16x32_bf16 v[98:101], v[210:213], v[176:179], v[98:101]
	v_mfma_f32_16x16x32_bf16 v[86:89], v[200:203], v[184:187], v[86:89]
	v_mfma_f32_16x16x32_bf16 v[82:85], v[210:213], v[184:187], v[82:85]
	v_mfma_f32_16x16x32_bf16 v[70:73], v[200:203], v[192:195], v[70:73]
	v_mfma_f32_16x16x32_bf16 v[66:69], v[210:213], v[192:195], v[66:69]
	s_setprio 0
	s_barrier
	s_add_i32 s38, s56, 0x10000
	v_lshl_add_u64 v[140:141], s[48:49], 0, v[0:1]
	s_mov_b32 m0, s38
	v_lshl_add_u64 v[214:215], s[48:49], 0, v[130:131]
	global_load_lds_dwordx4 v[140:141], off
	s_add_i32 m0, s38, 0x2000
	s_nop 0
	global_load_lds_dwordx4 v[214:215], off
	s_mov_b32 m0, s9
	v_lshl_add_u64 v[216:217], s[50:51], 0, v[134:135]
	global_load_lds_dwordx4 v[216:217], off
	v_lshl_add_u64 v[224:225], s[50:51], 0, v[132:133]
	s_mov_b32 m0, s60
	s_nop 0
	global_load_lds_dwordx4 v[224:225], off
	ds_read_b128 v[164:167], v145 offset:16384
	ds_read_b128 v[168:171], v145 offset:17408
	ds_read_b128 v[172:175], v145 offset:18432
	ds_read_b128 v[176:179], v145 offset:19456
	ds_read_b128 v[180:183], v145 offset:20480
	ds_read_b128 v[184:187], v145 offset:21504
	ds_read_b128 v[188:191], v145 offset:22528
	ds_read_b128 v[192:195], v145 offset:23552
	s_waitcnt vmcnt(4)
	s_barrier
	s_waitcnt lgkmcnt(0)
	s_setprio 1
	v_mfma_f32_16x16x32_bf16 v[62:65], v[146:149], v[164:167], v[62:65]
	v_mfma_f32_16x16x32_bf16 v[58:61], v[154:157], v[164:167], v[58:61]
	v_mfma_f32_16x16x32_bf16 v[46:49], v[146:149], v[172:175], v[46:49]
	v_mfma_f32_16x16x32_bf16 v[42:45], v[154:157], v[172:175], v[42:45]
	v_mfma_f32_16x16x32_bf16 v[30:33], v[146:149], v[180:183], v[30:33]
	v_mfma_f32_16x16x32_bf16 v[26:29], v[154:157], v[180:183], v[26:29]
	v_mfma_f32_16x16x32_bf16 v[14:17], v[146:149], v[188:191], v[14:17]
	v_mfma_f32_16x16x32_bf16 v[10:13], v[154:157], v[188:191], v[10:13]
	v_mfma_f32_16x16x32_bf16 v[62:65], v[150:153], v[168:171], v[62:65]
	v_mfma_f32_16x16x32_bf16 v[58:61], v[160:163], v[168:171], v[58:61]
	v_mfma_f32_16x16x32_bf16 v[46:49], v[150:153], v[176:179], v[46:49]
	v_mfma_f32_16x16x32_bf16 v[42:45], v[160:163], v[176:179], v[42:45]
	v_mfma_f32_16x16x32_bf16 v[30:33], v[150:153], v[184:187], v[30:33]
	v_mfma_f32_16x16x32_bf16 v[26:29], v[160:163], v[184:187], v[26:29]
	v_mfma_f32_16x16x32_bf16 v[14:17], v[150:153], v[192:195], v[14:17]
	v_mfma_f32_16x16x32_bf16 v[10:13], v[160:163], v[192:195], v[10:13]
	v_mfma_f32_16x16x32_bf16 v[54:57], v[196:199], v[164:167], v[54:57]
	v_mfma_f32_16x16x32_bf16 v[50:53], v[204:207], v[164:167], v[50:53]
	v_mfma_f32_16x16x32_bf16 v[38:41], v[196:199], v[172:175], v[38:41]
	v_mfma_f32_16x16x32_bf16 v[34:37], v[204:207], v[172:175], v[34:37]
	v_mfma_f32_16x16x32_bf16 v[22:25], v[196:199], v[180:183], v[22:25]
	v_mfma_f32_16x16x32_bf16 v[18:21], v[204:207], v[180:183], v[18:21]
	v_mfma_f32_16x16x32_bf16 v[6:9], v[196:199], v[188:191], v[6:9]
	v_mfma_f32_16x16x32_bf16 v[2:5], v[204:207], v[188:191], v[2:5]
	v_mfma_f32_16x16x32_bf16 v[54:57], v[200:203], v[168:171], v[54:57]
	v_mfma_f32_16x16x32_bf16 v[50:53], v[210:213], v[168:171], v[50:53]
	v_mfma_f32_16x16x32_bf16 v[38:41], v[200:203], v[176:179], v[38:41]
	v_mfma_f32_16x16x32_bf16 v[34:37], v[210:213], v[176:179], v[34:37]
	v_mfma_f32_16x16x32_bf16 v[22:25], v[200:203], v[184:187], v[22:25]
	v_mfma_f32_16x16x32_bf16 v[18:21], v[210:213], v[184:187], v[18:21]
	v_mfma_f32_16x16x32_bf16 v[6:9], v[200:203], v[192:195], v[6:9]
	v_mfma_f32_16x16x32_bf16 v[2:5], v[210:213], v[192:195], v[2:5]
	s_setprio 0
	s_barrier
; #define PG8_STAGE(bufoff, gbase, voff) do { _Pragma("unroll") for (int _i = 0; _i < 2; ++_i) \
;         __builtin_amdgcn_global_load_lds((const unsigned*)((const char*)(gbase) + (voff)[_i]), (LAS unsigned*)(lds + (bufoff) + ldsw + _i * 8192), 16, 0, 0); } while (0)
; #define PG8_LDA(dst, b, h) do { _Pragma("unroll") for (int m = 0; m < 4; ++m) _Pragma("unroll") for (int k = 0; k < 2; ++k) dst[m][k] = *(const LAS bf16x8*)(lds + PG8_SA(b, h) + aoff + m * 2048 + k * 1024); } while (0)
; #define PG8_LDB(dst, b, h) do { _Pragma("unroll") for (int n = 0; n < 2; ++n) _Pragma("unroll") for (int k = 0; k < 2; ++k) dst[n][k] = *(const LAS bf16x8*)(lds + PG8_SB(b, h) + boff + n * 2048 + k * 1024); } while (0)
; #define PG8_MMA(ai, bj, At, Bt) do { __builtin_amdgcn_s_setprio(1); _Pragma("unroll") for (int m = 0; m < 4; ++m) _Pragma("unroll") for (int n = 0; n < 2; ++n) _Pragma("unroll") for (int k = 0; k < 2; ++k) \
;         acc[ai][bj][m][n] = __builtin_amdgcn_mfma_f32_16x16x32_bf16(Bt[n][k], At[m][k], acc[ai][bj][m][n], 0, 0, 0); __builtin_amdgcn_s_setprio(0); } while (0)
; #define PG8_WAIT_V(n) asm volatile("s_waitcnt vmcnt(" #n ")" ::: "memory")
; #define PG8_WAIT_L(n) asm volatile("s_waitcnt lgkmcnt(" #n ")" ::: "memory")
; #define PG8_BAR __builtin_amdgcn_s_barrier()
; #define PG8_SCHED __builtin_amdgcn_sched_barrier(0)
; template <class Epi, class Sched>
; __device__ __forceinline__ void gemm_phase(LAS unsigned char* lds, const Gemm g, const Sched& S, const Epi& E) {
;     ...
;             PG8_STAGE(PG8_SB(0, 1), b2 + hstep, voffB);
;             PG8_WAIT_V(6); PG8_BAR; PG8_MMA(1, 1, At, B1); PG8_BAR;
;             PG8_LDB(B0, 1, 0); PG8_SCHED; PG8_LDA(At, 1, 0); PG8_STAGE(PG8_SA(0, 1), a2 + hstep, voffA);
;             PG8_WAIT_L(8); PG8_BAR; PG8_WAIT_L(0); PG8_MMA(0, 0, At, B0); PG8_BAR; PG8_SCHED;
;             PG8_LDB(B1, 1, 1); PG8_STAGE(PG8_SB(1, 0), b3, voffB);
;             PG8_BAR; PG8_WAIT_L(0); PG8_MMA(0, 1, At, B1); PG8_BAR;
;             PG8_LDA(At, 1, 1); PG8_STAGE(PG8_SA(1, 0), a3, voffA);
;             PG8_BAR; PG8_WAIT_L(0); PG8_MMA(1, 0, At, B0); PG8_BAR; PG8_SCHED;
;             PG8_STAGE(PG8_SB(1, 1), b3 + hstep, voffB);
	s_add_u32 s38, s48, 0x80000
	s_addc_u32 s39, s49, 0
	s_add_i32 s74, s56, 0x14000
	v_lshl_add_u64 v[146:147], s[38:39], 0, v[0:1]
	s_mov_b32 m0, s74
	s_nop 0
	global_load_lds_dwordx4 v[146:147], off
	v_lshl_add_u64 v[146:147], s[38:39], 0, v[130:131]
	s_add_i32 m0, s74, 0x2000
	s_nop 0
	global_load_lds_dwordx4 v[146:147], off
	v_add_u32_e32 v160, 0x18000, v143
	ds_read_b128 v[146:149], v160
	ds_read_b128 v[150:153], v160 offset:1024
	ds_read_b128 v[154:157], v160 offset:2048
	ds_read_b128 v[160:163], v160 offset:3072
	ds_read_b128 v[164:167], v145 offset:32768
	ds_read_b128 v[168:171], v145 offset:33792
	ds_read_b128 v[172:175], v145 offset:34816
	ds_read_b128 v[176:179], v145 offset:35840
	ds_read_b128 v[180:183], v145 offset:36864
	ds_read_b128 v[184:187], v145 offset:37888
	ds_read_b128 v[188:191], v145 offset:38912
	ds_read_b128 v[192:195], v145 offset:39936
	v_add_u32_e32 v210, 0x1c000, v143
	ds_read_b128 v[196:199], v210
	ds_read_b128 v[200:203], v210 offset:1024
	ds_read_b128 v[204:207], v210 offset:2048
	ds_read_b128 v[210:213], v210 offset:3072
	s_waitcnt lgkmcnt(4)
	s_barrier
	s_waitcnt lgkmcnt(0)
	s_setprio 1
	v_mfma_f32_16x16x32_bf16 v[126:129], v[146:149], v[164:167], v[126:129]
	v_mfma_f32_16x16x32_bf16 v[122:125], v[154:157], v[164:167], v[122:125]
	v_mfma_f32_16x16x32_bf16 v[110:113], v[146:149], v[172:175], v[110:113]
	v_mfma_f32_16x16x32_bf16 v[106:109], v[154:157], v[172:175], v[106:109]
	v_mfma_f32_16x16x32_bf16 v[94:97], v[146:149], v[180:183], v[94:97]
	v_mfma_f32_16x16x32_bf16 v[90:93], v[154:157], v[180:183], v[90:93]
	v_mfma_f32_16x16x32_bf16 v[78:81], v[146:149], v[188:191], v[78:81]
	v_mfma_f32_16x16x32_bf16 v[74:77], v[154:157], v[188:191], v[74:77]
	v_mfma_f32_16x16x32_bf16 v[126:129], v[150:153], v[168:171], v[126:129]
	v_mfma_f32_16x16x32_bf16 v[122:125], v[160:163], v[168:171], v[122:125]
	v_mfma_f32_16x16x32_bf16 v[110:113], v[150:153], v[176:179], v[110:113]
	v_mfma_f32_16x16x32_bf16 v[106:109], v[160:163], v[176:179], v[106:109]
	v_mfma_f32_16x16x32_bf16 v[94:97], v[150:153], v[184:187], v[94:97]
	v_mfma_f32_16x16x32_bf16 v[90:93], v[160:163], v[184:187], v[90:93]
	v_mfma_f32_16x16x32_bf16 v[78:81], v[150:153], v[192:195], v[78:81]
	v_mfma_f32_16x16x32_bf16 v[74:77], v[160:163], v[192:195], v[74:77]
	s_add_u32 s38, s50, 0x80000
	s_addc_u32 s39, s51, 0
	s_mov_b32 m0, s61
	v_lshl_add_u64 v[226:227], s[38:39], 0, v[134:135]
	global_load_lds_dwordx4 v[226:227], off
	v_lshl_add_u64 v[226:227], s[38:39], 0, v[132:133]
	s_mov_b32 m0, s62
	s_nop 0
	global_load_lds_dwordx4 v[226:227], off
	v_mfma_f32_16x16x32_bf16 v[118:121], v[196:199], v[164:167], v[118:121]
	v_mfma_f32_16x16x32_bf16 v[114:117], v[204:207], v[164:167], v[114:117]
	v_mfma_f32_16x16x32_bf16 v[102:105], v[196:199], v[172:175], v[102:105]
	v_mfma_f32_16x16x32_bf16 v[98:101], v[204:207], v[172:175], v[98:101]
	v_mfma_f32_16x16x32_bf16 v[86:89], v[196:199], v[180:183], v[86:89]
	v_mfma_f32_16x16x32_bf16 v[82:85], v[204:207], v[180:183], v[82:85]
	v_mfma_f32_16x16x32_bf16 v[70:73], v[196:199], v[188:191], v[70:73]
	v_mfma_f32_16x16x32_bf16 v[66:69], v[204:207], v[188:191], v[66:69]
	v_mfma_f32_16x16x32_bf16 v[118:121], v[200:203], v[168:171], v[118:121]
	v_mfma_f32_16x16x32_bf16 v[114:117], v[210:213], v[168:171], v[114:117]
	v_mfma_f32_16x16x32_bf16 v[102:105], v[200:203], v[176:179], v[102:105]
	v_mfma_f32_16x16x32_bf16 v[98:101], v[210:213], v[176:179], v[98:101]
	v_mfma_f32_16x16x32_bf16 v[86:89], v[200:203], v[184:187], v[86:89]
	v_mfma_f32_16x16x32_bf16 v[82:85], v[210:213], v[184:187], v[82:85]
	v_mfma_f32_16x16x32_bf16 v[70:73], v[200:203], v[192:195], v[70:73]
	v_mfma_f32_16x16x32_bf16 v[66:69], v[210:213], v[192:195], v[66:69]
	s_setprio 0
	s_barrier
	s_add_i32 s38, s56, 0x18000
	v_lshl_add_u64 v[140:141], v[140:141], 0, s[36:37]
	s_mov_b32 m0, s38
	s_nop 0
	global_load_lds_dwordx4 v[140:141], off
	v_lshl_add_u64 v[140:141], v[214:215], 0, s[36:37]
	s_add_i32 m0, s38, 0x2000
	s_nop 0
	global_load_lds_dwordx4 v[140:141], off
	s_mov_b32 m0, s64
	v_lshl_add_u64 v[140:141], v[216:217], 0, s[36:37]
	global_load_lds_dwordx4 v[140:141], off
	v_lshl_add_u64 v[140:141], v[224:225], 0, s[36:37]
	s_mov_b32 m0, s65
	s_nop 0
	global_load_lds_dwordx4 v[140:141], off
	ds_read_b128 v[164:167], v145 offset:49152
	ds_read_b128 v[168:171], v145 offset:50176
	ds_read_b128 v[172:175], v145 offset:51200
	ds_read_b128 v[176:179], v145 offset:52224
	ds_read_b128 v[180:183], v145 offset:53248
	ds_read_b128 v[184:187], v145 offset:54272
	ds_read_b128 v[188:191], v145 offset:55296
	ds_read_b128 v[192:195], v145 offset:56320
	s_waitcnt vmcnt(4)
	s_barrier
; __device__ __forceinline__ unsigned cvt_pk_bf16(float lo, float hi) { unsigned r; asm("v_cvt_pk_bf16_f32 %0, %1, %2" : "=v"(r) : "v"(lo), "v"(hi)); return r; }
; #define PG8_STAGE(bufoff, gbase, voff) do { _Pragma("unroll") for (int _i = 0; _i < 2; ++_i) \
;         __builtin_amdgcn_global_load_lds((const unsigned*)((const char*)(gbase) + (voff)[_i]), (LAS unsigned*)(lds + (bufoff) + ldsw + _i * 8192), 16, 0, 0); } while (0)
; #define PG8_MMA(ai, bj, At, Bt) do { __builtin_amdgcn_s_setprio(1); _Pragma("unroll") for (int m = 0; m < 4; ++m) _Pragma("unroll") for (int n = 0; n < 2; ++n) _Pragma("unroll") for (int k = 0; k < 2; ++k) \
;         acc[ai][bj][m][n] = __builtin_amdgcn_mfma_f32_16x16x32_bf16(Bt[n][k], At[m][k], acc[ai][bj][m][n], 0, 0, 0); __builtin_amdgcn_s_setprio(0); } while (0)
; #define PG8_WAIT_V(n) asm volatile("s_waitcnt vmcnt(" #n ")" ::: "memory")
; #define PG8_BAR __builtin_amdgcn_s_barrier()
;     __device__ __forceinline__ void operator()(const f32x4 (&acc)[2][2][4][2], const Unit& u, int wr, int wc, int fr, int fq) const {
;         const int row0 = u.pm * BM + wr * 64 + fr, col0 = u.pn * BM + wc * 32 + 8 * fq;
; #pragma unroll
;         for (int ai = 0; ai < 2; ++ai)
; #pragma unroll
;             for (int m = 0; m < 4; ++m) { bf16_t* rowp = O + (size_t)(row0 + ai * HALF + m * 16) * ldc + col0;
; #pragma unroll
;                 for (int bj = 0; bj < 2; ++bj) { f32x4 v0 = acc[ai][bj][m][0], v1 = acc[ai][bj][m][1];
;                     if (ACT == 1) {
; #pragma unroll
;                         for (int j = 0; j < 4; ++j) { float a = fmaxf(v0[j], 0.f), b = fmaxf(v1[j], 0.f); v0[j] = a * a; v1[j] = b * b; } }
;                     u32x4 w; w.x = cvt_pk_bf16(v0[0], v0[1]); w.y = cvt_pk_bf16(v0[2], v0[3]); w.z = cvt_pk_bf16(v1[0], v1[1]); w.w = cvt_pk_bf16(v1[2], v1[3]);
;                     if (ACT == 1) __builtin_nontemporal_store(w, (u32x4*)(rowp + bj * HALF));
;                     else *(u32x4*)(rowp + bj * HALF) = w; } }
; template <class Epi, class Sched>
; __device__ __forceinline__ void gemm_phase(LAS unsigned char* lds, const Gemm g, const Sched& S, const Epi& E) {
;     ...
;             PG8_STAGE(PG8_SB(1, 1), b3 + hstep, voffB);
;             PG8_WAIT_V(6); PG8_BAR; PG8_MMA(1, 1, At, B1); PG8_BAR;
;         }
;         E(acc, cur, wr, wc, fr, fq);
	s_waitcnt lgkmcnt(0)
	s_setprio 1
	v_mfma_f32_16x16x32_bf16 v[62:65], v[146:149], v[164:167], v[62:65]
	v_mfma_f32_16x16x32_bf16 v[58:61], v[154:157], v[164:167], v[58:61]
	v_mfma_f32_16x16x32_bf16 v[46:49], v[146:149], v[172:175], v[46:49]
	v_mfma_f32_16x16x32_bf16 v[42:45], v[154:157], v[172:175], v[42:45]
	v_mfma_f32_16x16x32_bf16 v[30:33], v[146:149], v[180:183], v[30:33]
	v_mfma_f32_16x16x32_bf16 v[26:29], v[154:157], v[180:183], v[26:29]
	v_mfma_f32_16x16x32_bf16 v[14:17], v[146:149], v[188:191], v[14:17]
	v_mfma_f32_16x16x32_bf16 v[10:13], v[154:157], v[188:191], v[10:13]
	v_mfma_f32_16x16x32_bf16 v[62:65], v[150:153], v[168:171], v[62:65]
	v_mfma_f32_16x16x32_bf16 v[58:61], v[160:163], v[168:171], v[58:61]
	v_mfma_f32_16x16x32_bf16 v[46:49], v[150:153], v[176:179], v[46:49]
	v_mfma_f32_16x16x32_bf16 v[42:45], v[160:163], v[176:179], v[42:45]
	v_mfma_f32_16x16x32_bf16 v[30:33], v[150:153], v[184:187], v[30:33]
	v_mfma_f32_16x16x32_bf16 v[26:29], v[160:163], v[184:187], v[26:29]
	v_mfma_f32_16x16x32_bf16 v[14:17], v[150:153], v[192:195], v[14:17]
	v_mfma_f32_16x16x32_bf16 v[10:13], v[160:163], v[192:195], v[10:13]
	s_add_u32 s38, s48, 0x80080
	s_addc_u32 s39, s49, 0
	s_add_i32 s48, s56, 0x1c000
	v_lshl_add_u64 v[140:141], s[38:39], 0, v[0:1]
	s_mov_b32 m0, s48
	s_nop 0
	global_load_lds_dwordx4 v[140:141], off
	v_lshl_add_u64 v[140:141], s[38:39], 0, v[130:131]
	s_add_i32 m0, s48, 0x2000
	s_nop 0
	global_load_lds_dwordx4 v[140:141], off
	v_mfma_f32_16x16x32_bf16 v[54:57], v[196:199], v[164:167], v[54:57]
	v_mfma_f32_16x16x32_bf16 v[50:53], v[204:207], v[164:167], v[50:53]
	v_mfma_f32_16x16x32_bf16 v[38:41], v[196:199], v[172:175], v[38:41]
	v_mfma_f32_16x16x32_bf16 v[34:37], v[204:207], v[172:175], v[34:37]
	v_mfma_f32_16x16x32_bf16 v[22:25], v[196:199], v[180:183], v[22:25]
	v_mfma_f32_16x16x32_bf16 v[18:21], v[204:207], v[180:183], v[18:21]
	v_mfma_f32_16x16x32_bf16 v[6:9], v[196:199], v[188:191], v[6:9]
	v_mfma_f32_16x16x32_bf16 v[2:5], v[204:207], v[188:191], v[2:5]
	v_mfma_f32_16x16x32_bf16 v[54:57], v[200:203], v[168:171], v[54:57]
	v_mfma_f32_16x16x32_bf16 v[50:53], v[210:213], v[168:171], v[50:53]
	v_mfma_f32_16x16x32_bf16 v[38:41], v[200:203], v[176:179], v[38:41]
	v_mfma_f32_16x16x32_bf16 v[34:37], v[210:213], v[176:179], v[34:37]
	v_mfma_f32_16x16x32_bf16 v[22:25], v[200:203], v[184:187], v[22:25]
	v_mfma_f32_16x16x32_bf16 v[18:21], v[210:213], v[184:187], v[18:21]
	v_mfma_f32_16x16x32_bf16 v[6:9], v[200:203], v[192:195], v[6:9]
	v_mfma_f32_16x16x32_bf16 v[2:5], v[210:213], v[192:195], v[2:5]
	s_setprio 0
	s_add_i32 s73, s73, 2
	s_add_u32 s71, s71, 0x100
	s_addc_u32 s72, s72, 0
	s_add_u32 s46, s46, 0x100
	s_addc_u32 s47, s47, 0
	s_cmp_gt_u32 s73, 29
	s_barrier
	s_cbranch_scc0 .LBB0_73
	v_lshl_add_u32 v146, s8, 8, v142
	v_max_f32_e32 v122, v122, v122
	v_ashrrev_i32_e32 v147, 31, v146
	v_max_f32_e32 v122, 0, v122
	v_max_f32_e32 v123, v123, v123
	v_max_f32_e32 v124, v124, v124
	v_lshl_or_b32 v140, s68, 8, v144
	v_lshlrev_b64 v[148:149], 14, v[146:147]
	v_mul_f32_e32 v147, v122, v122
	v_max_f32_e32 v122, v127, v127
	v_max_f32_e32 v123, 0, v123
	v_max_f32_e32 v124, 0, v124
	v_ashrrev_i32_e32 v141, 31, v140
	v_max_f32_e32 v126, v126, v126
	v_max_f32_e32 v122, 0, v122
	v_mul_f32_e32 v127, v123, v123
	v_max_f32_e32 v123, v128, v128
	v_mul_f32_e32 v128, v124, v124
	v_max_f32_e32 v124, v129, v129
	v_max_f32_e32 v125, v125, v125
	v_lshl_add_u64 v[148:149], s[24:25], 0, v[148:149]
	v_lshlrev_b64 v[150:151], 1, v[140:141]
	v_max_f32_e32 v126, 0, v126
	v_mul_f32_e32 v122, v122, v122
	v_max_f32_e32 v123, 0, v123
	v_max_f32_e32 v124, 0, v124
	v_max_f32_e32 v125, 0, v125
	v_max_f32_e32 v114, v114, v114
	v_lshl_add_u64 v[140:141], v[148:149], 0, v[150:151]
	v_mul_f32_e32 v126, v126, v126
	v_mul_f32_e32 v123, v123, v123
	v_mul_f32_e32 v124, v124, v124
	v_mul_f32_e32 v125, v125, v125
	v_cvt_pk_bf16_f32 v122, v126, v122
	v_max_f32_e32 v114, 0, v114
	v_max_f32_e32 v115, v115, v115
	v_max_f32_e32 v116, v116, v116
	v_cvt_pk_bf16_f32 v123, v123, v124
	v_cvt_pk_bf16_f32 v124, v147, v127
	v_cvt_pk_bf16_f32 v125, v128, v125
	global_store_dwordx4 v[140:141], v[122:125], off nt
	v_max_f32_e32 v115, 0, v115
	v_max_f32_e32 v116, 0, v116
	v_mul_f32_e32 v122, v114, v114
	v_max_f32_e32 v114, v119, v119
	v_max_f32_e32 v118, v118, v118
	v_max_f32_e32 v114, 0, v114
	v_mul_f32_e32 v119, v115, v115
	v_max_f32_e32 v115, v120, v120
	v_mul_f32_e32 v120, v116, v116
	v_max_f32_e32 v116, v121, v121
	v_max_f32_e32 v117, v117, v117
	v_max_f32_e32 v118, 0, v118
	v_mul_f32_e32 v114, v114, v114
	v_max_f32_e32 v115, 0, v115
	v_max_f32_e32 v116, 0, v116
	v_max_f32_e32 v117, 0, v117
	v_mul_f32_e32 v118, v118, v118
	v_mul_f32_e32 v115, v115, v115
	v_mul_f32_e32 v116, v116, v116
	v_mul_f32_e32 v117, v117, v117
	v_cvt_pk_bf16_f32 v114, v118, v114
	v_max_f32_e32 v106, v106, v106
	v_cvt_pk_bf16_f32 v115, v115, v116
	v_cvt_pk_bf16_f32 v116, v122, v119
	v_cvt_pk_bf16_f32 v117, v120, v117
	global_store_dwordx4 v[140:141], v[114:117], off offset:256 nt
	v_max_f32_e32 v106, 0, v106
	v_max_f32_e32 v107, v107, v107
	v_or_b32_e32 v114, 16, v146
	v_max_f32_e32 v108, v108, v108
	v_ashrrev_i32_e32 v115, 31, v114
	v_mul_f32_e32 v116, v106, v106
	v_max_f32_e32 v106, v111, v111
	v_max_f32_e32 v107, 0, v107
	v_max_f32_e32 v108, 0, v108
	v_lshlrev_b64 v[114:115], 14, v[114:115]
	v_max_f32_e32 v110, v110, v110
	v_max_f32_e32 v106, 0, v106
	v_mul_f32_e32 v111, v107, v107
	v_max_f32_e32 v107, v112, v112
	v_mul_f32_e32 v112, v108, v108
	v_max_f32_e32 v108, v113, v113
	v_max_f32_e32 v109, v109, v109
	v_lshl_add_u64 v[114:115], s[24:25], 0, v[114:115]
	v_max_f32_e32 v110, 0, v110
	v_mul_f32_e32 v106, v106, v106
; __device__ __forceinline__ unsigned cvt_pk_bf16(float lo, float hi) { unsigned r; asm("v_cvt_pk_bf16_f32 %0, %1, %2" : "=v"(r) : "v"(lo), "v"(hi)); return r; }
;     __device__ __forceinline__ void operator()(const f32x4 (&acc)[2][2][4][2], const Unit& u, int wr, int wc, int fr, int fq) const {
;         const int row0 = u.pm * BM + wr * 64 + fr, col0 = u.pn * BM + wc * 32 + 8 * fq;
; #pragma unroll
;         for (int ai = 0; ai < 2; ++ai)
; #pragma unroll
;             for (int m = 0; m < 4; ++m) { bf16_t* rowp = O + (size_t)(row0 + ai * HALF + m * 16) * ldc + col0;
; #pragma unroll
;                 for (int bj = 0; bj < 2; ++bj) { f32x4 v0 = acc[ai][bj][m][0], v1 = acc[ai][bj][m][1];
;                     if (ACT == 1) {
; #pragma unroll
;                         for (int j = 0; j < 4; ++j) { float a = fmaxf(v0[j], 0.f), b = fmaxf(v1[j], 0.f); v0[j] = a * a; v1[j] = b * b; } }
;                     u32x4 w; w.x = cvt_pk_bf16(v0[0], v0[1]); w.y = cvt_pk_bf16(v0[2], v0[3]); w.z = cvt_pk_bf16(v1[0], v1[1]); w.w = cvt_pk_bf16(v1[2], v1[3]);
;                     if (ACT == 1) __builtin_nontemporal_store(w, (u32x4*)(rowp + bj * HALF));
;                     else *(u32x4*)(rowp + bj * HALF) = w; } }
	v_max_f32_e32 v107, 0, v107
	v_max_f32_e32 v108, 0, v108
	v_max_f32_e32 v109, 0, v109
	v_max_f32_e32 v98, v98, v98
	v_lshl_add_u64 v[114:115], v[114:115], 0, v[150:151]
	v_mul_f32_e32 v110, v110, v110
	v_mul_f32_e32 v107, v107, v107
	v_mul_f32_e32 v108, v108, v108
	v_mul_f32_e32 v109, v109, v109
	v_cvt_pk_bf16_f32 v106, v110, v106
	v_max_f32_e32 v98, 0, v98
	v_max_f32_e32 v99, v99, v99
	v_max_f32_e32 v100, v100, v100
	v_cvt_pk_bf16_f32 v107, v107, v108
	v_cvt_pk_bf16_f32 v108, v116, v111
	v_cvt_pk_bf16_f32 v109, v112, v109
	global_store_dwordx4 v[114:115], v[106:109], off nt
	v_max_f32_e32 v99, 0, v99
	v_max_f32_e32 v100, 0, v100
	v_mul_f32_e32 v106, v98, v98
	v_max_f32_e32 v98, v103, v103
	v_max_f32_e32 v102, v102, v102
	v_max_f32_e32 v98, 0, v98
	v_mul_f32_e32 v103, v99, v99
	v_max_f32_e32 v99, v104, v104
	v_mul_f32_e32 v104, v100, v100
	v_max_f32_e32 v100, v105, v105
	v_max_f32_e32 v101, v101, v101
	v_max_f32_e32 v102, 0, v102
	v_mul_f32_e32 v98, v98, v98
	v_max_f32_e32 v99, 0, v99
	v_max_f32_e32 v100, 0, v100
	v_max_f32_e32 v101, 0, v101
	v_mul_f32_e32 v102, v102, v102
	v_mul_f32_e32 v99, v99, v99
	v_mul_f32_e32 v100, v100, v100
	v_mul_f32_e32 v101, v101, v101
	v_cvt_pk_bf16_f32 v98, v102, v98
	v_max_f32_e32 v90, v90, v90
	v_cvt_pk_bf16_f32 v99, v99, v100
	v_cvt_pk_bf16_f32 v100, v106, v103
	v_cvt_pk_bf16_f32 v101, v104, v101
	global_store_dwordx4 v[114:115], v[98:101], off offset:256 nt
	v_max_f32_e32 v90, 0, v90
	v_max_f32_e32 v91, v91, v91
	v_or_b32_e32 v98, 32, v146
	v_max_f32_e32 v92, v92, v92
	v_ashrrev_i32_e32 v99, 31, v98
	v_mul_f32_e32 v100, v90, v90
	v_max_f32_e32 v90, v95, v95
	v_max_f32_e32 v91, 0, v91
	v_max_f32_e32 v92, 0, v92
	v_lshlrev_b64 v[98:99], 14, v[98:99]
	v_max_f32_e32 v94, v94, v94
	v_max_f32_e32 v90, 0, v90
	v_mul_f32_e32 v95, v91, v91
	v_max_f32_e32 v91, v96, v96
	v_mul_f32_e32 v96, v92, v92
	v_max_f32_e32 v92, v97, v97
	v_max_f32_e32 v93, v93, v93
	v_lshl_add_u64 v[98:99], s[24:25], 0, v[98:99]
	v_max_f32_e32 v94, 0, v94
	v_mul_f32_e32 v90, v90, v90
	v_max_f32_e32 v91, 0, v91
	v_max_f32_e32 v92, 0, v92
	v_max_f32_e32 v93, 0, v93
	v_max_f32_e32 v82, v82, v82
	v_lshl_add_u64 v[98:99], v[98:99], 0, v[150:151]
	v_mul_f32_e32 v94, v94, v94
	v_mul_f32_e32 v91, v91, v91
	v_mul_f32_e32 v92, v92, v92
	v_mul_f32_e32 v93, v93, v93
	v_cvt_pk_bf16_f32 v90, v94, v90
	v_max_f32_e32 v82, 0, v82
	v_max_f32_e32 v83, v83, v83
	v_max_f32_e32 v84, v84, v84
	v_cvt_pk_bf16_f32 v91, v91, v92
	v_cvt_pk_bf16_f32 v92, v100, v95
	v_cvt_pk_bf16_f32 v93, v96, v93
	global_store_dwordx4 v[98:99], v[90:93], off nt
	v_max_f32_e32 v83, 0, v83
	v_max_f32_e32 v84, 0, v84
	v_mul_f32_e32 v90, v82, v82
	v_max_f32_e32 v82, v87, v87
	v_max_f32_e32 v86, v86, v86
	v_max_f32_e32 v82, 0, v82
	v_mul_f32_e32 v87, v83, v83
	v_max_f32_e32 v83, v88, v88
	v_mul_f32_e32 v88, v84, v84
	v_max_f32_e32 v84, v89, v89
	v_max_f32_e32 v85, v85, v85
	v_max_f32_e32 v86, 0, v86
	v_mul_f32_e32 v82, v82, v82
	v_max_f32_e32 v83, 0, v83
	v_max_f32_e32 v84, 0, v84
	v_max_f32_e32 v85, 0, v85
	v_mul_f32_e32 v86, v86, v86
	v_mul_f32_e32 v83, v83, v83
	v_mul_f32_e32 v84, v84, v84
	v_mul_f32_e32 v85, v85, v85
	v_cvt_pk_bf16_f32 v82, v86, v82
	v_max_f32_e32 v74, v74, v74
	v_cvt_pk_bf16_f32 v83, v83, v84
	v_cvt_pk_bf16_f32 v84, v90, v87
	v_cvt_pk_bf16_f32 v85, v88, v85
	global_store_dwordx4 v[98:99], v[82:85], off offset:256 nt
	v_max_f32_e32 v74, 0, v74
	v_max_f32_e32 v75, v75, v75
	v_or_b32_e32 v82, 48, v146
	v_max_f32_e32 v76, v76, v76
	v_ashrrev_i32_e32 v83, 31, v82
	v_mul_f32_e32 v84, v74, v74
	v_max_f32_e32 v74, v79, v79
	v_max_f32_e32 v75, 0, v75
	v_max_f32_e32 v76, 0, v76
	v_lshlrev_b64 v[82:83], 14, v[82:83]
	v_max_f32_e32 v78, v78, v78
	v_max_f32_e32 v74, 0, v74
	v_mul_f32_e32 v79, v75, v75
	v_max_f32_e32 v75, v80, v80
	v_mul_f32_e32 v80, v76, v76
	v_max_f32_e32 v76, v81, v81
	v_max_f32_e32 v77, v77, v77
	v_lshl_add_u64 v[82:83], s[24:25], 0, v[82:83]
	v_max_f32_e32 v78, 0, v78
	v_mul_f32_e32 v74, v74, v74
	v_max_f32_e32 v75, 0, v75
	v_max_f32_e32 v76, 0, v76
	v_max_f32_e32 v77, 0, v77
	v_max_f32_e32 v66, v66, v66
	v_max_f32_e32 v67, v67, v67
	v_max_f32_e32 v68, v68, v68
	v_lshl_add_u64 v[82:83], v[82:83], 0, v[150:151]
	v_mul_f32_e32 v78, v78, v78
	v_mul_f32_e32 v75, v75, v75
	v_mul_f32_e32 v76, v76, v76
	v_mul_f32_e32 v77, v77, v77
	v_cvt_pk_bf16_f32 v74, v78, v74
	v_max_f32_e32 v66, 0, v66
	v_max_f32_e32 v67, 0, v67
	v_max_f32_e32 v68, 0, v68
	v_cvt_pk_bf16_f32 v75, v75, v76
	v_cvt_pk_bf16_f32 v76, v84, v79
	v_cvt_pk_bf16_f32 v77, v80, v77
	global_store_dwordx4 v[82:83], v[74:77], off nt
	v_max_f32_e32 v69, v69, v69
	v_max_f32_e32 v70, v70, v70
	v_mul_f32_e32 v74, v66, v66
	v_max_f32_e32 v66, v71, v71
	v_mul_f32_e32 v71, v67, v67
	v_max_f32_e32 v67, v72, v72
	v_mul_f32_e32 v72, v68, v68
	v_max_f32_e32 v68, v73, v73
	v_max_f32_e32 v67, 0, v67
	v_max_f32_e32 v68, 0, v68
	v_max_f32_e32 v66, 0, v66
	v_mul_f32_e32 v67, v67, v67
	v_max_f32_e32 v69, 0, v69
	v_mul_f32_e32 v68, v68, v68
	v_max_f32_e32 v58, v58, v58
	v_max_f32_e32 v70, 0, v70
	v_mul_f32_e32 v66, v66, v66
	v_mul_f32_e32 v69, v69, v69
	v_cvt_pk_bf16_f32 v67, v67, v68
	v_cvt_pk_bf16_f32 v68, v74, v71
	v_max_f32_e32 v58, 0, v58
	v_max_f32_e32 v59, v59, v59
	v_max_f32_e32 v60, v60, v60
	v_mul_f32_e32 v70, v70, v70
	v_cvt_pk_bf16_f32 v66, v70, v66
	v_cvt_pk_bf16_f32 v69, v72, v69
	global_store_dwordx4 v[82:83], v[66:69], off offset:256 nt
	v_max_f32_e32 v62, v62, v62
	v_max_f32_e32 v59, 0, v59
	v_mul_f32_e32 v68, v58, v58
	v_max_f32_e32 v58, v63, v63
	v_max_f32_e32 v60, 0, v60
	v_max_f32_e32 v62, 0, v62
	v_max_f32_e32 v58, 0, v58
	v_mul_f32_e32 v63, v59, v59
	v_max_f32_e32 v59, v64, v64
	v_mul_f32_e32 v64, v60, v60
; __device__ __forceinline__ unsigned cvt_pk_bf16(float lo, float hi) { unsigned r; asm("v_cvt_pk_bf16_f32 %0, %1, %2" : "=v"(r) : "v"(lo), "v"(hi)); return r; }
;     __device__ __forceinline__ void operator()(const f32x4 (&acc)[2][2][4][2], const Unit& u, int wr, int wc, int fr, int fq) const {
;         const int row0 = u.pm * BM + wr * 64 + fr, col0 = u.pn * BM + wc * 32 + 8 * fq;
; #pragma unroll
;         for (int ai = 0; ai < 2; ++ai)
; #pragma unroll
;             for (int m = 0; m < 4; ++m) { bf16_t* rowp = O + (size_t)(row0 + ai * HALF + m * 16) * ldc + col0;
; #pragma unroll
;                 for (int bj = 0; bj < 2; ++bj) { f32x4 v0 = acc[ai][bj][m][0], v1 = acc[ai][bj][m][1];
;                     if (ACT == 1) {
; #pragma unroll
;                         for (int j = 0; j < 4; ++j) { float a = fmaxf(v0[j], 0.f), b = fmaxf(v1[j], 0.f); v0[j] = a * a; v1[j] = b * b; } }
;                     u32x4 w; w.x = cvt_pk_bf16(v0[0], v0[1]); w.y = cvt_pk_bf16(v0[2], v0[3]); w.z = cvt_pk_bf16(v1[0], v1[1]); w.w = cvt_pk_bf16(v1[2], v1[3]);
;                     if (ACT == 1) __builtin_nontemporal_store(w, (u32x4*)(rowp + bj * HALF));
;                     else *(u32x4*)(rowp + bj * HALF) = w; } }
	v_max_f32_e32 v60, v65, v65
	v_mul_f32_e32 v62, v62, v62
	v_mul_f32_e32 v58, v58, v58
	v_max_f32_e32 v59, 0, v59
	v_max_f32_e32 v60, 0, v60
	v_max_f32_e32 v61, v61, v61
	s_mov_b32 s8, 0x200000
	v_mul_f32_e32 v59, v59, v59
	v_max_f32_e32 v61, 0, v61
	v_mul_f32_e32 v60, v60, v60
	v_cvt_pk_bf16_f32 v58, v62, v58
	v_add_co_u32_e32 v62, vcc, s8, v140
	v_max_f32_e32 v50, v50, v50
	v_max_f32_e32 v51, v51, v51
	v_max_f32_e32 v52, v52, v52
	v_mul_f32_e32 v61, v61, v61
	v_cvt_pk_bf16_f32 v59, v59, v60
	v_cvt_pk_bf16_f32 v60, v68, v63
	v_addc_co_u32_e32 v63, vcc, 0, v141, vcc
	v_max_f32_e32 v50, 0, v50
	v_max_f32_e32 v51, 0, v51
	v_max_f32_e32 v52, 0, v52
	v_cvt_pk_bf16_f32 v61, v64, v61
	global_store_dwordx4 v[62:63], v[58:61], off nt
	v_max_f32_e32 v53, v53, v53
	s_mov_b64 s[38:39], 0x200000
	v_mul_f32_e32 v58, v50, v50
	v_max_f32_e32 v50, v55, v55
	v_mul_f32_e32 v55, v51, v51
	v_max_f32_e32 v51, v56, v56
	v_mul_f32_e32 v56, v52, v52
	v_max_f32_e32 v52, v57, v57
	v_max_f32_e32 v51, 0, v51
	v_max_f32_e32 v52, 0, v52
	v_max_f32_e32 v54, v54, v54
	v_max_f32_e32 v50, 0, v50
	v_mul_f32_e32 v51, v51, v51
	v_max_f32_e32 v53, 0, v53
	v_mul_f32_e32 v52, v52, v52
	v_max_f32_e32 v42, v42, v42
	v_lshl_add_u64 v[66:67], v[140:141], 0, s[38:39]
	v_max_f32_e32 v54, 0, v54
	v_mul_f32_e32 v50, v50, v50
	v_mul_f32_e32 v53, v53, v53
	v_cvt_pk_bf16_f32 v51, v51, v52
	v_cvt_pk_bf16_f32 v52, v58, v55
	v_max_f32_e32 v42, 0, v42
	v_max_f32_e32 v43, v43, v43
	v_max_f32_e32 v44, v44, v44
	v_mul_f32_e32 v54, v54, v54
	v_cvt_pk_bf16_f32 v50, v54, v50
	v_cvt_pk_bf16_f32 v53, v56, v53
	global_store_dwordx4 v[66:67], v[50:53], off offset:256 nt
	v_max_f32_e32 v46, v46, v46
	v_max_f32_e32 v43, 0, v43
	v_mul_f32_e32 v52, v42, v42
	v_max_f32_e32 v42, v47, v47
	v_max_f32_e32 v44, 0, v44
	v_max_f32_e32 v46, 0, v46
	v_max_f32_e32 v42, 0, v42
	v_mul_f32_e32 v47, v43, v43
	v_max_f32_e32 v43, v48, v48
	v_mul_f32_e32 v48, v44, v44
	v_max_f32_e32 v44, v49, v49
	v_mul_f32_e32 v46, v46, v46
	v_mul_f32_e32 v42, v42, v42
	v_max_f32_e32 v43, 0, v43
	v_max_f32_e32 v44, 0, v44
	v_max_f32_e32 v45, v45, v45
	s_mov_b32 s8, 0x240000
	v_mul_f32_e32 v43, v43, v43
	v_max_f32_e32 v45, 0, v45
	v_mul_f32_e32 v44, v44, v44
	v_cvt_pk_bf16_f32 v42, v46, v42
	v_add_co_u32_e32 v46, vcc, s8, v140
	v_max_f32_e32 v34, v34, v34
	v_max_f32_e32 v35, v35, v35
	v_max_f32_e32 v36, v36, v36
	v_mul_f32_e32 v45, v45, v45
	v_cvt_pk_bf16_f32 v43, v43, v44
	v_cvt_pk_bf16_f32 v44, v52, v47
	v_addc_co_u32_e32 v47, vcc, 0, v141, vcc
	v_max_f32_e32 v34, 0, v34
	v_max_f32_e32 v35, 0, v35
	v_max_f32_e32 v36, 0, v36
	v_cvt_pk_bf16_f32 v45, v48, v45
	global_store_dwordx4 v[46:47], v[42:45], off nt
	v_max_f32_e32 v37, v37, v37
	s_mov_b64 s[38:39], 0x240000
	v_mul_f32_e32 v42, v34, v34
	v_max_f32_e32 v34, v39, v39
	v_mul_f32_e32 v39, v35, v35
	v_max_f32_e32 v35, v40, v40
	v_mul_f32_e32 v40, v36, v36
	v_max_f32_e32 v36, v41, v41
	v_max_f32_e32 v35, 0, v35
	v_max_f32_e32 v36, 0, v36
	v_max_f32_e32 v38, v38, v38
	v_max_f32_e32 v34, 0, v34
	v_mul_f32_e32 v35, v35, v35
	v_max_f32_e32 v37, 0, v37
	v_mul_f32_e32 v36, v36, v36
	v_max_f32_e32 v26, v26, v26
	v_lshl_add_u64 v[50:51], v[140:141], 0, s[38:39]
	v_max_f32_e32 v38, 0, v38
	v_mul_f32_e32 v34, v34, v34
	v_mul_f32_e32 v37, v37, v37
	v_cvt_pk_bf16_f32 v35, v35, v36
	v_cvt_pk_bf16_f32 v36, v42, v39
	v_max_f32_e32 v26, 0, v26
	v_max_f32_e32 v27, v27, v27
	v_max_f32_e32 v28, v28, v28
	v_mul_f32_e32 v38, v38, v38
	v_cvt_pk_bf16_f32 v34, v38, v34
	v_cvt_pk_bf16_f32 v37, v40, v37
	global_store_dwordx4 v[50:51], v[34:37], off offset:256 nt
	v_max_f32_e32 v30, v30, v30
	v_max_f32_e32 v27, 0, v27
	v_mul_f32_e32 v36, v26, v26
	v_max_f32_e32 v26, v31, v31
	v_max_f32_e32 v28, 0, v28
	v_max_f32_e32 v30, 0, v30
; __device__ __forceinline__ unsigned cvt_pk_bf16(float lo, float hi) { unsigned r; asm("v_cvt_pk_bf16_f32 %0, %1, %2" : "=v"(r) : "v"(lo), "v"(hi)); return r; }
;     __device__ __forceinline__ void operator()(const f32x4 (&acc)[2][2][4][2], const Unit& u, int wr, int wc, int fr, int fq) const {
;         const int row0 = u.pm * BM + wr * 64 + fr, col0 = u.pn * BM + wc * 32 + 8 * fq;
; #pragma unroll
;         for (int ai = 0; ai < 2; ++ai)
; #pragma unroll
;             for (int m = 0; m < 4; ++m) { bf16_t* rowp = O + (size_t)(row0 + ai * HALF + m * 16) * ldc + col0;
; #pragma unroll
;                 for (int bj = 0; bj < 2; ++bj) { f32x4 v0 = acc[ai][bj][m][0], v1 = acc[ai][bj][m][1];
;                     if (ACT == 1) {
; #pragma unroll
;                         for (int j = 0; j < 4; ++j) { float a = fmaxf(v0[j], 0.f), b = fmaxf(v1[j], 0.f); v0[j] = a * a; v1[j] = b * b; } }
;                     u32x4 w; w.x = cvt_pk_bf16(v0[0], v0[1]); w.y = cvt_pk_bf16(v0[2], v0[3]); w.z = cvt_pk_bf16(v1[0], v1[1]); w.w = cvt_pk_bf16(v1[2], v1[3]);
;                     if (ACT == 1) __builtin_nontemporal_store(w, (u32x4*)(rowp + bj * HALF));
;                     else *(u32x4*)(rowp + bj * HALF) = w; } }
; template <class Epi, class Sched>
; __device__ __forceinline__ void gemm_phase(LAS unsigned char* lds, const Gemm g, const Sched& S, const Epi& E) {
;     ...
;         E(acc, cur, wr, wc, fr, fq);
;         if (!has_next) break;
; #pragma unroll
;         for (int a = 0; a < 2; ++a)
; #pragma unroll
;             for (int b = 0; b < 2; ++b)
; #pragma unroll
;                 for (int m = 0; m < 4; ++m)
; #pragma unroll
;                     for (int n = 0; n < 2; ++n) acc[a][b][m][n] = (f32x4){0.f, 0.f, 0.f, 0.f};
;         cur = nxt; cA = nA; cB = nB; ++ui;
;     }
	v_max_f32_e32 v26, 0, v26
	v_mul_f32_e32 v31, v27, v27
	v_max_f32_e32 v27, v32, v32
	v_mul_f32_e32 v32, v28, v28
	v_max_f32_e32 v28, v33, v33
	v_mul_f32_e32 v30, v30, v30
	v_mul_f32_e32 v26, v26, v26
	v_max_f32_e32 v27, 0, v27
	v_max_f32_e32 v28, 0, v28
	v_max_f32_e32 v29, v29, v29
	s_mov_b32 s8, 0x280000
	v_mul_f32_e32 v27, v27, v27
	v_max_f32_e32 v29, 0, v29
	v_mul_f32_e32 v28, v28, v28
	v_cvt_pk_bf16_f32 v26, v30, v26
	v_add_co_u32_e32 v30, vcc, s8, v140
	v_max_f32_e32 v18, v18, v18
	v_max_f32_e32 v19, v19, v19
	v_max_f32_e32 v20, v20, v20
	v_mul_f32_e32 v29, v29, v29
	v_cvt_pk_bf16_f32 v27, v27, v28
	v_cvt_pk_bf16_f32 v28, v36, v31
	v_addc_co_u32_e32 v31, vcc, 0, v141, vcc
	v_max_f32_e32 v18, 0, v18
	v_max_f32_e32 v19, 0, v19
	v_max_f32_e32 v20, 0, v20
	v_cvt_pk_bf16_f32 v29, v32, v29
	global_store_dwordx4 v[30:31], v[26:29], off nt
	v_max_f32_e32 v21, v21, v21
	s_mov_b64 s[38:39], 0x280000
	v_mul_f32_e32 v26, v18, v18
	v_max_f32_e32 v18, v23, v23
	v_mul_f32_e32 v23, v19, v19
	v_max_f32_e32 v19, v24, v24
	v_mul_f32_e32 v24, v20, v20
	v_max_f32_e32 v20, v25, v25
	v_max_f32_e32 v19, 0, v19
	v_max_f32_e32 v20, 0, v20
	v_max_f32_e32 v22, v22, v22
	v_max_f32_e32 v18, 0, v18
	v_mul_f32_e32 v19, v19, v19
	v_max_f32_e32 v21, 0, v21
	v_mul_f32_e32 v20, v20, v20
	v_max_f32_e32 v10, v10, v10
	v_lshl_add_u64 v[34:35], v[140:141], 0, s[38:39]
	v_max_f32_e32 v22, 0, v22
	v_mul_f32_e32 v18, v18, v18
	v_mul_f32_e32 v21, v21, v21
	v_cvt_pk_bf16_f32 v19, v19, v20
	v_cvt_pk_bf16_f32 v20, v26, v23
	v_max_f32_e32 v10, 0, v10
	v_max_f32_e32 v11, v11, v11
	v_max_f32_e32 v12, v12, v12
	v_mul_f32_e32 v22, v22, v22
	v_cvt_pk_bf16_f32 v18, v22, v18
	v_cvt_pk_bf16_f32 v21, v24, v21
	global_store_dwordx4 v[34:35], v[18:21], off offset:256 nt
	v_max_f32_e32 v14, v14, v14
	v_max_f32_e32 v11, 0, v11
	v_mul_f32_e32 v20, v10, v10
	v_max_f32_e32 v10, v15, v15
	v_max_f32_e32 v12, 0, v12
	v_max_f32_e32 v14, 0, v14
	v_max_f32_e32 v10, 0, v10
	v_mul_f32_e32 v15, v11, v11
	v_max_f32_e32 v11, v16, v16
	v_mul_f32_e32 v16, v12, v12
	v_max_f32_e32 v12, v17, v17
	v_mul_f32_e32 v14, v14, v14
	v_mul_f32_e32 v10, v10, v10
	v_max_f32_e32 v11, 0, v11
	v_max_f32_e32 v12, 0, v12
	v_max_f32_e32 v13, v13, v13
	s_mov_b32 s8, 0x2c0000
	v_mul_f32_e32 v11, v11, v11
	v_max_f32_e32 v13, 0, v13
	v_mul_f32_e32 v12, v12, v12
	v_cvt_pk_bf16_f32 v10, v14, v10
	v_add_co_u32_e32 v14, vcc, s8, v140
	v_max_f32_e32 v2, v2, v2
	v_max_f32_e32 v3, v3, v3
	v_max_f32_e32 v4, v4, v4
	v_mul_f32_e32 v13, v13, v13
	v_cvt_pk_bf16_f32 v11, v11, v12
	v_cvt_pk_bf16_f32 v12, v20, v15
	v_addc_co_u32_e32 v15, vcc, 0, v141, vcc
	v_max_f32_e32 v2, 0, v2
	v_max_f32_e32 v3, 0, v3
	v_max_f32_e32 v4, 0, v4
	v_cvt_pk_bf16_f32 v13, v16, v13
	global_store_dwordx4 v[14:15], v[10:13], off nt
	v_max_f32_e32 v5, v5, v5
	s_mov_b64 s[38:39], 0x2c0000
	v_mul_f32_e32 v10, v2, v2
	v_max_f32_e32 v2, v7, v7
	v_mul_f32_e32 v7, v3, v3
	v_max_f32_e32 v3, v8, v8
	v_mul_f32_e32 v8, v4, v4
	v_max_f32_e32 v4, v9, v9
	v_max_f32_e32 v6, v6, v6
	v_max_f32_e32 v2, 0, v2
	v_max_f32_e32 v3, 0, v3
	v_max_f32_e32 v4, 0, v4
	v_max_f32_e32 v5, 0, v5
	v_lshl_add_u64 v[18:19], v[140:141], 0, s[38:39]
	v_max_f32_e32 v6, 0, v6
	v_mul_f32_e32 v2, v2, v2
	v_mul_f32_e32 v3, v3, v3
	v_mul_f32_e32 v4, v4, v4
	v_mul_f32_e32 v5, v5, v5
	s_and_b64 vcc, exec, s[40:41]
	s_mov_b32 s68, s26
	s_mov_b32 s8, s28
	s_mov_b64 s[46:47], s[44:45]
	s_mov_b64 s[48:49], s[42:43]
	v_mul_f32_e32 v6, v6, v6
	v_cvt_pk_bf16_f32 v2, v6, v2
	v_cvt_pk_bf16_f32 v3, v3, v4
	v_cvt_pk_bf16_f32 v4, v10, v7
	v_cvt_pk_bf16_f32 v5, v8, v5
	global_store_dwordx4 v[18:19], v[2:5], off offset:256 nt
	s_cbranch_vccz .LBB0_70
	s_waitcnt vmcnt(0)
	s_cmpk_gt_u32 s52, 0xff
	s_cbranch_scc1 .LBB0_77
	s_barrier

; #define PG8_STAGE(bufoff, gbase, voff) do { _Pragma("unroll") for (int _i = 0; _i < 2; ++_i) \
;         __builtin_amdgcn_global_load_lds((const unsigned*)((const char*)(gbase) + (voff)[_i]), (LAS unsigned*)(lds + (bufoff) + ldsw + _i * 8192), 16, 0, 0); } while (0)
; #define PG8_LDA(dst, b, h) do { _Pragma("unroll") for (int m = 0; m < 4; ++m) _Pragma("unroll") for (int k = 0; k < 2; ++k) dst[m][k] = *(const LAS bf16x8*)(lds + PG8_SA(b, h) + aoff + m * 2048 + k * 1024); } while (0)
; #define PG8_LDB(dst, b, h) do { _Pragma("unroll") for (int n = 0; n < 2; ++n) _Pragma("unroll") for (int k = 0; k < 2; ++k) dst[n][k] = *(const LAS bf16x8*)(lds + PG8_SB(b, h) + boff + n * 2048 + k * 1024); } while (0)
; #define PG8_MMA(ai, bj, At, Bt) do { __builtin_amdgcn_s_setprio(1); _Pragma("unroll") for (int m = 0; m < 4; ++m) _Pragma("unroll") for (int n = 0; n < 2; ++n) _Pragma("unroll") for (int k = 0; k < 2; ++k) \
;         acc[ai][bj][m][n] = __builtin_amdgcn_mfma_f32_16x16x32_bf16(Bt[n][k], At[m][k], acc[ai][bj][m][n], 0, 0, 0); __builtin_amdgcn_s_setprio(0); } while (0)
; #define PG8_WAIT_V(n) asm volatile("s_waitcnt vmcnt(" #n ")" ::: "memory")
; #define PG8_WAIT_L(n) asm volatile("s_waitcnt lgkmcnt(" #n ")" ::: "memory")
; #define PG8_BAR __builtin_amdgcn_s_barrier()
; #define PG8_SCHED __builtin_amdgcn_sched_barrier(0)
; template <class Epi, class Sched>
; __device__ __forceinline__ void gemm_phase(LAS unsigned char* lds, const Gemm g, const Sched& S, const Epi& E) {
;     ...
;             PG8_LDB(B0, 0, 0); PG8_SCHED; PG8_LDA(At, 0, 0); PG8_STAGE(PG8_SA(1, 1), a1 + hstep, voffA);
;             PG8_WAIT_L(8); PG8_BAR; PG8_WAIT_L(0); PG8_MMA(0, 0, At, B0); PG8_BAR; PG8_SCHED;
;             PG8_LDB(B1, 0, 1); PG8_STAGE(PG8_SB(0, 0), b2, voffB);
;             PG8_BAR; PG8_WAIT_L(0); PG8_MMA(0, 1, At, B1); PG8_BAR;
;             PG8_LDA(At, 0, 1); PG8_STAGE(PG8_SA(0, 0), a2, voffA);
;             PG8_BAR; PG8_WAIT_L(0); PG8_MMA(1, 0, At, B0); PG8_BAR; PG8_SCHED;
;             PG8_STAGE(PG8_SB(0, 1), b2 + hstep, voffB);
;             PG8_WAIT_V(6); PG8_BAR; PG8_MMA(1, 1, At, B1); PG8_BAR;
.LBB0_99:
	v_add_u32_e32 v110, 0x10000, v169
	ds_read_b128 v[98:101], v110
	ds_read_b128 v[102:105], v110 offset:1024
	ds_read_b128 v[106:109], v110 offset:2048
	ds_read_b128 v[110:113], v110 offset:3072
	ds_read_b128 v[152:155], v171
	ds_read_b128 v[160:163], v171 offset:1024
	ds_read_b128 v[164:167], v171 offset:2048
	ds_read_b128 v[172:175], v171 offset:3072
	ds_read_b128 v[176:179], v171 offset:4096
	ds_read_b128 v[180:183], v171 offset:5120
	ds_read_b128 v[184:187], v171 offset:6144
	ds_read_b128 v[188:191], v171 offset:7168
	v_add_u32_e32 v156, 0x14000, v169
	ds_read_b128 v[192:195], v156
	ds_read_b128 v[196:199], v156 offset:1024
	ds_read_b128 v[200:203], v156 offset:2048
	ds_read_b128 v[204:207], v156 offset:3072
	s_waitcnt lgkmcnt(4)
	s_barrier
	s_waitcnt lgkmcnt(0)
	s_setprio 1
	v_mfma_f32_16x16x32_bf16 v[142:145], v[98:101], v[152:155], v[142:145]
	v_mfma_f32_16x16x32_bf16 v[138:141], v[106:109], v[152:155], v[138:141]
	v_mfma_f32_16x16x32_bf16 v[126:129], v[98:101], v[164:167], v[126:129]
	v_mfma_f32_16x16x32_bf16 v[122:125], v[106:109], v[164:167], v[122:125]
	v_mfma_f32_16x16x32_bf16 v[94:97], v[98:101], v[176:179], v[94:97]
	v_mfma_f32_16x16x32_bf16 v[90:93], v[106:109], v[176:179], v[90:93]
	v_mfma_f32_16x16x32_bf16 v[86:89], v[98:101], v[184:187], v[86:89]
	v_mfma_f32_16x16x32_bf16 v[82:85], v[106:109], v[184:187], v[82:85]
	v_mfma_f32_16x16x32_bf16 v[142:145], v[102:105], v[160:163], v[142:145]
	v_mfma_f32_16x16x32_bf16 v[138:141], v[110:113], v[160:163], v[138:141]
	v_mfma_f32_16x16x32_bf16 v[126:129], v[102:105], v[172:175], v[126:129]
	v_mfma_f32_16x16x32_bf16 v[122:125], v[110:113], v[172:175], v[122:125]
	v_mfma_f32_16x16x32_bf16 v[94:97], v[102:105], v[180:183], v[94:97]
	v_mfma_f32_16x16x32_bf16 v[90:93], v[110:113], v[180:183], v[90:93]
	v_mfma_f32_16x16x32_bf16 v[86:89], v[102:105], v[188:191], v[86:89]
	v_mfma_f32_16x16x32_bf16 v[82:85], v[110:113], v[188:191], v[82:85]
	s_add_u32 s56, s28, 0x100
	s_addc_u32 s57, s29, 0
	s_cmp_eq_u32 s81, 28
	s_cselect_b32 s61, s51, s57
	s_cselect_b32 s60, s77, s56
	s_cselect_b32 s59, s49, s80
	s_cselect_b32 s58, s78, s79
	v_lshl_add_u64 v[228:229], s[28:29], 0, v[150:151]
	s_add_i32 m0, s9, 0xc000
	s_nop 0
	global_load_lds_dwordx4 v[228:229], off
	v_lshl_add_u64 v[228:229], s[28:29], 0, v[148:149]
	s_add_i32 m0, s9, 0xe000
	s_nop 0
	global_load_lds_dwordx4 v[228:229], off
	v_mfma_f32_16x16x32_bf16 v[134:137], v[192:195], v[152:155], v[134:137]
	v_mfma_f32_16x16x32_bf16 v[130:133], v[200:203], v[152:155], v[130:133]
	v_mfma_f32_16x16x32_bf16 v[118:121], v[192:195], v[164:167], v[118:121]
	v_mfma_f32_16x16x32_bf16 v[114:117], v[200:203], v[164:167], v[114:117]
	v_mfma_f32_16x16x32_bf16 v[78:81], v[192:195], v[176:179], v[78:81]
	v_mfma_f32_16x16x32_bf16 v[74:77], v[200:203], v[176:179], v[74:77]
	v_mfma_f32_16x16x32_bf16 v[70:73], v[192:195], v[184:187], v[70:73]
	v_mfma_f32_16x16x32_bf16 v[66:69], v[200:203], v[184:187], v[66:69]
	v_mfma_f32_16x16x32_bf16 v[134:137], v[196:199], v[160:163], v[134:137]
	v_mfma_f32_16x16x32_bf16 v[130:133], v[204:207], v[160:163], v[130:133]
	v_mfma_f32_16x16x32_bf16 v[118:121], v[196:199], v[172:175], v[118:121]
	v_mfma_f32_16x16x32_bf16 v[114:117], v[204:207], v[172:175], v[114:117]
	v_mfma_f32_16x16x32_bf16 v[78:81], v[196:199], v[180:183], v[78:81]
	v_mfma_f32_16x16x32_bf16 v[74:77], v[204:207], v[180:183], v[74:77]
	v_mfma_f32_16x16x32_bf16 v[70:73], v[196:199], v[188:191], v[70:73]
	v_mfma_f32_16x16x32_bf16 v[66:69], v[204:207], v[188:191], v[66:69]
	s_setprio 0
	s_barrier
	s_add_i32 s28, s67, 0x10000
	v_lshl_add_u64 v[156:157], s[58:59], 0, v[0:1]
	s_mov_b32 m0, s28
	v_lshl_add_u64 v[210:211], s[58:59], 0, v[146:147]
	global_load_lds_dwordx4 v[156:157], off
	s_add_i32 m0, s28, 0x2000
	s_nop 0
	global_load_lds_dwordx4 v[210:211], off
	s_mov_b32 m0, s9
	v_lshl_add_u64 v[212:213], s[60:61], 0, v[0:1]
	global_load_lds_dwordx4 v[212:213], off
	v_lshl_add_u64 v[214:215], s[60:61], 0, v[146:147]
	s_mov_b32 m0, s68
	s_nop 0
	global_load_lds_dwordx4 v[214:215], off
	ds_read_b128 v[152:155], v171 offset:16384
	ds_read_b128 v[160:163], v171 offset:17408
	ds_read_b128 v[164:167], v171 offset:18432
	ds_read_b128 v[172:175], v171 offset:19456
	ds_read_b128 v[176:179], v171 offset:20480
	ds_read_b128 v[180:183], v171 offset:21504
	ds_read_b128 v[184:187], v171 offset:22528
	ds_read_b128 v[188:191], v171 offset:23552
	s_waitcnt vmcnt(4)
	s_barrier
	s_waitcnt lgkmcnt(0)
	s_setprio 1
	v_mfma_f32_16x16x32_bf16 v[62:65], v[98:101], v[152:155], v[62:65]
	v_mfma_f32_16x16x32_bf16 v[58:61], v[106:109], v[152:155], v[58:61]
	v_mfma_f32_16x16x32_bf16 v[46:49], v[98:101], v[164:167], v[46:49]
	v_mfma_f32_16x16x32_bf16 v[42:45], v[106:109], v[164:167], v[42:45]
	v_mfma_f32_16x16x32_bf16 v[30:33], v[98:101], v[176:179], v[30:33]
	v_mfma_f32_16x16x32_bf16 v[26:29], v[106:109], v[176:179], v[26:29]
	v_mfma_f32_16x16x32_bf16 v[22:25], v[98:101], v[184:187], v[22:25]
	v_mfma_f32_16x16x32_bf16 v[18:21], v[106:109], v[184:187], v[18:21]
	v_mfma_f32_16x16x32_bf16 v[62:65], v[102:105], v[160:163], v[62:65]
	v_mfma_f32_16x16x32_bf16 v[58:61], v[110:113], v[160:163], v[58:61]
	v_mfma_f32_16x16x32_bf16 v[46:49], v[102:105], v[172:175], v[46:49]
	v_mfma_f32_16x16x32_bf16 v[42:45], v[110:113], v[172:175], v[42:45]
	v_mfma_f32_16x16x32_bf16 v[30:33], v[102:105], v[180:183], v[30:33]
	v_mfma_f32_16x16x32_bf16 v[26:29], v[110:113], v[180:183], v[26:29]
	v_mfma_f32_16x16x32_bf16 v[22:25], v[102:105], v[188:191], v[22:25]
	v_mfma_f32_16x16x32_bf16 v[18:21], v[110:113], v[188:191], v[18:21]
	v_mfma_f32_16x16x32_bf16 v[54:57], v[192:195], v[152:155], v[54:57]
	v_mfma_f32_16x16x32_bf16 v[50:53], v[200:203], v[152:155], v[50:53]
	v_mfma_f32_16x16x32_bf16 v[38:41], v[192:195], v[164:167], v[38:41]
	v_mfma_f32_16x16x32_bf16 v[34:37], v[200:203], v[164:167], v[34:37]
	v_mfma_f32_16x16x32_bf16 v[14:17], v[192:195], v[176:179], v[14:17]
	v_mfma_f32_16x16x32_bf16 v[10:13], v[200:203], v[176:179], v[10:13]
	v_mfma_f32_16x16x32_bf16 v[6:9], v[192:195], v[184:187], v[6:9]
	v_mfma_f32_16x16x32_bf16 v[2:5], v[200:203], v[184:187], v[2:5]
	v_mfma_f32_16x16x32_bf16 v[54:57], v[196:199], v[160:163], v[54:57]
	v_mfma_f32_16x16x32_bf16 v[50:53], v[204:207], v[160:163], v[50:53]
	v_mfma_f32_16x16x32_bf16 v[38:41], v[196:199], v[172:175], v[38:41]
	v_mfma_f32_16x16x32_bf16 v[34:37], v[204:207], v[172:175], v[34:37]
	v_mfma_f32_16x16x32_bf16 v[14:17], v[196:199], v[180:183], v[14:17]
	v_mfma_f32_16x16x32_bf16 v[10:13], v[204:207], v[180:183], v[10:13]
	v_mfma_f32_16x16x32_bf16 v[6:9], v[196:199], v[188:191], v[6:9]
	v_mfma_f32_16x16x32_bf16 v[2:5], v[204:207], v[188:191], v[2:5]
	s_setprio 0
	s_barrier
; #define PG8_STAGE(bufoff, gbase, voff) do { _Pragma("unroll") for (int _i = 0; _i < 2; ++_i) \
;         __builtin_amdgcn_global_load_lds((const unsigned*)((const char*)(gbase) + (voff)[_i]), (LAS unsigned*)(lds + (bufoff) + ldsw + _i * 8192), 16, 0, 0); } while (0)
; #define PG8_LDA(dst, b, h) do { _Pragma("unroll") for (int m = 0; m < 4; ++m) _Pragma("unroll") for (int k = 0; k < 2; ++k) dst[m][k] = *(const LAS bf16x8*)(lds + PG8_SA(b, h) + aoff + m * 2048 + k * 1024); } while (0)
; #define PG8_LDB(dst, b, h) do { _Pragma("unroll") for (int n = 0; n < 2; ++n) _Pragma("unroll") for (int k = 0; k < 2; ++k) dst[n][k] = *(const LAS bf16x8*)(lds + PG8_SB(b, h) + boff + n * 2048 + k * 1024); } while (0)
; #define PG8_MMA(ai, bj, At, Bt) do { __builtin_amdgcn_s_setprio(1); _Pragma("unroll") for (int m = 0; m < 4; ++m) _Pragma("unroll") for (int n = 0; n < 2; ++n) _Pragma("unroll") for (int k = 0; k < 2; ++k) \
;         acc[ai][bj][m][n] = __builtin_amdgcn_mfma_f32_16x16x32_bf16(Bt[n][k], At[m][k], acc[ai][bj][m][n], 0, 0, 0); __builtin_amdgcn_s_setprio(0); } while (0)
; #define PG8_WAIT_V(n) asm volatile("s_waitcnt vmcnt(" #n ")" ::: "memory")
; #define PG8_WAIT_L(n) asm volatile("s_waitcnt lgkmcnt(" #n ")" ::: "memory")
; #define PG8_BAR __builtin_amdgcn_s_barrier()
; #define PG8_SCHED __builtin_amdgcn_sched_barrier(0)
; template <class Epi, class Sched>
; __device__ __forceinline__ void gemm_phase(LAS unsigned char* lds, const Gemm g, const Sched& S, const Epi& E) {
;     ...
;             PG8_STAGE(PG8_SB(0, 1), b2 + hstep, voffB);
;             PG8_WAIT_V(6); PG8_BAR; PG8_MMA(1, 1, At, B1); PG8_BAR;
;             PG8_LDB(B0, 1, 0); PG8_SCHED; PG8_LDA(At, 1, 0); PG8_STAGE(PG8_SA(0, 1), a2 + hstep, voffA);
;             PG8_WAIT_L(8); PG8_BAR; PG8_WAIT_L(0); PG8_MMA(0, 0, At, B0); PG8_BAR; PG8_SCHED;
;             PG8_LDB(B1, 1, 1); PG8_STAGE(PG8_SB(1, 0), b3, voffB);
;             PG8_BAR; PG8_WAIT_L(0); PG8_MMA(0, 1, At, B1); PG8_BAR;
	s_add_u32 s28, s58, 0x80000
	s_addc_u32 s29, s59, 0
	s_add_i32 s38, s67, 0x14000
	v_lshl_add_u64 v[98:99], s[28:29], 0, v[0:1]
	s_mov_b32 m0, s38
	s_nop 0
	global_load_lds_dwordx4 v[98:99], off
	v_lshl_add_u64 v[98:99], s[28:29], 0, v[146:147]
	s_add_i32 m0, s38, 0x2000
	s_nop 0
	global_load_lds_dwordx4 v[98:99], off
	v_add_u32_e32 v110, 0x18000, v169
	ds_read_b128 v[98:101], v110
	ds_read_b128 v[102:105], v110 offset:1024
	ds_read_b128 v[106:109], v110 offset:2048
	ds_read_b128 v[110:113], v110 offset:3072
	ds_read_b128 v[152:155], v171 offset:32768
	ds_read_b128 v[160:163], v171 offset:33792
	ds_read_b128 v[164:167], v171 offset:34816
	ds_read_b128 v[172:175], v171 offset:35840
	ds_read_b128 v[176:179], v171 offset:36864
	ds_read_b128 v[180:183], v171 offset:37888
	ds_read_b128 v[184:187], v171 offset:38912
	ds_read_b128 v[188:191], v171 offset:39936
	v_add_u32_e32 v204, 0x1c000, v169
	ds_read_b128 v[192:195], v204
	ds_read_b128 v[196:199], v204 offset:1024
	ds_read_b128 v[200:203], v204 offset:2048
	ds_read_b128 v[204:207], v204 offset:3072
	s_waitcnt lgkmcnt(4)
	s_barrier
	s_waitcnt lgkmcnt(0)
	s_setprio 1
	v_mfma_f32_16x16x32_bf16 v[142:145], v[98:101], v[152:155], v[142:145]
	v_mfma_f32_16x16x32_bf16 v[138:141], v[106:109], v[152:155], v[138:141]
	v_mfma_f32_16x16x32_bf16 v[126:129], v[98:101], v[164:167], v[126:129]
	v_mfma_f32_16x16x32_bf16 v[122:125], v[106:109], v[164:167], v[122:125]
	v_mfma_f32_16x16x32_bf16 v[94:97], v[98:101], v[176:179], v[94:97]
	v_mfma_f32_16x16x32_bf16 v[90:93], v[106:109], v[176:179], v[90:93]
	v_mfma_f32_16x16x32_bf16 v[86:89], v[98:101], v[184:187], v[86:89]
	v_mfma_f32_16x16x32_bf16 v[82:85], v[106:109], v[184:187], v[82:85]
	v_mfma_f32_16x16x32_bf16 v[142:145], v[102:105], v[160:163], v[142:145]
	v_mfma_f32_16x16x32_bf16 v[138:141], v[110:113], v[160:163], v[138:141]
	v_mfma_f32_16x16x32_bf16 v[126:129], v[102:105], v[172:175], v[126:129]
	v_mfma_f32_16x16x32_bf16 v[122:125], v[110:113], v[172:175], v[122:125]
	v_mfma_f32_16x16x32_bf16 v[94:97], v[102:105], v[180:183], v[94:97]
	v_mfma_f32_16x16x32_bf16 v[90:93], v[110:113], v[180:183], v[90:93]
	v_mfma_f32_16x16x32_bf16 v[86:89], v[102:105], v[188:191], v[86:89]
	v_mfma_f32_16x16x32_bf16 v[82:85], v[110:113], v[188:191], v[82:85]
	s_add_u32 s28, s60, 0x80000
	s_addc_u32 s29, s61, 0
	s_mov_b32 m0, s69
	v_lshl_add_u64 v[226:227], s[28:29], 0, v[0:1]
	global_load_lds_dwordx4 v[226:227], off
	v_lshl_add_u64 v[226:227], s[28:29], 0, v[146:147]
	s_mov_b32 m0, s70
	s_nop 0
	global_load_lds_dwordx4 v[226:227], off
	v_mfma_f32_16x16x32_bf16 v[134:137], v[192:195], v[152:155], v[134:137]
	v_mfma_f32_16x16x32_bf16 v[130:133], v[200:203], v[152:155], v[130:133]
	v_mfma_f32_16x16x32_bf16 v[118:121], v[192:195], v[164:167], v[118:121]
	v_mfma_f32_16x16x32_bf16 v[114:117], v[200:203], v[164:167], v[114:117]
	v_mfma_f32_16x16x32_bf16 v[78:81], v[192:195], v[176:179], v[78:81]
	v_mfma_f32_16x16x32_bf16 v[74:77], v[200:203], v[176:179], v[74:77]
	v_mfma_f32_16x16x32_bf16 v[70:73], v[192:195], v[184:187], v[70:73]
	v_mfma_f32_16x16x32_bf16 v[66:69], v[200:203], v[184:187], v[66:69]
	v_mfma_f32_16x16x32_bf16 v[134:137], v[196:199], v[160:163], v[134:137]
	v_mfma_f32_16x16x32_bf16 v[130:133], v[204:207], v[160:163], v[130:133]
	v_mfma_f32_16x16x32_bf16 v[118:121], v[196:199], v[172:175], v[118:121]
	v_mfma_f32_16x16x32_bf16 v[114:117], v[204:207], v[172:175], v[114:117]
	v_mfma_f32_16x16x32_bf16 v[78:81], v[196:199], v[180:183], v[78:81]
	v_mfma_f32_16x16x32_bf16 v[74:77], v[204:207], v[180:183], v[74:77]
	v_mfma_f32_16x16x32_bf16 v[70:73], v[196:199], v[188:191], v[70:73]
	v_mfma_f32_16x16x32_bf16 v[66:69], v[204:207], v[188:191], v[66:69]
	s_setprio 0
	s_barrier
; #define PG8_STAGE(bufoff, gbase, voff) do { _Pragma("unroll") for (int _i = 0; _i < 2; ++_i) \
;         __builtin_amdgcn_global_load_lds((const unsigned*)((const char*)(gbase) + (voff)[_i]), (LAS unsigned*)(lds + (bufoff) + ldsw + _i * 8192), 16, 0, 0); } while (0)
; #define PG8_LDA(dst, b, h) do { _Pragma("unroll") for (int m = 0; m < 4; ++m) _Pragma("unroll") for (int k = 0; k < 2; ++k) dst[m][k] = *(const LAS bf16x8*)(lds + PG8_SA(b, h) + aoff + m * 2048 + k * 1024); } while (0)
; #define PG8_MMA(ai, bj, At, Bt) do { __builtin_amdgcn_s_setprio(1); _Pragma("unroll") for (int m = 0; m < 4; ++m) _Pragma("unroll") for (int n = 0; n < 2; ++n) _Pragma("unroll") for (int k = 0; k < 2; ++k) \
;         acc[ai][bj][m][n] = __builtin_amdgcn_mfma_f32_16x16x32_bf16(Bt[n][k], At[m][k], acc[ai][bj][m][n], 0, 0, 0); __builtin_amdgcn_s_setprio(0); } while (0)
; #define PG8_WAIT_V(n) asm volatile("s_waitcnt vmcnt(" #n ")" ::: "memory")
; #define PG8_WAIT_L(n) asm volatile("s_waitcnt lgkmcnt(" #n ")" ::: "memory")
; #define PG8_BAR __builtin_amdgcn_s_barrier()
; #define PG8_SCHED __builtin_amdgcn_sched_barrier(0)
;     __device__ __forceinline__ void operator()(const f32x4 (&acc)[2][2][4][2], const Unit& u, int wr, int wc, int fr, int fq) const {
;         const bool lat = u.pm < 64; const int r = lat ? (u.pm >> 3) : 8;
;         const float* s = lat ? src_lat : src_ctx; float* d = lat ? dst_lat : dst_ctx;
; template <class Epi, class Sched>
; __device__ __forceinline__ void gemm_phase(LAS unsigned char* lds, const Gemm g, const Sched& S, const Epi& E) {
;     ...
;             PG8_LDA(At, 1, 1); PG8_STAGE(PG8_SA(1, 0), a3, voffA);
;             PG8_BAR; PG8_WAIT_L(0); PG8_MMA(1, 0, At, B0); PG8_BAR; PG8_SCHED;
;             PG8_STAGE(PG8_SB(1, 1), b3 + hstep, voffB);
;             PG8_WAIT_V(6); PG8_BAR; PG8_MMA(1, 1, At, B1); PG8_BAR;
;         }
;         E(acc, cur, wr, wc, fr, fq);
;         if (!has_next) break;
	s_add_i32 s28, s67, 0x18000
	v_lshl_add_u64 v[156:157], v[156:157], 0, s[36:37]
	s_mov_b32 m0, s28
	s_nop 0
	global_load_lds_dwordx4 v[156:157], off
	v_lshl_add_u64 v[156:157], v[210:211], 0, s[36:37]
	s_add_i32 m0, s28, 0x2000
	s_nop 0
	global_load_lds_dwordx4 v[156:157], off
	s_mov_b32 m0, s72
	v_lshl_add_u64 v[156:157], v[212:213], 0, s[36:37]
	global_load_lds_dwordx4 v[156:157], off
	v_lshl_add_u64 v[156:157], v[214:215], 0, s[36:37]
	s_mov_b32 m0, s73
	s_nop 0
	global_load_lds_dwordx4 v[156:157], off
	ds_read_b128 v[152:155], v171 offset:49152
	ds_read_b128 v[160:163], v171 offset:50176
	ds_read_b128 v[164:167], v171 offset:51200
	ds_read_b128 v[172:175], v171 offset:52224
	ds_read_b128 v[176:179], v171 offset:53248
	ds_read_b128 v[180:183], v171 offset:54272
	ds_read_b128 v[184:187], v171 offset:55296
	ds_read_b128 v[188:191], v171 offset:56320
	s_waitcnt vmcnt(4)
	s_barrier
	s_waitcnt lgkmcnt(0)
	s_setprio 1
	v_mfma_f32_16x16x32_bf16 v[62:65], v[98:101], v[152:155], v[62:65]
	v_mfma_f32_16x16x32_bf16 v[58:61], v[106:109], v[152:155], v[58:61]
	v_mfma_f32_16x16x32_bf16 v[46:49], v[98:101], v[164:167], v[46:49]
	v_mfma_f32_16x16x32_bf16 v[42:45], v[106:109], v[164:167], v[42:45]
	v_mfma_f32_16x16x32_bf16 v[30:33], v[98:101], v[176:179], v[30:33]
	v_mfma_f32_16x16x32_bf16 v[26:29], v[106:109], v[176:179], v[26:29]
	v_mfma_f32_16x16x32_bf16 v[22:25], v[98:101], v[184:187], v[22:25]
	v_mfma_f32_16x16x32_bf16 v[18:21], v[106:109], v[184:187], v[18:21]
	v_mfma_f32_16x16x32_bf16 v[62:65], v[102:105], v[160:163], v[62:65]
	v_mfma_f32_16x16x32_bf16 v[58:61], v[110:113], v[160:163], v[58:61]
	v_mfma_f32_16x16x32_bf16 v[46:49], v[102:105], v[172:175], v[46:49]
	v_mfma_f32_16x16x32_bf16 v[42:45], v[110:113], v[172:175], v[42:45]
	v_mfma_f32_16x16x32_bf16 v[30:33], v[102:105], v[180:183], v[30:33]
	v_mfma_f32_16x16x32_bf16 v[26:29], v[110:113], v[180:183], v[26:29]
	v_mfma_f32_16x16x32_bf16 v[22:25], v[102:105], v[188:191], v[22:25]
	v_mfma_f32_16x16x32_bf16 v[18:21], v[110:113], v[188:191], v[18:21]
	s_add_u32 s28, s58, 0x80080
	s_addc_u32 s29, s59, 0
	s_add_i32 s38, s67, 0x1c000
	v_lshl_add_u64 v[98:99], s[28:29], 0, v[0:1]
	s_mov_b32 m0, s38
	s_nop 0
	global_load_lds_dwordx4 v[98:99], off
	v_lshl_add_u64 v[98:99], s[28:29], 0, v[146:147]
	s_add_i32 m0, s38, 0x2000
	s_nop 0
	global_load_lds_dwordx4 v[98:99], off
	v_mfma_f32_16x16x32_bf16 v[54:57], v[192:195], v[152:155], v[54:57]
	v_mfma_f32_16x16x32_bf16 v[50:53], v[200:203], v[152:155], v[50:53]
	v_mfma_f32_16x16x32_bf16 v[38:41], v[192:195], v[164:167], v[38:41]
	v_mfma_f32_16x16x32_bf16 v[34:37], v[200:203], v[164:167], v[34:37]
	v_mfma_f32_16x16x32_bf16 v[14:17], v[192:195], v[176:179], v[14:17]
	v_mfma_f32_16x16x32_bf16 v[10:13], v[200:203], v[176:179], v[10:13]
	v_mfma_f32_16x16x32_bf16 v[6:9], v[192:195], v[184:187], v[6:9]
	v_mfma_f32_16x16x32_bf16 v[2:5], v[200:203], v[184:187], v[2:5]
	v_mfma_f32_16x16x32_bf16 v[54:57], v[196:199], v[160:163], v[54:57]
	v_mfma_f32_16x16x32_bf16 v[50:53], v[204:207], v[160:163], v[50:53]
	v_mfma_f32_16x16x32_bf16 v[38:41], v[196:199], v[172:175], v[38:41]
	v_mfma_f32_16x16x32_bf16 v[34:37], v[204:207], v[172:175], v[34:37]
	v_mfma_f32_16x16x32_bf16 v[14:17], v[196:199], v[180:183], v[14:17]
	v_mfma_f32_16x16x32_bf16 v[10:13], v[204:207], v[180:183], v[10:13]
	v_mfma_f32_16x16x32_bf16 v[6:9], v[196:199], v[188:191], v[6:9]
	v_mfma_f32_16x16x32_bf16 v[2:5], v[204:207], v[188:191], v[2:5]
	s_setprio 0
	s_add_i32 s81, s81, 2
	s_add_u32 s79, s79, 0x100
	s_addc_u32 s80, s80, 0
	s_cmp_gt_u32 s81, 29
	s_mov_b64 s[28:29], s[56:57]
	s_barrier
	s_cbranch_scc0 .LBB0_99
	s_cmp_lt_i32 s8, 64
	s_cselect_b64 s[58:59], -1, 0
	s_cmp_gt_i32 s8, 63
	s_cbranch_scc0 .LBB0_90
	s_mov_b64 s[60:61], 0x18000
	s_mov_b64 s[28:29], s[46:47]
	s_mov_b64 s[56:57], s[24:25]
	s_branch .LBB0_91

; #define PG8_STAGE(bufoff, gbase, voff) do { _Pragma("unroll") for (int _i = 0; _i < 2; ++_i) \
;         __builtin_amdgcn_global_load_lds((const unsigned*)((const char*)(gbase) + (voff)[_i]), (LAS unsigned*)(lds + (bufoff) + ldsw + _i * 8192), 16, 0, 0); } while (0)
; #define PG8_LDA(dst, b, h) do { _Pragma("unroll") for (int m = 0; m < 4; ++m) _Pragma("unroll") for (int k = 0; k < 2; ++k) dst[m][k] = *(const LAS bf16x8*)(lds + PG8_SA(b, h) + aoff + m * 2048 + k * 1024); } while (0)
; #define PG8_LDB(dst, b, h) do { _Pragma("unroll") for (int n = 0; n < 2; ++n) _Pragma("unroll") for (int k = 0; k < 2; ++k) dst[n][k] = *(const LAS bf16x8*)(lds + PG8_SB(b, h) + boff + n * 2048 + k * 1024); } while (0)
; #define PG8_MMA(ai, bj, At, Bt) do { __builtin_amdgcn_s_setprio(1); _Pragma("unroll") for (int m = 0; m < 4; ++m) _Pragma("unroll") for (int n = 0; n < 2; ++n) _Pragma("unroll") for (int k = 0; k < 2; ++k) \
;         acc[ai][bj][m][n] = __builtin_amdgcn_mfma_f32_16x16x32_bf16(Bt[n][k], At[m][k], acc[ai][bj][m][n], 0, 0, 0); __builtin_amdgcn_s_setprio(0); } while (0)
; #define PG8_WAIT_V(n) asm volatile("s_waitcnt vmcnt(" #n ")" ::: "memory")
; #define PG8_WAIT_L(n) asm volatile("s_waitcnt lgkmcnt(" #n ")" ::: "memory")
; #define PG8_BAR __builtin_amdgcn_s_barrier()
; #define PG8_SCHED __builtin_amdgcn_sched_barrier(0)
; template <class Epi, class Sched>
; __device__ __forceinline__ void gemm_phase(LAS unsigned char* lds, const Gemm g, const Sched& S, const Epi& E) {
;     ...
;             PG8_LDB(B0, 0, 0); PG8_SCHED; PG8_LDA(At, 0, 0); PG8_STAGE(PG8_SA(1, 1), a1 + hstep, voffA);
;             PG8_WAIT_L(8); PG8_BAR; PG8_WAIT_L(0); PG8_MMA(0, 0, At, B0); PG8_BAR; PG8_SCHED;
;             PG8_LDB(B1, 0, 1); PG8_STAGE(PG8_SB(0, 0), b2, voffB);
;             PG8_BAR; PG8_WAIT_L(0); PG8_MMA(0, 1, At, B1); PG8_BAR;
;             PG8_LDA(At, 0, 1); PG8_STAGE(PG8_SA(0, 0), a2, voffA);
;             PG8_BAR; PG8_WAIT_L(0); PG8_MMA(1, 0, At, B0); PG8_BAR; PG8_SCHED;
;             PG8_STAGE(PG8_SB(0, 1), b2 + hstep, voffB);
;             PG8_WAIT_V(6); PG8_BAR; PG8_MMA(1, 1, At, B1); PG8_BAR;
.LBB0_113:
	v_add_u32_e32 v152, 0x10000, v137
	ds_read_b128 v[140:143], v152
	ds_read_b128 v[144:147], v152 offset:1024
	ds_read_b128 v[148:151], v152 offset:2048
	ds_read_b128 v[152:155], v152 offset:3072
	ds_read_b128 v[160:163], v139
	ds_read_b128 v[164:167], v139 offset:1024
	ds_read_b128 v[168:171], v139 offset:2048
	ds_read_b128 v[172:175], v139 offset:3072
	ds_read_b128 v[176:179], v139 offset:4096
	ds_read_b128 v[180:183], v139 offset:5120
	ds_read_b128 v[184:187], v139 offset:6144
	ds_read_b128 v[188:191], v139 offset:7168
	v_add_u32_e32 v156, 0x14000, v137
	ds_read_b128 v[192:195], v156
	ds_read_b128 v[196:199], v156 offset:1024
	ds_read_b128 v[200:203], v156 offset:2048
	ds_read_b128 v[204:207], v156 offset:3072
	s_waitcnt lgkmcnt(4)
	s_barrier
	s_waitcnt lgkmcnt(0)
	s_setprio 1
	v_mfma_f32_16x16x32_bf16 v[126:129], v[140:143], v[160:163], v[126:129]
	v_mfma_f32_16x16x32_bf16 v[122:125], v[148:151], v[160:163], v[122:125]
	v_mfma_f32_16x16x32_bf16 v[118:121], v[140:143], v[168:171], v[118:121]
	v_mfma_f32_16x16x32_bf16 v[114:117], v[148:151], v[168:171], v[114:117]
	v_mfma_f32_16x16x32_bf16 v[106:109], v[140:143], v[176:179], v[106:109]
	v_mfma_f32_16x16x32_bf16 v[98:101], v[148:151], v[176:179], v[98:101]
	v_mfma_f32_16x16x32_bf16 v[90:93], v[140:143], v[184:187], v[90:93]
	v_mfma_f32_16x16x32_bf16 v[82:85], v[148:151], v[184:187], v[82:85]
	v_mfma_f32_16x16x32_bf16 v[126:129], v[144:147], v[164:167], v[126:129]
	v_mfma_f32_16x16x32_bf16 v[122:125], v[152:155], v[164:167], v[122:125]
	v_mfma_f32_16x16x32_bf16 v[118:121], v[144:147], v[172:175], v[118:121]
	v_mfma_f32_16x16x32_bf16 v[114:117], v[152:155], v[172:175], v[114:117]
	v_mfma_f32_16x16x32_bf16 v[106:109], v[144:147], v[180:183], v[106:109]
	v_mfma_f32_16x16x32_bf16 v[98:101], v[152:155], v[180:183], v[98:101]
	v_mfma_f32_16x16x32_bf16 v[90:93], v[144:147], v[188:191], v[90:93]
	v_mfma_f32_16x16x32_bf16 v[82:85], v[152:155], v[188:191], v[82:85]
	s_add_u32 s54, s52, 0x100
	s_addc_u32 s55, s53, 0
	s_cmp_eq_u32 s73, 4
	s_cselect_b32 s59, s11, s55
	s_cselect_b32 s58, s29, s54
	s_cselect_b32 s57, s41, s72
	s_cselect_b32 s56, s45, s71
	v_lshl_add_u64 v[228:229], s[52:53], 0, v[134:135]
	s_add_i32 m0, s25, 0xc000
	s_nop 0
	global_load_lds_dwordx4 v[228:229], off
	v_lshl_add_u64 v[228:229], s[52:53], 0, v[132:133]
	s_add_i32 m0, s25, 0xe000
	s_nop 0
	global_load_lds_dwordx4 v[228:229], off
	v_mfma_f32_16x16x32_bf16 v[110:113], v[192:195], v[160:163], v[110:113]
	v_mfma_f32_16x16x32_bf16 v[102:105], v[200:203], v[160:163], v[102:105]
	v_mfma_f32_16x16x32_bf16 v[94:97], v[192:195], v[168:171], v[94:97]
	v_mfma_f32_16x16x32_bf16 v[86:89], v[200:203], v[168:171], v[86:89]
	v_mfma_f32_16x16x32_bf16 v[78:81], v[192:195], v[176:179], v[78:81]
	v_mfma_f32_16x16x32_bf16 v[74:77], v[200:203], v[176:179], v[74:77]
	v_mfma_f32_16x16x32_bf16 v[70:73], v[192:195], v[184:187], v[70:73]
	v_mfma_f32_16x16x32_bf16 v[66:69], v[200:203], v[184:187], v[66:69]
	v_mfma_f32_16x16x32_bf16 v[110:113], v[196:199], v[164:167], v[110:113]
	v_mfma_f32_16x16x32_bf16 v[102:105], v[204:207], v[164:167], v[102:105]
	v_mfma_f32_16x16x32_bf16 v[94:97], v[196:199], v[172:175], v[94:97]
	v_mfma_f32_16x16x32_bf16 v[86:89], v[204:207], v[172:175], v[86:89]
	v_mfma_f32_16x16x32_bf16 v[78:81], v[196:199], v[180:183], v[78:81]
	v_mfma_f32_16x16x32_bf16 v[74:77], v[204:207], v[180:183], v[74:77]
	v_mfma_f32_16x16x32_bf16 v[70:73], v[196:199], v[188:191], v[70:73]
	v_mfma_f32_16x16x32_bf16 v[66:69], v[204:207], v[188:191], v[66:69]
	s_setprio 0
	s_barrier
	s_add_i32 s38, s65, 0x10000
	v_lshl_add_u64 v[156:157], s[56:57], 0, v[0:1]
	s_mov_b32 m0, s38
	v_lshl_add_u64 v[210:211], s[56:57], 0, v[130:131]
	global_load_lds_dwordx4 v[156:157], off
	s_add_i32 m0, s38, 0x2000
	s_nop 0
	global_load_lds_dwordx4 v[210:211], off
	s_mov_b32 m0, s25
	v_lshl_add_u64 v[212:213], s[58:59], 0, v[0:1]
	global_load_lds_dwordx4 v[212:213], off
	v_lshl_add_u64 v[214:215], s[58:59], 0, v[130:131]
	s_mov_b32 m0, s27
	s_nop 0
	global_load_lds_dwordx4 v[214:215], off
	ds_read_b128 v[160:163], v139 offset:16384
	ds_read_b128 v[164:167], v139 offset:17408
	ds_read_b128 v[168:171], v139 offset:18432
	ds_read_b128 v[172:175], v139 offset:19456
	ds_read_b128 v[176:179], v139 offset:20480
	ds_read_b128 v[180:183], v139 offset:21504
	ds_read_b128 v[184:187], v139 offset:22528
	ds_read_b128 v[188:191], v139 offset:23552
	s_waitcnt vmcnt(4)
	s_barrier
	s_waitcnt lgkmcnt(0)
	s_setprio 1
	v_mfma_f32_16x16x32_bf16 v[62:65], v[140:143], v[160:163], v[62:65]
	v_mfma_f32_16x16x32_bf16 v[58:61], v[148:151], v[160:163], v[58:61]
	v_mfma_f32_16x16x32_bf16 v[54:57], v[140:143], v[168:171], v[54:57]
	v_mfma_f32_16x16x32_bf16 v[50:53], v[148:151], v[168:171], v[50:53]
	v_mfma_f32_16x16x32_bf16 v[38:41], v[140:143], v[176:179], v[38:41]
	v_mfma_f32_16x16x32_bf16 v[34:37], v[148:151], v[176:179], v[34:37]
	v_mfma_f32_16x16x32_bf16 v[22:25], v[140:143], v[184:187], v[22:25]
	v_mfma_f32_16x16x32_bf16 v[18:21], v[148:151], v[184:187], v[18:21]
	v_mfma_f32_16x16x32_bf16 v[62:65], v[144:147], v[164:167], v[62:65]
	v_mfma_f32_16x16x32_bf16 v[58:61], v[152:155], v[164:167], v[58:61]
	v_mfma_f32_16x16x32_bf16 v[54:57], v[144:147], v[172:175], v[54:57]
	v_mfma_f32_16x16x32_bf16 v[50:53], v[152:155], v[172:175], v[50:53]
	v_mfma_f32_16x16x32_bf16 v[38:41], v[144:147], v[180:183], v[38:41]
	v_mfma_f32_16x16x32_bf16 v[34:37], v[152:155], v[180:183], v[34:37]
	v_mfma_f32_16x16x32_bf16 v[22:25], v[144:147], v[188:191], v[22:25]
	v_mfma_f32_16x16x32_bf16 v[18:21], v[152:155], v[188:191], v[18:21]
	v_mfma_f32_16x16x32_bf16 v[46:49], v[192:195], v[160:163], v[46:49]
	v_mfma_f32_16x16x32_bf16 v[42:45], v[200:203], v[160:163], v[42:45]
	v_mfma_f32_16x16x32_bf16 v[30:33], v[192:195], v[168:171], v[30:33]
	v_mfma_f32_16x16x32_bf16 v[26:29], v[200:203], v[168:171], v[26:29]
	v_mfma_f32_16x16x32_bf16 v[14:17], v[192:195], v[176:179], v[14:17]
	v_mfma_f32_16x16x32_bf16 v[10:13], v[200:203], v[176:179], v[10:13]
	v_mfma_f32_16x16x32_bf16 v[6:9], v[192:195], v[184:187], v[6:9]
	v_mfma_f32_16x16x32_bf16 v[2:5], v[200:203], v[184:187], v[2:5]
	v_mfma_f32_16x16x32_bf16 v[46:49], v[196:199], v[164:167], v[46:49]
	v_mfma_f32_16x16x32_bf16 v[42:45], v[204:207], v[164:167], v[42:45]
	v_mfma_f32_16x16x32_bf16 v[30:33], v[196:199], v[172:175], v[30:33]
	v_mfma_f32_16x16x32_bf16 v[26:29], v[204:207], v[172:175], v[26:29]
	v_mfma_f32_16x16x32_bf16 v[14:17], v[196:199], v[180:183], v[14:17]
	v_mfma_f32_16x16x32_bf16 v[10:13], v[204:207], v[180:183], v[10:13]
	v_mfma_f32_16x16x32_bf16 v[6:9], v[196:199], v[188:191], v[6:9]
	v_mfma_f32_16x16x32_bf16 v[2:5], v[204:207], v[188:191], v[2:5]
	s_setprio 0
	s_barrier
; #define PG8_STAGE(bufoff, gbase, voff) do { _Pragma("unroll") for (int _i = 0; _i < 2; ++_i) \
;         __builtin_amdgcn_global_load_lds((const unsigned*)((const char*)(gbase) + (voff)[_i]), (LAS unsigned*)(lds + (bufoff) + ldsw + _i * 8192), 16, 0, 0); } while (0)
; #define PG8_LDA(dst, b, h) do { _Pragma("unroll") for (int m = 0; m < 4; ++m) _Pragma("unroll") for (int k = 0; k < 2; ++k) dst[m][k] = *(const LAS bf16x8*)(lds + PG8_SA(b, h) + aoff + m * 2048 + k * 1024); } while (0)
; #define PG8_LDB(dst, b, h) do { _Pragma("unroll") for (int n = 0; n < 2; ++n) _Pragma("unroll") for (int k = 0; k < 2; ++k) dst[n][k] = *(const LAS bf16x8*)(lds + PG8_SB(b, h) + boff + n * 2048 + k * 1024); } while (0)
; #define PG8_MMA(ai, bj, At, Bt) do { __builtin_amdgcn_s_setprio(1); _Pragma("unroll") for (int m = 0; m < 4; ++m) _Pragma("unroll") for (int n = 0; n < 2; ++n) _Pragma("unroll") for (int k = 0; k < 2; ++k) \
;         acc[ai][bj][m][n] = __builtin_amdgcn_mfma_f32_16x16x32_bf16(Bt[n][k], At[m][k], acc[ai][bj][m][n], 0, 0, 0); __builtin_amdgcn_s_setprio(0); } while (0)
; #define PG8_WAIT_V(n) asm volatile("s_waitcnt vmcnt(" #n ")" ::: "memory")
; #define PG8_WAIT_L(n) asm volatile("s_waitcnt lgkmcnt(" #n ")" ::: "memory")
; #define PG8_BAR __builtin_amdgcn_s_barrier()
; #define PG8_SCHED __builtin_amdgcn_sched_barrier(0)
; template <class Epi, class Sched>
; __device__ __forceinline__ void gemm_phase(LAS unsigned char* lds, const Gemm g, const Sched& S, const Epi& E) {
;     ...
;             PG8_STAGE(PG8_SB(0, 1), b2 + hstep, voffB);
;             PG8_WAIT_V(6); PG8_BAR; PG8_MMA(1, 1, At, B1); PG8_BAR;
;             PG8_LDB(B0, 1, 0); PG8_SCHED; PG8_LDA(At, 1, 0); PG8_STAGE(PG8_SA(0, 1), a2 + hstep, voffA);
;             PG8_WAIT_L(8); PG8_BAR; PG8_WAIT_L(0); PG8_MMA(0, 0, At, B0); PG8_BAR; PG8_SCHED;
;             PG8_LDB(B1, 1, 1); PG8_STAGE(PG8_SB(1, 0), b3, voffB);
;             PG8_BAR; PG8_WAIT_L(0); PG8_MMA(0, 1, At, B1); PG8_BAR;
;             PG8_LDA(At, 1, 1); PG8_STAGE(PG8_SA(1, 0), a3, voffA);
;             PG8_BAR; PG8_WAIT_L(0); PG8_MMA(1, 0, At, B0); PG8_BAR; PG8_SCHED;
;             PG8_STAGE(PG8_SB(1, 1), b3 + hstep, voffB);
	s_add_u32 s38, s56, 0x80000
	s_addc_u32 s39, s57, 0
	s_add_i32 s52, s65, 0x14000
	v_lshl_add_u64 v[140:141], s[38:39], 0, v[0:1]
	s_mov_b32 m0, s52
	s_nop 0
	global_load_lds_dwordx4 v[140:141], off
	v_lshl_add_u64 v[140:141], s[38:39], 0, v[130:131]
	s_add_i32 m0, s52, 0x2000
	s_nop 0
	global_load_lds_dwordx4 v[140:141], off
	v_add_u32_e32 v152, 0x18000, v137
	ds_read_b128 v[140:143], v152
	ds_read_b128 v[144:147], v152 offset:1024
	ds_read_b128 v[148:151], v152 offset:2048
	ds_read_b128 v[152:155], v152 offset:3072
	ds_read_b128 v[160:163], v139 offset:32768
	ds_read_b128 v[164:167], v139 offset:33792
	ds_read_b128 v[168:171], v139 offset:34816
	ds_read_b128 v[172:175], v139 offset:35840
	ds_read_b128 v[176:179], v139 offset:36864
	ds_read_b128 v[180:183], v139 offset:37888
	ds_read_b128 v[184:187], v139 offset:38912
	ds_read_b128 v[188:191], v139 offset:39936
	v_add_u32_e32 v204, 0x1c000, v137
	ds_read_b128 v[192:195], v204
	ds_read_b128 v[196:199], v204 offset:1024
	ds_read_b128 v[200:203], v204 offset:2048
	ds_read_b128 v[204:207], v204 offset:3072
	s_waitcnt lgkmcnt(4)
	s_barrier
	s_waitcnt lgkmcnt(0)
	s_setprio 1
	v_mfma_f32_16x16x32_bf16 v[126:129], v[140:143], v[160:163], v[126:129]
	v_mfma_f32_16x16x32_bf16 v[122:125], v[148:151], v[160:163], v[122:125]
	v_mfma_f32_16x16x32_bf16 v[118:121], v[140:143], v[168:171], v[118:121]
	v_mfma_f32_16x16x32_bf16 v[114:117], v[148:151], v[168:171], v[114:117]
	v_mfma_f32_16x16x32_bf16 v[106:109], v[140:143], v[176:179], v[106:109]
	v_mfma_f32_16x16x32_bf16 v[98:101], v[148:151], v[176:179], v[98:101]
	v_mfma_f32_16x16x32_bf16 v[90:93], v[140:143], v[184:187], v[90:93]
	v_mfma_f32_16x16x32_bf16 v[82:85], v[148:151], v[184:187], v[82:85]
	v_mfma_f32_16x16x32_bf16 v[126:129], v[144:147], v[164:167], v[126:129]
	v_mfma_f32_16x16x32_bf16 v[122:125], v[152:155], v[164:167], v[122:125]
	v_mfma_f32_16x16x32_bf16 v[118:121], v[144:147], v[172:175], v[118:121]
	v_mfma_f32_16x16x32_bf16 v[114:117], v[152:155], v[172:175], v[114:117]
	v_mfma_f32_16x16x32_bf16 v[106:109], v[144:147], v[180:183], v[106:109]
	v_mfma_f32_16x16x32_bf16 v[98:101], v[152:155], v[180:183], v[98:101]
	v_mfma_f32_16x16x32_bf16 v[90:93], v[144:147], v[188:191], v[90:93]
	v_mfma_f32_16x16x32_bf16 v[82:85], v[152:155], v[188:191], v[82:85]
	s_add_u32 s38, s58, 0x80000
	s_addc_u32 s39, s59, 0
	s_mov_b32 m0, s66
	v_lshl_add_u64 v[226:227], s[38:39], 0, v[0:1]
	global_load_lds_dwordx4 v[226:227], off
	v_lshl_add_u64 v[226:227], s[38:39], 0, v[130:131]
	s_mov_b32 m0, s67
	s_nop 0
	global_load_lds_dwordx4 v[226:227], off
	v_mfma_f32_16x16x32_bf16 v[110:113], v[192:195], v[160:163], v[110:113]
	v_mfma_f32_16x16x32_bf16 v[102:105], v[200:203], v[160:163], v[102:105]
	v_mfma_f32_16x16x32_bf16 v[94:97], v[192:195], v[168:171], v[94:97]
	v_mfma_f32_16x16x32_bf16 v[86:89], v[200:203], v[168:171], v[86:89]
	v_mfma_f32_16x16x32_bf16 v[78:81], v[192:195], v[176:179], v[78:81]
	v_mfma_f32_16x16x32_bf16 v[74:77], v[200:203], v[176:179], v[74:77]
	v_mfma_f32_16x16x32_bf16 v[70:73], v[192:195], v[184:187], v[70:73]
	v_mfma_f32_16x16x32_bf16 v[66:69], v[200:203], v[184:187], v[66:69]
	v_mfma_f32_16x16x32_bf16 v[110:113], v[196:199], v[164:167], v[110:113]
	v_mfma_f32_16x16x32_bf16 v[102:105], v[204:207], v[164:167], v[102:105]
	v_mfma_f32_16x16x32_bf16 v[94:97], v[196:199], v[172:175], v[94:97]
	v_mfma_f32_16x16x32_bf16 v[86:89], v[204:207], v[172:175], v[86:89]
	v_mfma_f32_16x16x32_bf16 v[78:81], v[196:199], v[180:183], v[78:81]
	v_mfma_f32_16x16x32_bf16 v[74:77], v[204:207], v[180:183], v[74:77]
	v_mfma_f32_16x16x32_bf16 v[70:73], v[196:199], v[188:191], v[70:73]
	v_mfma_f32_16x16x32_bf16 v[66:69], v[204:207], v[188:191], v[66:69]
	s_setprio 0
	s_barrier
	s_add_i32 s38, s65, 0x18000
	v_lshl_add_u64 v[156:157], v[156:157], 0, s[36:37]
	s_mov_b32 m0, s38
	s_nop 0
	global_load_lds_dwordx4 v[156:157], off
	v_lshl_add_u64 v[156:157], v[210:211], 0, s[36:37]
	s_add_i32 m0, s38, 0x2000
	s_nop 0
	global_load_lds_dwordx4 v[156:157], off
	s_mov_b32 m0, s68
	v_lshl_add_u64 v[156:157], v[212:213], 0, s[36:37]
	global_load_lds_dwordx4 v[156:157], off
	v_lshl_add_u64 v[156:157], v[214:215], 0, s[36:37]
	s_mov_b32 m0, s69
	s_nop 0
	global_load_lds_dwordx4 v[156:157], off
	ds_read_b128 v[160:163], v139 offset:49152
	ds_read_b128 v[164:167], v139 offset:50176
	ds_read_b128 v[168:171], v139 offset:51200
	ds_read_b128 v[172:175], v139 offset:52224
	ds_read_b128 v[176:179], v139 offset:53248
	ds_read_b128 v[180:183], v139 offset:54272
	ds_read_b128 v[184:187], v139 offset:55296
	ds_read_b128 v[188:191], v139 offset:56320
	s_waitcnt vmcnt(4)
	s_barrier
; #define PG8_STAGE(bufoff, gbase, voff) do { _Pragma("unroll") for (int _i = 0; _i < 2; ++_i) \
;         __builtin_amdgcn_global_load_lds((const unsigned*)((const char*)(gbase) + (voff)[_i]), (LAS unsigned*)(lds + (bufoff) + ldsw + _i * 8192), 16, 0, 0); } while (0)
; #define PG8_MMA(ai, bj, At, Bt) do { __builtin_amdgcn_s_setprio(1); _Pragma("unroll") for (int m = 0; m < 4; ++m) _Pragma("unroll") for (int n = 0; n < 2; ++n) _Pragma("unroll") for (int k = 0; k < 2; ++k) \
;         acc[ai][bj][m][n] = __builtin_amdgcn_mfma_f32_16x16x32_bf16(Bt[n][k], At[m][k], acc[ai][bj][m][n], 0, 0, 0); __builtin_amdgcn_s_setprio(0); } while (0)
; #define PG8_WAIT_V(n) asm volatile("s_waitcnt vmcnt(" #n ")" ::: "memory")
; #define PG8_BAR __builtin_amdgcn_s_barrier()
;     __device__ __forceinline__ void operator()(const f32x4 (&acc)[2][2][4][2], const Unit& u, int wr, int wc, int fr, int fq) const {
;         const int row0 = u.pm * BM + wr * 64 + fr, col0 = u.pn * BM + wc * 32 + 4 * fq;
;         float* base = part + (size_t)u.ks * Mp * ldc;
; #pragma unroll
;         for (int ai = 0; ai < 2; ++ai)
; #pragma unroll
;             for (int m = 0; m < 4; ++m) { float* rowp = base + (size_t)(row0 + ai * HALF + m * 16) * ldc + col0;
; #pragma unroll
;                 for (int bj = 0; bj < 2; ++bj)
; #pragma unroll
;                     for (int n = 0; n < 2; ++n) *(f32x4*)(rowp + bj * HALF + n * 16) = acc[ai][bj][m][n]; }
;     }
; template <class Epi, class Sched>
; __device__ __forceinline__ void gemm_phase(LAS unsigned char* lds, const Gemm g, const Sched& S, const Epi& E) {
;     ...
;             PG8_STAGE(PG8_SB(1, 1), b3 + hstep, voffB);
;             PG8_WAIT_V(6); PG8_BAR; PG8_MMA(1, 1, At, B1); PG8_BAR;
;         }
;         E(acc, cur, wr, wc, fr, fq);
;         if (!has_next) break;
	s_waitcnt lgkmcnt(0)
	s_setprio 1
	v_mfma_f32_16x16x32_bf16 v[62:65], v[140:143], v[160:163], v[62:65]
	v_mfma_f32_16x16x32_bf16 v[58:61], v[148:151], v[160:163], v[58:61]
	v_mfma_f32_16x16x32_bf16 v[54:57], v[140:143], v[168:171], v[54:57]
	v_mfma_f32_16x16x32_bf16 v[50:53], v[148:151], v[168:171], v[50:53]
	v_mfma_f32_16x16x32_bf16 v[38:41], v[140:143], v[176:179], v[38:41]
	v_mfma_f32_16x16x32_bf16 v[34:37], v[148:151], v[176:179], v[34:37]
	v_mfma_f32_16x16x32_bf16 v[22:25], v[140:143], v[184:187], v[22:25]
	v_mfma_f32_16x16x32_bf16 v[18:21], v[148:151], v[184:187], v[18:21]
	v_mfma_f32_16x16x32_bf16 v[62:65], v[144:147], v[164:167], v[62:65]
	v_mfma_f32_16x16x32_bf16 v[58:61], v[152:155], v[164:167], v[58:61]
	v_mfma_f32_16x16x32_bf16 v[54:57], v[144:147], v[172:175], v[54:57]
	v_mfma_f32_16x16x32_bf16 v[50:53], v[152:155], v[172:175], v[50:53]
	v_mfma_f32_16x16x32_bf16 v[38:41], v[144:147], v[180:183], v[38:41]
	v_mfma_f32_16x16x32_bf16 v[34:37], v[152:155], v[180:183], v[34:37]
	v_mfma_f32_16x16x32_bf16 v[22:25], v[144:147], v[188:191], v[22:25]
	v_mfma_f32_16x16x32_bf16 v[18:21], v[152:155], v[188:191], v[18:21]
	s_add_u32 s38, s56, 0x80080
	s_addc_u32 s39, s57, 0
	s_add_i32 s52, s65, 0x1c000
	v_lshl_add_u64 v[140:141], s[38:39], 0, v[0:1]
	s_mov_b32 m0, s52
	s_nop 0
	global_load_lds_dwordx4 v[140:141], off
	v_lshl_add_u64 v[140:141], s[38:39], 0, v[130:131]
	s_add_i32 m0, s52, 0x2000
	s_nop 0
	global_load_lds_dwordx4 v[140:141], off
	v_mfma_f32_16x16x32_bf16 v[46:49], v[192:195], v[160:163], v[46:49]
	v_mfma_f32_16x16x32_bf16 v[42:45], v[200:203], v[160:163], v[42:45]
	v_mfma_f32_16x16x32_bf16 v[30:33], v[192:195], v[168:171], v[30:33]
	v_mfma_f32_16x16x32_bf16 v[26:29], v[200:203], v[168:171], v[26:29]
	v_mfma_f32_16x16x32_bf16 v[14:17], v[192:195], v[176:179], v[14:17]
	v_mfma_f32_16x16x32_bf16 v[10:13], v[200:203], v[176:179], v[10:13]
	v_mfma_f32_16x16x32_bf16 v[6:9], v[192:195], v[184:187], v[6:9]
	v_mfma_f32_16x16x32_bf16 v[2:5], v[200:203], v[184:187], v[2:5]
	v_mfma_f32_16x16x32_bf16 v[46:49], v[196:199], v[164:167], v[46:49]
	v_mfma_f32_16x16x32_bf16 v[42:45], v[204:207], v[164:167], v[42:45]
	v_mfma_f32_16x16x32_bf16 v[30:33], v[196:199], v[172:175], v[30:33]
	v_mfma_f32_16x16x32_bf16 v[26:29], v[204:207], v[172:175], v[26:29]
	v_mfma_f32_16x16x32_bf16 v[14:17], v[196:199], v[180:183], v[14:17]
	v_mfma_f32_16x16x32_bf16 v[10:13], v[204:207], v[180:183], v[10:13]
	v_mfma_f32_16x16x32_bf16 v[6:9], v[196:199], v[188:191], v[6:9]
	v_mfma_f32_16x16x32_bf16 v[2:5], v[204:207], v[188:191], v[2:5]
	s_setprio 0
	s_add_i32 s73, s73, 2
	s_add_u32 s71, s71, 0x100
	s_addc_u32 s72, s72, 0
	s_cmp_gt_u32 s73, 5
	s_mov_b64 s[52:53], s[54:55]
	s_barrier
	s_cbranch_scc0 .LBB0_113
	s_ashr_i32 s11, s10, 31
	s_lshl_b64 s[10:11], s[10:11], 24
	v_lshl_or_b32 v140, s26, 8, v138
	s_add_u32 s10, s8, s10
	v_lshl_add_u32 v142, s24, 8, v136
	s_addc_u32 s11, s9, s11
	v_ashrrev_i32_e32 v141, 31, v140
	v_ashrrev_i32_e32 v143, 31, v142
	v_lshl_add_u64 v[140:141], v[140:141], 2, s[10:11]
	v_lshlrev_b64 v[144:145], 13, v[142:143]
	v_lshl_add_u64 v[144:145], v[140:141], 0, v[144:145]
	global_store_dwordx4 v[144:145], v[126:129], off
	global_store_dwordx4 v[144:145], v[122:125], off offset:64
	global_store_dwordx4 v[144:145], v[110:113], off offset:512
	global_store_dwordx4 v[144:145], v[102:105], off offset:576
	s_mov_b64 s[10:11], 0x100000
	s_mov_b32 s26, s40
	v_or_b32_e32 v102, 16, v142
	v_ashrrev_i32_e32 v103, 31, v102
	v_lshlrev_b64 v[102:103], 13, v[102:103]
	v_lshl_add_u64 v[102:103], v[140:141], 0, v[102:103]
	global_store_dwordx4 v[102:103], v[118:121], off
	global_store_dwordx4 v[102:103], v[114:117], off offset:64
	global_store_dwordx4 v[102:103], v[94:97], off offset:512
	global_store_dwordx4 v[102:103], v[86:89], off offset:576
	s_mov_b32 s24, s44
	s_mov_b64 s[54:55], s[50:51]
	v_or_b32_e32 v86, 32, v142
	v_ashrrev_i32_e32 v87, 31, v86
	v_lshlrev_b64 v[86:87], 13, v[86:87]
	v_lshl_add_u64 v[86:87], v[140:141], 0, v[86:87]
	global_store_dwordx4 v[86:87], v[106:109], off
	global_store_dwordx4 v[86:87], v[98:101], off offset:64
	global_store_dwordx4 v[86:87], v[78:81], off offset:512
	global_store_dwordx4 v[86:87], v[74:77], off offset:576
	s_mov_b64 s[52:53], s[48:49]
	s_nop 0
	v_or_b32_e32 v74, 48, v142
	v_ashrrev_i32_e32 v75, 31, v74
	v_lshlrev_b64 v[74:75], 13, v[74:75]
	v_lshl_add_u64 v[74:75], v[140:141], 0, v[74:75]
	global_store_dwordx4 v[74:75], v[90:93], off
	global_store_dwordx4 v[74:75], v[82:85], off offset:64
	global_store_dwordx4 v[74:75], v[70:73], off offset:512
	global_store_dwordx4 v[74:75], v[66:69], off offset:576
	s_nop 1
	v_add_co_u32_e32 v68, vcc, s93, v144
	v_lshl_add_u64 v[66:67], v[144:145], 0, s[10:11]
	s_nop 0
	v_addc_co_u32_e32 v69, vcc, 0, v145, vcc
	s_mov_b64 s[10:11], 0x120000
	global_store_dwordx4 v[68:69], v[62:65], off
	global_store_dwordx4 v[66:67], v[58:61], off offset:64
	global_store_dwordx4 v[66:67], v[46:49], off offset:512
	global_store_dwordx4 v[66:67], v[42:45], off offset:576
	s_nop 1
	v_lshl_add_u64 v[42:43], v[144:145], 0, s[10:11]
	s_mov_b32 s10, 0x120000
	v_add_co_u32_e32 v44, vcc, s10, v144
	s_mov_b64 s[10:11], 0x140000
	s_nop 0
	v_addc_co_u32_e32 v45, vcc, 0, v145, vcc
	global_store_dwordx4 v[44:45], v[54:57], off
	global_store_dwordx4 v[42:43], v[50:53], off offset:64
	global_store_dwordx4 v[42:43], v[30:33], off offset:512
	global_store_dwordx4 v[42:43], v[26:29], off offset:576
	s_nop 1
	v_lshl_add_u64 v[26:27], v[144:145], 0, s[10:11]
	s_mov_b32 s10, 0x140000
	v_add_co_u32_e32 v28, vcc, s10, v144
	s_mov_b64 s[10:11], 0x160000
	s_nop 0
	v_addc_co_u32_e32 v29, vcc, 0, v145, vcc
	global_store_dwordx4 v[28:29], v[38:41], off
	global_store_dwordx4 v[26:27], v[34:37], off offset:64
	global_store_dwordx4 v[26:27], v[14:17], off offset:512
	global_store_dwordx4 v[26:27], v[10:13], off offset:576
	s_nop 1
	v_add_co_u32_e32 v12, vcc, 0x160000, v144
	v_lshl_add_u64 v[10:11], v[144:145], 0, s[10:11]
	s_nop 0
	v_addc_co_u32_e32 v13, vcc, 0, v145, vcc
	s_and_b64 vcc, exec, s[46:47]
	s_mov_b32 s10, s28
	global_store_dwordx4 v[12:13], v[22:25], off
	global_store_dwordx4 v[10:11], v[18:21], off offset:64
	global_store_dwordx4 v[10:11], v[6:9], off offset:512
	global_store_dwordx4 v[10:11], v[2:5], off offset:576
	s_cbranch_vccz .LBB0_110
	s_waitcnt vmcnt(0)
	s_cmpk_gt_u32 s60, 0xff
	s_cbranch_scc1 .LBB0_117
	s_barrier

; #define PG8_STAGE(bufoff, gbase, voff) do { _Pragma("unroll") for (int _i = 0; _i < 2; ++_i) \
;         __builtin_amdgcn_global_load_lds((const unsigned*)((const char*)(gbase) + (voff)[_i]), (LAS unsigned*)(lds + (bufoff) + ldsw + _i * 8192), 16, 0, 0); } while (0)
; #define PG8_LDA(dst, b, h) do { _Pragma("unroll") for (int m = 0; m < 4; ++m) _Pragma("unroll") for (int k = 0; k < 2; ++k) dst[m][k] = *(const LAS bf16x8*)(lds + PG8_SA(b, h) + aoff + m * 2048 + k * 1024); } while (0)
; #define PG8_LDB(dst, b, h) do { _Pragma("unroll") for (int n = 0; n < 2; ++n) _Pragma("unroll") for (int k = 0; k < 2; ++k) dst[n][k] = *(const LAS bf16x8*)(lds + PG8_SB(b, h) + boff + n * 2048 + k * 1024); } while (0)
; #define PG8_MMA(ai, bj, At, Bt) do { __builtin_amdgcn_s_setprio(1); _Pragma("unroll") for (int m = 0; m < 4; ++m) _Pragma("unroll") for (int n = 0; n < 2; ++n) _Pragma("unroll") for (int k = 0; k < 2; ++k) \
;         acc[ai][bj][m][n] = __builtin_amdgcn_mfma_f32_16x16x32_bf16(Bt[n][k], At[m][k], acc[ai][bj][m][n], 0, 0, 0); __builtin_amdgcn_s_setprio(0); } while (0)
; #define PG8_WAIT_V(n) asm volatile("s_waitcnt vmcnt(" #n ")" ::: "memory")
; #define PG8_WAIT_L(n) asm volatile("s_waitcnt lgkmcnt(" #n ")" ::: "memory")
; #define PG8_BAR __builtin_amdgcn_s_barrier()
; #define PG8_SCHED __builtin_amdgcn_sched_barrier(0)
; template <class Epi, class Sched>
; __device__ __forceinline__ void gemm_phase(LAS unsigned char* lds, const Gemm g, const Sched& S, const Epi& E) {
;     ...
;             PG8_LDB(B0, 0, 0); PG8_SCHED; PG8_LDA(At, 0, 0); PG8_STAGE(PG8_SA(1, 1), a1 + hstep, voffA);
;             PG8_WAIT_L(8); PG8_BAR; PG8_WAIT_L(0); PG8_MMA(0, 0, At, B0); PG8_BAR; PG8_SCHED;
;             PG8_LDB(B1, 0, 1); PG8_STAGE(PG8_SB(0, 0), b2, voffB);
;             PG8_BAR; PG8_WAIT_L(0); PG8_MMA(0, 1, At, B1); PG8_BAR;
;             PG8_LDA(At, 0, 1); PG8_STAGE(PG8_SA(0, 0), a2, voffA);
;             PG8_BAR; PG8_WAIT_L(0); PG8_MMA(1, 0, At, B0); PG8_BAR; PG8_SCHED;
;             PG8_STAGE(PG8_SB(0, 1), b2 + hstep, voffB);
;             PG8_WAIT_V(6); PG8_BAR; PG8_MMA(1, 1, At, B1); PG8_BAR;
.LBB0_354:
	v_add_u32_e32 v156, 0x10000, v145
	ds_read_b128 v[140:143], v156
	ds_read_b128 v[148:151], v156 offset:1024
	ds_read_b128 v[152:155], v156 offset:2048
	ds_read_b128 v[160:163], v156 offset:3072
	ds_read_b128 v[164:167], v147
	ds_read_b128 v[168:171], v147 offset:1024
	ds_read_b128 v[172:175], v147 offset:2048
	ds_read_b128 v[176:179], v147 offset:3072
	ds_read_b128 v[180:183], v147 offset:4096
	ds_read_b128 v[184:187], v147 offset:5120
	ds_read_b128 v[188:191], v147 offset:6144
	ds_read_b128 v[192:195], v147 offset:7168
	v_add_u32_e32 v156, 0x14000, v145
	ds_read_b128 v[196:199], v156
	ds_read_b128 v[200:203], v156 offset:1024
	ds_read_b128 v[204:207], v156 offset:2048
	ds_read_b128 v[210:213], v156 offset:3072
	s_waitcnt lgkmcnt(4)
	s_barrier
	s_waitcnt lgkmcnt(0)
	s_setprio 1
	v_mfma_f32_16x16x32_bf16 v[126:129], v[140:143], v[164:167], v[126:129]
	v_mfma_f32_16x16x32_bf16 v[122:125], v[152:155], v[164:167], v[122:125]
	v_mfma_f32_16x16x32_bf16 v[118:121], v[140:143], v[172:175], v[118:121]
	v_mfma_f32_16x16x32_bf16 v[110:113], v[152:155], v[172:175], v[110:113]
	v_mfma_f32_16x16x32_bf16 v[102:105], v[140:143], v[180:183], v[102:105]
	v_mfma_f32_16x16x32_bf16 v[94:97], v[152:155], v[180:183], v[94:97]
	v_mfma_f32_16x16x32_bf16 v[86:89], v[140:143], v[188:191], v[86:89]
	v_mfma_f32_16x16x32_bf16 v[78:81], v[152:155], v[188:191], v[78:81]
	v_mfma_f32_16x16x32_bf16 v[126:129], v[148:151], v[168:171], v[126:129]
	v_mfma_f32_16x16x32_bf16 v[122:125], v[160:163], v[168:171], v[122:125]
	v_mfma_f32_16x16x32_bf16 v[118:121], v[148:151], v[176:179], v[118:121]
	v_mfma_f32_16x16x32_bf16 v[110:113], v[160:163], v[176:179], v[110:113]
	v_mfma_f32_16x16x32_bf16 v[102:105], v[148:151], v[184:187], v[102:105]
	v_mfma_f32_16x16x32_bf16 v[94:97], v[160:163], v[184:187], v[94:97]
	v_mfma_f32_16x16x32_bf16 v[86:89], v[148:151], v[192:195], v[86:89]
	v_mfma_f32_16x16x32_bf16 v[78:81], v[160:163], v[192:195], v[78:81]
	s_add_u32 s38, s50, 0xfff80080
	s_addc_u32 s39, s51, -1
	s_cmp_eq_u32 s70, 28
	s_cselect_b32 s55, s9, s39
	s_cselect_b32 s54, s66, s38
	s_cselect_b32 s53, s43, s69
	s_cselect_b32 s52, s67, s68
	v_lshl_add_u64 v[228:229], s[50:51], 0, v[138:139]
	s_add_i32 m0, s29, 0xc000
	s_nop 0
	global_load_lds_dwordx4 v[228:229], off
	v_lshl_add_u64 v[228:229], s[50:51], 0, v[136:137]
	s_add_i32 m0, s29, 0xe000
	s_nop 0
	global_load_lds_dwordx4 v[228:229], off
	v_mfma_f32_16x16x32_bf16 v[114:117], v[196:199], v[164:167], v[114:117]
	v_mfma_f32_16x16x32_bf16 v[106:109], v[204:207], v[164:167], v[106:109]
	v_mfma_f32_16x16x32_bf16 v[98:101], v[196:199], v[172:175], v[98:101]
	v_mfma_f32_16x16x32_bf16 v[90:93], v[204:207], v[172:175], v[90:93]
	v_mfma_f32_16x16x32_bf16 v[82:85], v[196:199], v[180:183], v[82:85]
	v_mfma_f32_16x16x32_bf16 v[74:77], v[204:207], v[180:183], v[74:77]
	v_mfma_f32_16x16x32_bf16 v[70:73], v[196:199], v[188:191], v[70:73]
	v_mfma_f32_16x16x32_bf16 v[66:69], v[204:207], v[188:191], v[66:69]
	v_mfma_f32_16x16x32_bf16 v[114:117], v[200:203], v[168:171], v[114:117]
	v_mfma_f32_16x16x32_bf16 v[106:109], v[210:213], v[168:171], v[106:109]
	v_mfma_f32_16x16x32_bf16 v[98:101], v[200:203], v[176:179], v[98:101]
	v_mfma_f32_16x16x32_bf16 v[90:93], v[210:213], v[176:179], v[90:93]
	v_mfma_f32_16x16x32_bf16 v[82:85], v[200:203], v[184:187], v[82:85]
	v_mfma_f32_16x16x32_bf16 v[74:77], v[210:213], v[184:187], v[74:77]
	v_mfma_f32_16x16x32_bf16 v[70:73], v[200:203], v[192:195], v[70:73]
	v_mfma_f32_16x16x32_bf16 v[66:69], v[210:213], v[192:195], v[66:69]
	s_setprio 0
	s_barrier
	s_add_i32 s39, s56, 0x10000
	v_lshl_add_u64 v[156:157], s[52:53], 0, v[0:1]
	s_mov_b32 m0, s39
	v_lshl_add_u64 v[214:215], s[52:53], 0, v[134:135]
	global_load_lds_dwordx4 v[156:157], off
	s_add_i32 m0, s39, 0x2000
	s_nop 0
	global_load_lds_dwordx4 v[214:215], off
	s_mov_b32 m0, s29
	v_lshl_add_u64 v[216:217], s[54:55], 0, v[130:131]
	global_load_lds_dwordx4 v[216:217], off
	v_lshl_add_u64 v[224:225], s[54:55], 0, v[132:133]
	s_mov_b32 m0, s41
	s_nop 0
	global_load_lds_dwordx4 v[224:225], off
	ds_read_b128 v[164:167], v147 offset:16384
	ds_read_b128 v[168:171], v147 offset:17408
	ds_read_b128 v[172:175], v147 offset:18432
	ds_read_b128 v[176:179], v147 offset:19456
	ds_read_b128 v[180:183], v147 offset:20480
	ds_read_b128 v[184:187], v147 offset:21504
	ds_read_b128 v[188:191], v147 offset:22528
	ds_read_b128 v[192:195], v147 offset:23552
	s_waitcnt vmcnt(4)
	s_barrier
	s_waitcnt lgkmcnt(0)
	s_setprio 1
	v_mfma_f32_16x16x32_bf16 v[62:65], v[140:143], v[164:167], v[62:65]
	v_mfma_f32_16x16x32_bf16 v[58:61], v[152:155], v[164:167], v[58:61]
	v_mfma_f32_16x16x32_bf16 v[54:57], v[140:143], v[172:175], v[54:57]
	v_mfma_f32_16x16x32_bf16 v[46:49], v[152:155], v[172:175], v[46:49]
	v_mfma_f32_16x16x32_bf16 v[38:41], v[140:143], v[180:183], v[38:41]
	v_mfma_f32_16x16x32_bf16 v[30:33], v[152:155], v[180:183], v[30:33]
	v_mfma_f32_16x16x32_bf16 v[22:25], v[140:143], v[188:191], v[22:25]
	v_mfma_f32_16x16x32_bf16 v[14:17], v[152:155], v[188:191], v[14:17]
	v_mfma_f32_16x16x32_bf16 v[62:65], v[148:151], v[168:171], v[62:65]
	v_mfma_f32_16x16x32_bf16 v[58:61], v[160:163], v[168:171], v[58:61]
	v_mfma_f32_16x16x32_bf16 v[54:57], v[148:151], v[176:179], v[54:57]
	v_mfma_f32_16x16x32_bf16 v[46:49], v[160:163], v[176:179], v[46:49]
	v_mfma_f32_16x16x32_bf16 v[38:41], v[148:151], v[184:187], v[38:41]
	v_mfma_f32_16x16x32_bf16 v[30:33], v[160:163], v[184:187], v[30:33]
	v_mfma_f32_16x16x32_bf16 v[22:25], v[148:151], v[192:195], v[22:25]
	v_mfma_f32_16x16x32_bf16 v[14:17], v[160:163], v[192:195], v[14:17]
	v_mfma_f32_16x16x32_bf16 v[50:53], v[196:199], v[164:167], v[50:53]
	v_mfma_f32_16x16x32_bf16 v[42:45], v[204:207], v[164:167], v[42:45]
	v_mfma_f32_16x16x32_bf16 v[34:37], v[196:199], v[172:175], v[34:37]
	v_mfma_f32_16x16x32_bf16 v[26:29], v[204:207], v[172:175], v[26:29]
	v_mfma_f32_16x16x32_bf16 v[18:21], v[196:199], v[180:183], v[18:21]
	v_mfma_f32_16x16x32_bf16 v[10:13], v[204:207], v[180:183], v[10:13]
	v_mfma_f32_16x16x32_bf16 v[6:9], v[196:199], v[188:191], v[6:9]
	v_mfma_f32_16x16x32_bf16 v[2:5], v[204:207], v[188:191], v[2:5]
	v_mfma_f32_16x16x32_bf16 v[50:53], v[200:203], v[168:171], v[50:53]
	v_mfma_f32_16x16x32_bf16 v[42:45], v[210:213], v[168:171], v[42:45]
	v_mfma_f32_16x16x32_bf16 v[34:37], v[200:203], v[176:179], v[34:37]
	v_mfma_f32_16x16x32_bf16 v[26:29], v[210:213], v[176:179], v[26:29]
	v_mfma_f32_16x16x32_bf16 v[18:21], v[200:203], v[184:187], v[18:21]
	v_mfma_f32_16x16x32_bf16 v[10:13], v[210:213], v[184:187], v[10:13]
	v_mfma_f32_16x16x32_bf16 v[6:9], v[200:203], v[192:195], v[6:9]
	v_mfma_f32_16x16x32_bf16 v[2:5], v[210:213], v[192:195], v[2:5]
	s_setprio 0
	s_barrier
; #define PG8_STAGE(bufoff, gbase, voff) do { _Pragma("unroll") for (int _i = 0; _i < 2; ++_i) \
;         __builtin_amdgcn_global_load_lds((const unsigned*)((const char*)(gbase) + (voff)[_i]), (LAS unsigned*)(lds + (bufoff) + ldsw + _i * 8192), 16, 0, 0); } while (0)
; #define PG8_LDA(dst, b, h) do { _Pragma("unroll") for (int m = 0; m < 4; ++m) _Pragma("unroll") for (int k = 0; k < 2; ++k) dst[m][k] = *(const LAS bf16x8*)(lds + PG8_SA(b, h) + aoff + m * 2048 + k * 1024); } while (0)
; #define PG8_LDB(dst, b, h) do { _Pragma("unroll") for (int n = 0; n < 2; ++n) _Pragma("unroll") for (int k = 0; k < 2; ++k) dst[n][k] = *(const LAS bf16x8*)(lds + PG8_SB(b, h) + boff + n * 2048 + k * 1024); } while (0)
; #define PG8_MMA(ai, bj, At, Bt) do { __builtin_amdgcn_s_setprio(1); _Pragma("unroll") for (int m = 0; m < 4; ++m) _Pragma("unroll") for (int n = 0; n < 2; ++n) _Pragma("unroll") for (int k = 0; k < 2; ++k) \
;         acc[ai][bj][m][n] = __builtin_amdgcn_mfma_f32_16x16x32_bf16(Bt[n][k], At[m][k], acc[ai][bj][m][n], 0, 0, 0); __builtin_amdgcn_s_setprio(0); } while (0)
; #define PG8_WAIT_V(n) asm volatile("s_waitcnt vmcnt(" #n ")" ::: "memory")
; #define PG8_WAIT_L(n) asm volatile("s_waitcnt lgkmcnt(" #n ")" ::: "memory")
; #define PG8_BAR __builtin_amdgcn_s_barrier()
; #define PG8_SCHED __builtin_amdgcn_sched_barrier(0)
; template <class Epi, class Sched>
; __device__ __forceinline__ void gemm_phase(LAS unsigned char* lds, const Gemm g, const Sched& S, const Epi& E) {
;     ...
;             PG8_STAGE(PG8_SB(0, 1), b2 + hstep, voffB);
;             PG8_WAIT_V(6); PG8_BAR; PG8_MMA(1, 1, At, B1); PG8_BAR;
;             PG8_LDB(B0, 1, 0); PG8_SCHED; PG8_LDA(At, 1, 0); PG8_STAGE(PG8_SA(0, 1), a2 + hstep, voffA);
;             PG8_WAIT_L(8); PG8_BAR; PG8_WAIT_L(0); PG8_MMA(0, 0, At, B0); PG8_BAR; PG8_SCHED;
;             PG8_LDB(B1, 1, 1); PG8_STAGE(PG8_SB(1, 0), b3, voffB);
;             PG8_BAR; PG8_WAIT_L(0); PG8_MMA(0, 1, At, B1); PG8_BAR;
;             PG8_LDA(At, 1, 1); PG8_STAGE(PG8_SA(1, 0), a3, voffA);
;             PG8_BAR; PG8_WAIT_L(0); PG8_MMA(1, 0, At, B0); PG8_BAR; PG8_SCHED;
;             PG8_STAGE(PG8_SB(1, 1), b3 + hstep, voffB);
	s_add_u32 s72, s52, 0x80000
	s_addc_u32 s73, s53, 0
	s_add_i32 s38, s56, 0x14000
	v_lshl_add_u64 v[140:141], s[72:73], 0, v[0:1]
	s_mov_b32 m0, s38
	s_nop 0
	global_load_lds_dwordx4 v[140:141], off
	v_lshl_add_u64 v[140:141], s[72:73], 0, v[134:135]
	s_add_i32 m0, s38, 0x2000
	s_nop 0
	global_load_lds_dwordx4 v[140:141], off
	v_add_u32_e32 v160, 0x18000, v145
	ds_read_b128 v[140:143], v160
	ds_read_b128 v[148:151], v160 offset:1024
	ds_read_b128 v[152:155], v160 offset:2048
	ds_read_b128 v[160:163], v160 offset:3072
	ds_read_b128 v[164:167], v147 offset:32768
	ds_read_b128 v[168:171], v147 offset:33792
	ds_read_b128 v[172:175], v147 offset:34816
	ds_read_b128 v[176:179], v147 offset:35840
	ds_read_b128 v[180:183], v147 offset:36864
	ds_read_b128 v[184:187], v147 offset:37888
	ds_read_b128 v[188:191], v147 offset:38912
	ds_read_b128 v[192:195], v147 offset:39936
	v_add_u32_e32 v210, 0x1c000, v145
	ds_read_b128 v[196:199], v210
	ds_read_b128 v[200:203], v210 offset:1024
	ds_read_b128 v[204:207], v210 offset:2048
	ds_read_b128 v[210:213], v210 offset:3072
	s_waitcnt lgkmcnt(4)
	s_barrier
	s_waitcnt lgkmcnt(0)
	s_setprio 1
	v_mfma_f32_16x16x32_bf16 v[126:129], v[140:143], v[164:167], v[126:129]
	v_mfma_f32_16x16x32_bf16 v[122:125], v[152:155], v[164:167], v[122:125]
	v_mfma_f32_16x16x32_bf16 v[118:121], v[140:143], v[172:175], v[118:121]
	v_mfma_f32_16x16x32_bf16 v[110:113], v[152:155], v[172:175], v[110:113]
	v_mfma_f32_16x16x32_bf16 v[102:105], v[140:143], v[180:183], v[102:105]
	v_mfma_f32_16x16x32_bf16 v[94:97], v[152:155], v[180:183], v[94:97]
	v_mfma_f32_16x16x32_bf16 v[86:89], v[140:143], v[188:191], v[86:89]
	v_mfma_f32_16x16x32_bf16 v[78:81], v[152:155], v[188:191], v[78:81]
	v_mfma_f32_16x16x32_bf16 v[126:129], v[148:151], v[168:171], v[126:129]
	v_mfma_f32_16x16x32_bf16 v[122:125], v[160:163], v[168:171], v[122:125]
	v_mfma_f32_16x16x32_bf16 v[118:121], v[148:151], v[176:179], v[118:121]
	v_mfma_f32_16x16x32_bf16 v[110:113], v[160:163], v[176:179], v[110:113]
	v_mfma_f32_16x16x32_bf16 v[102:105], v[148:151], v[184:187], v[102:105]
	v_mfma_f32_16x16x32_bf16 v[94:97], v[160:163], v[184:187], v[94:97]
	v_mfma_f32_16x16x32_bf16 v[86:89], v[148:151], v[192:195], v[86:89]
	v_mfma_f32_16x16x32_bf16 v[78:81], v[160:163], v[192:195], v[78:81]
	s_add_u32 s54, s54, 0x80000
	s_addc_u32 s55, s55, 0
	s_mov_b32 m0, s57
	v_lshl_add_u64 v[226:227], s[54:55], 0, v[130:131]
	global_load_lds_dwordx4 v[226:227], off
	v_lshl_add_u64 v[226:227], s[54:55], 0, v[132:133]
	s_mov_b32 m0, s58
	s_nop 0
	global_load_lds_dwordx4 v[226:227], off
	v_mfma_f32_16x16x32_bf16 v[114:117], v[196:199], v[164:167], v[114:117]
	v_mfma_f32_16x16x32_bf16 v[106:109], v[204:207], v[164:167], v[106:109]
	v_mfma_f32_16x16x32_bf16 v[98:101], v[196:199], v[172:175], v[98:101]
	v_mfma_f32_16x16x32_bf16 v[90:93], v[204:207], v[172:175], v[90:93]
	v_mfma_f32_16x16x32_bf16 v[82:85], v[196:199], v[180:183], v[82:85]
	v_mfma_f32_16x16x32_bf16 v[74:77], v[204:207], v[180:183], v[74:77]
	v_mfma_f32_16x16x32_bf16 v[70:73], v[196:199], v[188:191], v[70:73]
	v_mfma_f32_16x16x32_bf16 v[66:69], v[204:207], v[188:191], v[66:69]
	v_mfma_f32_16x16x32_bf16 v[114:117], v[200:203], v[168:171], v[114:117]
	v_mfma_f32_16x16x32_bf16 v[106:109], v[210:213], v[168:171], v[106:109]
	v_mfma_f32_16x16x32_bf16 v[98:101], v[200:203], v[176:179], v[98:101]
	v_mfma_f32_16x16x32_bf16 v[90:93], v[210:213], v[176:179], v[90:93]
	v_mfma_f32_16x16x32_bf16 v[82:85], v[200:203], v[184:187], v[82:85]
	v_mfma_f32_16x16x32_bf16 v[74:77], v[210:213], v[184:187], v[74:77]
	v_mfma_f32_16x16x32_bf16 v[70:73], v[200:203], v[192:195], v[70:73]
	v_mfma_f32_16x16x32_bf16 v[66:69], v[210:213], v[192:195], v[66:69]
	s_setprio 0
	s_barrier
	s_add_i32 s38, s56, 0x18000
	v_lshl_add_u64 v[156:157], v[156:157], 0, s[36:37]
	s_mov_b32 m0, s38
	s_nop 0
	global_load_lds_dwordx4 v[156:157], off
	v_lshl_add_u64 v[156:157], v[214:215], 0, s[36:37]
	s_add_i32 m0, s38, 0x2000
	s_nop 0
	global_load_lds_dwordx4 v[156:157], off
	s_mov_b32 m0, s59
	v_lshl_add_u64 v[156:157], v[216:217], 0, s[36:37]
	global_load_lds_dwordx4 v[156:157], off
	v_lshl_add_u64 v[156:157], v[224:225], 0, s[36:37]
	s_mov_b32 m0, s60
	s_nop 0
	global_load_lds_dwordx4 v[156:157], off
	ds_read_b128 v[164:167], v147 offset:49152
	ds_read_b128 v[168:171], v147 offset:50176
	ds_read_b128 v[172:175], v147 offset:51200
	ds_read_b128 v[176:179], v147 offset:52224
	ds_read_b128 v[180:183], v147 offset:53248
	ds_read_b128 v[184:187], v147 offset:54272
	ds_read_b128 v[188:191], v147 offset:55296
	ds_read_b128 v[192:195], v147 offset:56320
	s_waitcnt vmcnt(4)
	s_barrier
; #define PG8_STAGE(bufoff, gbase, voff) do { _Pragma("unroll") for (int _i = 0; _i < 2; ++_i) \
;         __builtin_amdgcn_global_load_lds((const unsigned*)((const char*)(gbase) + (voff)[_i]), (LAS unsigned*)(lds + (bufoff) + ldsw + _i * 8192), 16, 0, 0); } while (0)
; #define PG8_LDA(dst, b, h) do { _Pragma("unroll") for (int m = 0; m < 4; ++m) _Pragma("unroll") for (int k = 0; k < 2; ++k) dst[m][k] = *(const LAS bf16x8*)(lds + PG8_SA(b, h) + aoff + m * 2048 + k * 1024); } while (0)
; #define PG8_LDB(dst, b, h) do { _Pragma("unroll") for (int n = 0; n < 2; ++n) _Pragma("unroll") for (int k = 0; k < 2; ++k) dst[n][k] = *(const LAS bf16x8*)(lds + PG8_SB(b, h) + boff + n * 2048 + k * 1024); } while (0)
; #define PG8_MMA(ai, bj, At, Bt) do { __builtin_amdgcn_s_setprio(1); _Pragma("unroll") for (int m = 0; m < 4; ++m) _Pragma("unroll") for (int n = 0; n < 2; ++n) _Pragma("unroll") for (int k = 0; k < 2; ++k) \
;         acc[ai][bj][m][n] = __builtin_amdgcn_mfma_f32_16x16x32_bf16(Bt[n][k], At[m][k], acc[ai][bj][m][n], 0, 0, 0); __builtin_amdgcn_s_setprio(0); } while (0)
; #define PG8_WAIT_V(n) asm volatile("s_waitcnt vmcnt(" #n ")" ::: "memory")
; #define PG8_WAIT_L(n) asm volatile("s_waitcnt lgkmcnt(" #n ")" ::: "memory")
; #define PG8_BAR __builtin_amdgcn_s_barrier()
; #define PG8_SCHED __builtin_amdgcn_sched_barrier(0)
; template <class Epi, class Sched>
; __device__ __forceinline__ void gemm_phase(LAS unsigned char* lds, const Gemm g, const Sched& S, const Epi& E) {
;     ...
;             PG8_LDB(B1, 1, 1); PG8_STAGE(PG8_SB(1, 0), b3, voffB);
;             PG8_BAR; PG8_WAIT_L(0); PG8_MMA(0, 1, At, B1); PG8_BAR;
;             PG8_LDA(At, 1, 1); PG8_STAGE(PG8_SA(1, 0), a3, voffA);
;             PG8_BAR; PG8_WAIT_L(0); PG8_MMA(1, 0, At, B0); PG8_BAR; PG8_SCHED;
;             PG8_STAGE(PG8_SB(1, 1), b3 + hstep, voffB);
;             PG8_WAIT_V(6); PG8_BAR; PG8_MMA(1, 1, At, B1); PG8_BAR;
;         }
	s_waitcnt lgkmcnt(0)
	s_setprio 1
	v_mfma_f32_16x16x32_bf16 v[62:65], v[140:143], v[164:167], v[62:65]
	v_mfma_f32_16x16x32_bf16 v[58:61], v[152:155], v[164:167], v[58:61]
	v_mfma_f32_16x16x32_bf16 v[54:57], v[140:143], v[172:175], v[54:57]
	v_mfma_f32_16x16x32_bf16 v[46:49], v[152:155], v[172:175], v[46:49]
	v_mfma_f32_16x16x32_bf16 v[38:41], v[140:143], v[180:183], v[38:41]
	v_mfma_f32_16x16x32_bf16 v[30:33], v[152:155], v[180:183], v[30:33]
	v_mfma_f32_16x16x32_bf16 v[22:25], v[140:143], v[188:191], v[22:25]
	v_mfma_f32_16x16x32_bf16 v[14:17], v[152:155], v[188:191], v[14:17]
	v_mfma_f32_16x16x32_bf16 v[62:65], v[148:151], v[168:171], v[62:65]
	v_mfma_f32_16x16x32_bf16 v[58:61], v[160:163], v[168:171], v[58:61]
	v_mfma_f32_16x16x32_bf16 v[54:57], v[148:151], v[176:179], v[54:57]
	v_mfma_f32_16x16x32_bf16 v[46:49], v[160:163], v[176:179], v[46:49]
	v_mfma_f32_16x16x32_bf16 v[38:41], v[148:151], v[184:187], v[38:41]
	v_mfma_f32_16x16x32_bf16 v[30:33], v[160:163], v[184:187], v[30:33]
	v_mfma_f32_16x16x32_bf16 v[22:25], v[148:151], v[192:195], v[22:25]
	v_mfma_f32_16x16x32_bf16 v[14:17], v[160:163], v[192:195], v[14:17]
	s_add_u32 s52, s52, 0x80080
	s_addc_u32 s53, s53, 0
	s_add_i32 s38, s56, 0x1c000
	v_lshl_add_u64 v[140:141], s[52:53], 0, v[0:1]
	s_mov_b32 m0, s38
	s_nop 0
	global_load_lds_dwordx4 v[140:141], off
	v_lshl_add_u64 v[140:141], s[52:53], 0, v[134:135]
	s_add_i32 m0, s38, 0x2000
	s_nop 0
	global_load_lds_dwordx4 v[140:141], off
	v_mfma_f32_16x16x32_bf16 v[50:53], v[196:199], v[164:167], v[50:53]
	v_mfma_f32_16x16x32_bf16 v[42:45], v[204:207], v[164:167], v[42:45]
	v_mfma_f32_16x16x32_bf16 v[34:37], v[196:199], v[172:175], v[34:37]
	v_mfma_f32_16x16x32_bf16 v[26:29], v[204:207], v[172:175], v[26:29]
	v_mfma_f32_16x16x32_bf16 v[18:21], v[196:199], v[180:183], v[18:21]
	v_mfma_f32_16x16x32_bf16 v[10:13], v[204:207], v[180:183], v[10:13]
	v_mfma_f32_16x16x32_bf16 v[6:9], v[196:199], v[188:191], v[6:9]
	v_mfma_f32_16x16x32_bf16 v[2:5], v[204:207], v[188:191], v[2:5]
	v_mfma_f32_16x16x32_bf16 v[50:53], v[200:203], v[168:171], v[50:53]
	v_mfma_f32_16x16x32_bf16 v[42:45], v[210:213], v[168:171], v[42:45]
	v_mfma_f32_16x16x32_bf16 v[34:37], v[200:203], v[176:179], v[34:37]
	v_mfma_f32_16x16x32_bf16 v[26:29], v[210:213], v[176:179], v[26:29]
	v_mfma_f32_16x16x32_bf16 v[18:21], v[200:203], v[184:187], v[18:21]
	v_mfma_f32_16x16x32_bf16 v[10:13], v[210:213], v[184:187], v[10:13]
	v_mfma_f32_16x16x32_bf16 v[6:9], v[200:203], v[192:195], v[6:9]
	v_mfma_f32_16x16x32_bf16 v[2:5], v[210:213], v[192:195], v[2:5]
	s_setprio 0
	s_add_i32 s70, s70, 2
	s_add_u32 s68, s68, 0x100
	s_addc_u32 s69, s69, 0
	s_add_u32 s50, s50, 0x100
	s_addc_u32 s51, s51, 0
	s_cmp_gt_u32 s70, 29
	s_barrier
	s_cbranch_scc0 .LBB0_354
; __device__ __forceinline__ unsigned cvt_pk_bf16(float lo, float hi) { unsigned r; asm("v_cvt_pk_bf16_f32 %0, %1, %2" : "=v"(r) : "v"(lo), "v"(hi)); return r; }
;     __device__ __forceinline__ void operator()(const f32x4 (&acc)[2][2][4][2], const Unit& u, int wr, int wc, int fr, int fq) const {
;         const int row0 = u.pm * BM + wr * 64 + fr, col0 = u.pn * BM + wc * 32 + 8 * fq;
; #pragma unroll
;         for (int ai = 0; ai < 2; ++ai)
; #pragma unroll
;             for (int m = 0; m < 4; ++m) { bf16_t* rowp = O + (size_t)(row0 + ai * HALF + m * 16) * ldc + col0;
; #pragma unroll
;                 for (int bj = 0; bj < 2; ++bj) { f32x4 v0 = acc[ai][bj][m][0], v1 = acc[ai][bj][m][1];
;                     if (ACT == 1) {
; #pragma unroll
;                         for (int j = 0; j < 4; ++j) { float a = fmaxf(v0[j], 0.f), b = fmaxf(v1[j], 0.f); v0[j] = a * a; v1[j] = b * b; } }
;                     u32x4 w; w.x = cvt_pk_bf16(v0[0], v0[1]); w.y = cvt_pk_bf16(v0[2], v0[3]); w.z = cvt_pk_bf16(v1[0], v1[1]); w.w = cvt_pk_bf16(v1[2], v1[3]);
;                     if (ACT == 1) __builtin_nontemporal_store(w, (u32x4*)(rowp + bj * HALF));
;                     else *(u32x4*)(rowp + bj * HALF) = w; } }
	s_load_dwordx2 s[50:51], s[0:1], 0xc0
	v_lshl_add_u32 v150, s28, 8, v144
	v_lshl_or_b32 v142, s40, 8, v146
	v_ashrrev_i32_e32 v143, 31, v142
	v_cvt_pk_bf16_f32 v70, v70, v71
	s_waitcnt lgkmcnt(0)
	v_mov_b64_e32 v[140:141], s[50:51]
	v_cvt_pk_bf16_f32 v71, v72, v73
	v_cvt_pk_bf16_f32 v72, v66, v67
	v_add_u32_e32 v66, 0x80, v150
	v_mad_i64_i32 v[148:149], s[50:51], v150, s17, v[140:141]
	v_lshlrev_b64 v[142:143], 1, v[142:143]
	v_cvt_pk_bf16_f32 v114, v114, v115
	v_cvt_pk_bf16_f32 v115, v116, v117
	v_cvt_pk_bf16_f32 v116, v106, v107
	v_or_b32_e32 v106, 16, v150
	v_mad_i64_i32 v[66:67], s[50:51], v66, s17, v[140:141]
	v_cvt_pk_bf16_f32 v50, v50, v51
	v_cvt_pk_bf16_f32 v51, v52, v53
	v_cvt_pk_bf16_f32 v52, v42, v43
	v_add_u32_e32 v42, 0x90, v150
	v_lshl_add_u64 v[148:149], v[148:149], 0, v[142:143]
	v_mad_i64_i32 v[106:107], s[50:51], v106, s17, v[140:141]
	v_cvt_pk_bf16_f32 v98, v98, v99
	v_cvt_pk_bf16_f32 v99, v100, v101
	v_cvt_pk_bf16_f32 v100, v90, v91
	v_or_b32_e32 v90, 32, v150
	v_lshl_add_u64 v[66:67], v[66:67], 0, v[142:143]
	v_mad_i64_i32 v[42:43], s[50:51], v42, s17, v[140:141]
	v_cvt_pk_bf16_f32 v34, v34, v35
	v_cvt_pk_bf16_f32 v35, v36, v37
	v_cvt_pk_bf16_f32 v36, v26, v27
	v_add_u32_e32 v26, 0xa0, v150
	v_cvt_pk_bf16_f32 v117, v108, v109
	global_store_dwordx4 v[148:149], v[114:117], off offset:256
	v_mad_i64_i32 v[90:91], s[50:51], v90, s17, v[140:141]
	s_nop 0
	v_lshl_add_u64 v[114:115], v[106:107], 0, v[142:143]
	v_cvt_pk_bf16_f32 v82, v82, v83
	v_cvt_pk_bf16_f32 v83, v84, v85
	v_cvt_pk_bf16_f32 v84, v74, v75
	v_or_b32_e32 v74, 48, v150
	v_cvt_pk_bf16_f32 v53, v44, v45
	global_store_dwordx4 v[66:67], v[50:53], off offset:256
	v_mad_i64_i32 v[26:27], s[50:51], v26, s17, v[140:141]
	s_nop 0
	v_lshl_add_u64 v[50:51], v[42:43], 0, v[142:143]
	v_cvt_pk_bf16_f32 v18, v18, v19
	v_cvt_pk_bf16_f32 v19, v20, v21
	v_cvt_pk_bf16_f32 v20, v10, v11
	v_add_u32_e32 v10, 0xb0, v150
	v_cvt_pk_bf16_f32 v101, v92, v93
	global_store_dwordx4 v[114:115], v[98:101], off offset:256
	v_mad_i64_i32 v[74:75], s[50:51], v74, s17, v[140:141]
	s_nop 0
	v_lshl_add_u64 v[98:99], v[90:91], 0, v[142:143]
	v_cvt_pk_bf16_f32 v37, v28, v29
	global_store_dwordx4 v[50:51], v[34:37], off offset:256
	v_mad_i64_i32 v[10:11], s[50:51], v10, s17, v[140:141]
	s_nop 0
	v_lshl_add_u64 v[34:35], v[26:27], 0, v[142:143]
	v_cvt_pk_bf16_f32 v85, v76, v77
	global_store_dwordx4 v[98:99], v[82:85], off offset:256
	v_cvt_pk_bf16_f32 v21, v12, v13
	global_store_dwordx4 v[34:35], v[18:21], off offset:256
	s_and_b64 vcc, exec, s[46:47]
	v_lshl_add_u64 v[82:83], v[74:75], 0, v[142:143]
	v_lshl_add_u64 v[18:19], v[10:11], 0, v[142:143]
	s_mov_b32 s40, s42
	s_mov_b32 s28, s8
	s_mov_b32 s43, s42
	s_mov_b32 s46, s8
	s_mov_b64 s[50:51], s[48:49]
	s_mov_b64 s[52:53], s[44:45]
	v_cvt_pk_bf16_f32 v126, v126, v127
	v_cvt_pk_bf16_f32 v127, v128, v129
	v_cvt_pk_bf16_f32 v128, v122, v123
	v_cvt_pk_bf16_f32 v129, v124, v125
	global_store_dwordx4 v[148:149], v[126:129], off
	v_cvt_pk_bf16_f32 v106, v118, v119
	v_cvt_pk_bf16_f32 v107, v120, v121
	v_cvt_pk_bf16_f32 v108, v110, v111
	v_cvt_pk_bf16_f32 v109, v112, v113
	global_store_dwordx4 v[114:115], v[106:109], off
	v_cvt_pk_bf16_f32 v90, v102, v103
	v_cvt_pk_bf16_f32 v91, v104, v105
	v_cvt_pk_bf16_f32 v92, v94, v95
	v_cvt_pk_bf16_f32 v93, v96, v97
	global_store_dwordx4 v[98:99], v[90:93], off
	v_cvt_pk_bf16_f32 v74, v86, v87
	v_cvt_pk_bf16_f32 v75, v88, v89
	v_cvt_pk_bf16_f32 v76, v78, v79
	v_cvt_pk_bf16_f32 v77, v80, v81
	global_store_dwordx4 v[82:83], v[74:77], off
	v_cvt_pk_bf16_f32 v73, v68, v69
	global_store_dwordx4 v[82:83], v[70:73], off offset:256
	v_cvt_pk_bf16_f32 v62, v62, v63
	v_cvt_pk_bf16_f32 v63, v64, v65
	v_cvt_pk_bf16_f32 v64, v58, v59
	v_cvt_pk_bf16_f32 v65, v60, v61
	global_store_dwordx4 v[66:67], v[62:65], off
	v_cvt_pk_bf16_f32 v42, v54, v55
	v_cvt_pk_bf16_f32 v43, v56, v57
	v_cvt_pk_bf16_f32 v44, v46, v47
	v_cvt_pk_bf16_f32 v45, v48, v49
	global_store_dwordx4 v[50:51], v[42:45], off
	v_cvt_pk_bf16_f32 v26, v38, v39
	v_cvt_pk_bf16_f32 v27, v40, v41
	v_cvt_pk_bf16_f32 v28, v30, v31
	v_cvt_pk_bf16_f32 v29, v32, v33
	global_store_dwordx4 v[34:35], v[26:29], off
	v_cvt_pk_bf16_f32 v10, v22, v23
	v_cvt_pk_bf16_f32 v11, v24, v25
	v_cvt_pk_bf16_f32 v12, v14, v15
	v_cvt_pk_bf16_f32 v13, v16, v17
	global_store_dwordx4 v[18:19], v[10:13], off
	v_cvt_pk_bf16_f32 v6, v6, v7
	v_cvt_pk_bf16_f32 v7, v8, v9
	v_cvt_pk_bf16_f32 v8, v2, v3
	v_cvt_pk_bf16_f32 v9, v4, v5
	global_store_dwordx4 v[18:19], v[6:9], off offset:256
	s_cbranch_vccz .LBB0_346
	s_waitcnt vmcnt(0)
	s_cmpk_gt_u32 s25, 0xff
	s_cbranch_scc1 .LBB0_358
	s_barrier
